# kpair variant: B-fragment-major pair order (same srcA for 4 consecutive pairs) + dropwaits + rotary
# speedup vs baseline: 1.0821x; 1.0821x over previous
.LBB0_642:
	ds_read_b128 v[148:151], v139
	ds_read_b128 v[152:155], v139 offset:1024
	ds_read_b128 v[156:159], v139 offset:2048
	ds_read_b128 v[160:163], v139 offset:3072
	ds_read_b128 v[164:167], v140
	ds_read_b128 v[168:171], v140 offset:1024
	ds_read_b128 v[172:175], v140 offset:2048
	ds_read_b128 v[176:179], v140 offset:3072
	s_add_i32 s18, s71, 0xffe80080
	s_cmp_eq_u32 s58, s73
	s_cselect_b32 s74, s69, s18
	s_cselect_b32 s76, s70, s72
	s_or_b32 s75, s74, 0x80
	s_add_i32 s18, s71, 0xfff80000
	s_mov_b32 m0, s59
	ds_read_b128 v[180:183], v141
	ds_read_b128 v[184:187], v141 offset:1024
	ds_read_b128 v[188:191], v141 offset:2048
	ds_read_b128 v[192:195], v141 offset:3072
	ds_read_b128 v[196:199], v141 offset:4096
	ds_read_b128 v[200:203], v141 offset:5120
	ds_read_b128 v[204:207], v141 offset:6144
	ds_read_b128 v[208:211], v141 offset:7168
	buffer_load_dwordx4 v137, s[12:15], s18 offen lds
	s_mov_b32 m0, s60
	s_nop 0
	buffer_load_dwordx4 v137, s[12:15], s71 offen lds
	s_waitcnt vmcnt(8)
	s_waitcnt lgkmcnt(0)
	s_setprio 1
	v_mfma_f32_16x16x32_bf16 v[118:121], v[148:151], v[180:183], v[118:121]
	s_barrier
	v_mfma_f32_16x16x32_bf16 v[118:121], v[152:155], v[184:187], v[118:121]
	v_mfma_f32_16x16x32_bf16 v[110:113], v[148:151], v[188:191], v[110:113]
	v_mfma_f32_16x16x32_bf16 v[110:113], v[152:155], v[192:195], v[110:113]
	v_mfma_f32_16x16x32_bf16 v[94:97], v[148:151], v[196:199], v[94:97]
	v_mfma_f32_16x16x32_bf16 v[94:97], v[152:155], v[200:203], v[94:97]
	v_mfma_f32_16x16x32_bf16 v[78:81], v[148:151], v[204:207], v[78:81]
	v_mfma_f32_16x16x32_bf16 v[78:81], v[152:155], v[208:211], v[78:81]
	v_mfma_f32_16x16x32_bf16 v[114:117], v[156:159], v[180:183], v[114:117]
	v_mfma_f32_16x16x32_bf16 v[114:117], v[160:163], v[184:187], v[114:117]
	v_mfma_f32_16x16x32_bf16 v[102:105], v[156:159], v[188:191], v[102:105]
	v_mfma_f32_16x16x32_bf16 v[102:105], v[160:163], v[192:195], v[102:105]
	v_mfma_f32_16x16x32_bf16 v[86:89], v[156:159], v[196:199], v[86:89]
	v_mfma_f32_16x16x32_bf16 v[86:89], v[160:163], v[200:203], v[86:89]
	v_mfma_f32_16x16x32_bf16 v[66:69], v[156:159], v[204:207], v[66:69]
	v_mfma_f32_16x16x32_bf16 v[66:69], v[160:163], v[208:211], v[66:69]
	v_mfma_f32_16x16x32_bf16 v[126:129], v[164:167], v[180:183], v[126:129]
	v_mfma_f32_16x16x32_bf16 v[126:129], v[168:171], v[184:187], v[126:129]
	v_mfma_f32_16x16x32_bf16 v[106:109], v[164:167], v[188:191], v[106:109]
	v_mfma_f32_16x16x32_bf16 v[106:109], v[168:171], v[192:195], v[106:109]
	v_mfma_f32_16x16x32_bf16 v[90:93], v[164:167], v[196:199], v[90:93]
	v_mfma_f32_16x16x32_bf16 v[90:93], v[168:171], v[200:203], v[90:93]
	v_mfma_f32_16x16x32_bf16 v[74:77], v[164:167], v[204:207], v[74:77]
	v_mfma_f32_16x16x32_bf16 v[74:77], v[168:171], v[208:211], v[74:77]
	v_mfma_f32_16x16x32_bf16 v[122:125], v[172:175], v[180:183], v[122:125]
	v_mfma_f32_16x16x32_bf16 v[122:125], v[176:179], v[184:187], v[122:125]
	v_mfma_f32_16x16x32_bf16 v[98:101], v[172:175], v[188:191], v[98:101]
	v_mfma_f32_16x16x32_bf16 v[98:101], v[176:179], v[192:195], v[98:101]
	v_mfma_f32_16x16x32_bf16 v[82:85], v[172:175], v[196:199], v[82:85]
	v_mfma_f32_16x16x32_bf16 v[82:85], v[176:179], v[200:203], v[82:85]
	v_mfma_f32_16x16x32_bf16 v[70:73], v[172:175], v[204:207], v[70:73]
	v_mfma_f32_16x16x32_bf16 v[70:73], v[176:179], v[208:211], v[70:73]
	s_setprio 0
	s_barrier
	s_mov_b32 m0, s30
	s_mov_b32 s18, s14
	s_mov_b32 s19, s15
	ds_read_b128 v[180:183], v141 offset:16384
	ds_read_b128 v[184:187], v141 offset:17408
	ds_read_b128 v[188:191], v141 offset:18432
	ds_read_b128 v[192:195], v141 offset:19456
	ds_read_b128 v[196:199], v141 offset:20480
	ds_read_b128 v[200:203], v141 offset:21504
	ds_read_b128 v[204:207], v141 offset:22528
	ds_read_b128 v[208:211], v141 offset:23552
	buffer_load_dwordx4 v138, s[16:19], s76 offen lds
	s_add_i32 s77, s76, 0x80000
	s_mov_b32 m0, s31
	s_nop 0
	buffer_load_dwordx4 v138, s[16:19], s77 offen lds
	s_add_i32 s77, s76, 0x100000
	s_mov_b32 m0, s44
	s_nop 0
	buffer_load_dwordx4 v138, s[16:19], s77 offen lds
	s_add_i32 s77, s76, 0x180000
	s_mov_b32 m0, s45
	s_nop 0
	buffer_load_dwordx4 v138, s[16:19], s77 offen lds
	s_mov_b32 m0, s27
	s_add_i32 s77, s74, 0x80000
	buffer_load_dwordx4 v137, s[12:15], s74 offen lds
	s_mov_b32 m0, s46
	s_nop 0
	buffer_load_dwordx4 v137, s[12:15], s77 offen lds
	s_waitcnt vmcnt(8)
	s_waitcnt lgkmcnt(0)
	s_setprio 1
	v_mfma_f32_16x16x32_bf16 v[62:65], v[148:151], v[180:183], v[62:65]
	s_barrier
	v_mfma_f32_16x16x32_bf16 v[62:65], v[152:155], v[184:187], v[62:65]
	v_mfma_f32_16x16x32_bf16 v[46:49], v[148:151], v[188:191], v[46:49]
	v_mfma_f32_16x16x32_bf16 v[46:49], v[152:155], v[192:195], v[46:49]
	v_mfma_f32_16x16x32_bf16 v[30:33], v[148:151], v[196:199], v[30:33]
	v_mfma_f32_16x16x32_bf16 v[30:33], v[152:155], v[200:203], v[30:33]
	v_mfma_f32_16x16x32_bf16 v[14:17], v[148:151], v[204:207], v[14:17]
	v_mfma_f32_16x16x32_bf16 v[14:17], v[152:155], v[208:211], v[14:17]
	v_mfma_f32_16x16x32_bf16 v[54:57], v[156:159], v[180:183], v[54:57]
	v_mfma_f32_16x16x32_bf16 v[54:57], v[160:163], v[184:187], v[54:57]
	v_mfma_f32_16x16x32_bf16 v[38:41], v[156:159], v[188:191], v[38:41]
	v_mfma_f32_16x16x32_bf16 v[38:41], v[160:163], v[192:195], v[38:41]
	v_mfma_f32_16x16x32_bf16 v[22:25], v[156:159], v[196:199], v[22:25]
	v_mfma_f32_16x16x32_bf16 v[22:25], v[160:163], v[200:203], v[22:25]
	v_mfma_f32_16x16x32_bf16 v[6:9], v[156:159], v[204:207], v[6:9]
	v_mfma_f32_16x16x32_bf16 v[6:9], v[160:163], v[208:211], v[6:9]
	v_mfma_f32_16x16x32_bf16 v[58:61], v[164:167], v[180:183], v[58:61]
	v_mfma_f32_16x16x32_bf16 v[58:61], v[168:171], v[184:187], v[58:61]
	v_mfma_f32_16x16x32_bf16 v[42:45], v[164:167], v[188:191], v[42:45]
	v_mfma_f32_16x16x32_bf16 v[42:45], v[168:171], v[192:195], v[42:45]
	v_mfma_f32_16x16x32_bf16 v[26:29], v[164:167], v[196:199], v[26:29]
	v_mfma_f32_16x16x32_bf16 v[26:29], v[168:171], v[200:203], v[26:29]
	v_mfma_f32_16x16x32_bf16 v[10:13], v[164:167], v[204:207], v[10:13]
	v_mfma_f32_16x16x32_bf16 v[10:13], v[168:171], v[208:211], v[10:13]
	v_mfma_f32_16x16x32_bf16 v[50:53], v[172:175], v[180:183], v[50:53]
	v_mfma_f32_16x16x32_bf16 v[50:53], v[176:179], v[184:187], v[50:53]
	v_mfma_f32_16x16x32_bf16 v[34:37], v[172:175], v[188:191], v[34:37]
	v_mfma_f32_16x16x32_bf16 v[34:37], v[176:179], v[192:195], v[34:37]
	v_mfma_f32_16x16x32_bf16 v[18:21], v[172:175], v[196:199], v[18:21]
	v_mfma_f32_16x16x32_bf16 v[18:21], v[176:179], v[200:203], v[18:21]
	v_mfma_f32_16x16x32_bf16 v[2:5], v[172:175], v[204:207], v[2:5]
	v_mfma_f32_16x16x32_bf16 v[2:5], v[176:179], v[208:211], v[2:5]
	s_setprio 0
	s_barrier
	ds_read_b128 v[148:151], v142
	ds_read_b128 v[152:155], v142 offset:1024
	ds_read_b128 v[156:159], v142 offset:2048
	ds_read_b128 v[160:163], v142 offset:3072
	ds_read_b128 v[164:167], v143
	ds_read_b128 v[168:171], v143 offset:1024
	ds_read_b128 v[172:175], v143 offset:2048
	ds_read_b128 v[176:179], v143 offset:3072
	s_mov_b32 m0, s47
	s_add_i32 s77, s74, 0x100000
	ds_read_b128 v[180:183], v141 offset:32768
	ds_read_b128 v[184:187], v141 offset:33792
	ds_read_b128 v[188:191], v141 offset:34816
	ds_read_b128 v[192:195], v141 offset:35840
	ds_read_b128 v[196:199], v141 offset:36864
	ds_read_b128 v[200:203], v141 offset:37888
	ds_read_b128 v[204:207], v141 offset:38912
	ds_read_b128 v[208:211], v141 offset:39936
	buffer_load_dwordx4 v137, s[12:15], s77 offen lds
	s_add_i32 s77, s74, 0x180000
	s_mov_b32 m0, s48
	s_nop 0
	buffer_load_dwordx4 v137, s[12:15], s77 offen lds
	s_waitcnt vmcnt(8)
	s_waitcnt lgkmcnt(0)
	s_setprio 1
	v_mfma_f32_16x16x32_bf16 v[118:121], v[148:151], v[180:183], v[118:121]
	s_barrier
	v_mfma_f32_16x16x32_bf16 v[118:121], v[152:155], v[184:187], v[118:121]
	v_mfma_f32_16x16x32_bf16 v[110:113], v[148:151], v[188:191], v[110:113]
	v_mfma_f32_16x16x32_bf16 v[110:113], v[152:155], v[192:195], v[110:113]
	v_mfma_f32_16x16x32_bf16 v[94:97], v[148:151], v[196:199], v[94:97]
	v_mfma_f32_16x16x32_bf16 v[94:97], v[152:155], v[200:203], v[94:97]
	v_mfma_f32_16x16x32_bf16 v[78:81], v[148:151], v[204:207], v[78:81]
	v_mfma_f32_16x16x32_bf16 v[78:81], v[152:155], v[208:211], v[78:81]
	v_mfma_f32_16x16x32_bf16 v[114:117], v[156:159], v[180:183], v[114:117]
	v_mfma_f32_16x16x32_bf16 v[114:117], v[160:163], v[184:187], v[114:117]
	v_mfma_f32_16x16x32_bf16 v[102:105], v[156:159], v[188:191], v[102:105]
	v_mfma_f32_16x16x32_bf16 v[102:105], v[160:163], v[192:195], v[102:105]
	v_mfma_f32_16x16x32_bf16 v[86:89], v[156:159], v[196:199], v[86:89]
	v_mfma_f32_16x16x32_bf16 v[86:89], v[160:163], v[200:203], v[86:89]
	v_mfma_f32_16x16x32_bf16 v[66:69], v[156:159], v[204:207], v[66:69]
	v_mfma_f32_16x16x32_bf16 v[66:69], v[160:163], v[208:211], v[66:69]
	v_mfma_f32_16x16x32_bf16 v[126:129], v[164:167], v[180:183], v[126:129]
	v_mfma_f32_16x16x32_bf16 v[126:129], v[168:171], v[184:187], v[126:129]
	v_mfma_f32_16x16x32_bf16 v[106:109], v[164:167], v[188:191], v[106:109]
	v_mfma_f32_16x16x32_bf16 v[106:109], v[168:171], v[192:195], v[106:109]
	v_mfma_f32_16x16x32_bf16 v[90:93], v[164:167], v[196:199], v[90:93]
	v_mfma_f32_16x16x32_bf16 v[90:93], v[168:171], v[200:203], v[90:93]
	v_mfma_f32_16x16x32_bf16 v[74:77], v[164:167], v[204:207], v[74:77]
	v_mfma_f32_16x16x32_bf16 v[74:77], v[168:171], v[208:211], v[74:77]
	v_mfma_f32_16x16x32_bf16 v[122:125], v[172:175], v[180:183], v[122:125]
	v_mfma_f32_16x16x32_bf16 v[122:125], v[176:179], v[184:187], v[122:125]
	v_mfma_f32_16x16x32_bf16 v[98:101], v[172:175], v[188:191], v[98:101]
	v_mfma_f32_16x16x32_bf16 v[98:101], v[176:179], v[192:195], v[98:101]
	v_mfma_f32_16x16x32_bf16 v[82:85], v[172:175], v[196:199], v[82:85]
	v_mfma_f32_16x16x32_bf16 v[82:85], v[176:179], v[200:203], v[82:85]
	v_mfma_f32_16x16x32_bf16 v[70:73], v[172:175], v[204:207], v[70:73]
	v_mfma_f32_16x16x32_bf16 v[70:73], v[176:179], v[208:211], v[70:73]
	s_setprio 0
	s_barrier
	s_mov_b32 m0, s50
	s_or_b32 s77, s76, 0x80
	ds_read_b128 v[180:183], v141 offset:49152
	ds_read_b128 v[184:187], v141 offset:50176
	ds_read_b128 v[188:191], v141 offset:51200
	ds_read_b128 v[192:195], v141 offset:52224
	ds_read_b128 v[196:199], v141 offset:53248
	ds_read_b128 v[200:203], v141 offset:54272
	ds_read_b128 v[204:207], v141 offset:55296
	ds_read_b128 v[208:211], v141 offset:56320
	buffer_load_dwordx4 v138, s[16:19], s77 offen lds
	s_add_i32 s77, s76, 0x80080
	s_mov_b32 m0, s51
	s_add_i32 s74, s74, 0x80080
	buffer_load_dwordx4 v138, s[16:19], s77 offen lds
	s_add_i32 s77, s76, 0x100080
	s_mov_b32 m0, s54
	s_add_i32 s76, s76, 0x180080
	buffer_load_dwordx4 v138, s[16:19], s77 offen lds
	s_mov_b32 m0, s55
	s_nop 0
	buffer_load_dwordx4 v138, s[16:19], s76 offen lds
	s_mov_b32 m0, s52
	s_nop 0
	buffer_load_dwordx4 v137, s[12:15], s75 offen lds
	s_mov_b32 m0, s53
	s_nop 0
	buffer_load_dwordx4 v137, s[12:15], s74 offen lds
	s_waitcnt vmcnt(8)
	s_waitcnt lgkmcnt(0)
	s_setprio 1
	v_mfma_f32_16x16x32_bf16 v[62:65], v[148:151], v[180:183], v[62:65]
	s_barrier
	v_mfma_f32_16x16x32_bf16 v[62:65], v[152:155], v[184:187], v[62:65]
	v_mfma_f32_16x16x32_bf16 v[46:49], v[148:151], v[188:191], v[46:49]
	v_mfma_f32_16x16x32_bf16 v[46:49], v[152:155], v[192:195], v[46:49]
	v_mfma_f32_16x16x32_bf16 v[30:33], v[148:151], v[196:199], v[30:33]
	v_mfma_f32_16x16x32_bf16 v[30:33], v[152:155], v[200:203], v[30:33]
	v_mfma_f32_16x16x32_bf16 v[14:17], v[148:151], v[204:207], v[14:17]
	v_mfma_f32_16x16x32_bf16 v[14:17], v[152:155], v[208:211], v[14:17]
	v_mfma_f32_16x16x32_bf16 v[54:57], v[156:159], v[180:183], v[54:57]
	v_mfma_f32_16x16x32_bf16 v[54:57], v[160:163], v[184:187], v[54:57]
	v_mfma_f32_16x16x32_bf16 v[38:41], v[156:159], v[188:191], v[38:41]
	v_mfma_f32_16x16x32_bf16 v[38:41], v[160:163], v[192:195], v[38:41]
	v_mfma_f32_16x16x32_bf16 v[22:25], v[156:159], v[196:199], v[22:25]
	v_mfma_f32_16x16x32_bf16 v[22:25], v[160:163], v[200:203], v[22:25]
	v_mfma_f32_16x16x32_bf16 v[6:9], v[156:159], v[204:207], v[6:9]
	v_mfma_f32_16x16x32_bf16 v[6:9], v[160:163], v[208:211], v[6:9]
	v_mfma_f32_16x16x32_bf16 v[58:61], v[164:167], v[180:183], v[58:61]
	v_mfma_f32_16x16x32_bf16 v[58:61], v[168:171], v[184:187], v[58:61]
	v_mfma_f32_16x16x32_bf16 v[42:45], v[164:167], v[188:191], v[42:45]
	v_mfma_f32_16x16x32_bf16 v[42:45], v[168:171], v[192:195], v[42:45]
	v_mfma_f32_16x16x32_bf16 v[26:29], v[164:167], v[196:199], v[26:29]
	v_mfma_f32_16x16x32_bf16 v[26:29], v[168:171], v[200:203], v[26:29]
	v_mfma_f32_16x16x32_bf16 v[10:13], v[164:167], v[204:207], v[10:13]
	v_mfma_f32_16x16x32_bf16 v[10:13], v[168:171], v[208:211], v[10:13]
	v_mfma_f32_16x16x32_bf16 v[50:53], v[172:175], v[180:183], v[50:53]
	v_mfma_f32_16x16x32_bf16 v[50:53], v[176:179], v[184:187], v[50:53]
	v_mfma_f32_16x16x32_bf16 v[34:37], v[172:175], v[188:191], v[34:37]
	v_mfma_f32_16x16x32_bf16 v[34:37], v[176:179], v[192:195], v[34:37]
	v_mfma_f32_16x16x32_bf16 v[18:21], v[172:175], v[196:199], v[18:21]
	v_mfma_f32_16x16x32_bf16 v[18:21], v[176:179], v[200:203], v[18:21]
	v_mfma_f32_16x16x32_bf16 v[2:5], v[172:175], v[204:207], v[2:5]
	v_mfma_f32_16x16x32_bf16 v[2:5], v[176:179], v[208:211], v[2:5]
	s_setprio 0
	s_barrier
	s_add_i32 s73, s73, 2
	s_addk_i32 s71, 0x100
	s_addk_i32 s72, 0x100
	s_cmp_ge_i32 s73, s3
	s_cbranch_scc0 .LBB0_642
	s_and_b64 vcc, exec, s[42:43]
	s_cbranch_vccz .LBB0_645

.LBB0_799:
	ds_read_b128 v[134:137], v210
	ds_read_b128 v[138:141], v210 offset:1024
	ds_read_b128 v[142:145], v210 offset:2048
	ds_read_b128 v[148:151], v210 offset:3072
	ds_read_b128 v[152:155], v211
	ds_read_b128 v[156:159], v211 offset:1024
	ds_read_b128 v[160:163], v211 offset:2048
	ds_read_b128 v[164:167], v211 offset:3072
	s_add_i32 s18, s77, 0xffbf8080
	s_cmp_eq_u32 s62, s79
	s_cselect_b32 s80, s6, s18
	s_cselect_b32 s82, s7, s78
	s_or_b32 s81, s80, 0x80
	s_add_i32 s18, s77, 0xffea8000
	s_mov_b32 m0, s63
	ds_read_b128 v[168:171], v212
	ds_read_b128 v[172:175], v212 offset:1024
	ds_read_b128 v[176:179], v212 offset:2048
	ds_read_b128 v[180:183], v212 offset:3072
	ds_read_b128 v[184:187], v212 offset:4096
	ds_read_b128 v[188:191], v212 offset:5120
	ds_read_b128 v[192:195], v212 offset:6144
	ds_read_b128 v[196:199], v212 offset:7168
	buffer_load_dwordx4 v208, s[12:15], s18 offen lds
	s_mov_b32 m0, s66
	s_nop 0
	buffer_load_dwordx4 v208, s[12:15], s77 offen lds
	s_waitcnt vmcnt(8)
	s_waitcnt lgkmcnt(0)
	s_setprio 1
	v_mfma_f32_16x16x32_bf16 v[126:129], v[134:137], v[168:171], v[126:129]
	s_barrier
	v_mfma_f32_16x16x32_bf16 v[126:129], v[138:141], v[172:175], v[126:129]
	v_mfma_f32_16x16x32_bf16 v[118:121], v[134:137], v[176:179], v[118:121]
	v_mfma_f32_16x16x32_bf16 v[118:121], v[138:141], v[180:183], v[118:121]
	v_mfma_f32_16x16x32_bf16 v[106:109], v[134:137], v[184:187], v[106:109]
	v_mfma_f32_16x16x32_bf16 v[106:109], v[138:141], v[188:191], v[106:109]
	v_mfma_f32_16x16x32_bf16 v[90:93], v[134:137], v[192:195], v[90:93]
	v_mfma_f32_16x16x32_bf16 v[90:93], v[138:141], v[196:199], v[90:93]
	v_mfma_f32_16x16x32_bf16 v[122:125], v[142:145], v[168:171], v[122:125]
	v_mfma_f32_16x16x32_bf16 v[122:125], v[148:151], v[172:175], v[122:125]
	v_mfma_f32_16x16x32_bf16 v[114:117], v[142:145], v[176:179], v[114:117]
	v_mfma_f32_16x16x32_bf16 v[114:117], v[148:151], v[180:183], v[114:117]
	v_mfma_f32_16x16x32_bf16 v[98:101], v[142:145], v[184:187], v[98:101]
	v_mfma_f32_16x16x32_bf16 v[98:101], v[148:151], v[188:191], v[98:101]
	v_mfma_f32_16x16x32_bf16 v[82:85], v[142:145], v[192:195], v[82:85]
	v_mfma_f32_16x16x32_bf16 v[82:85], v[148:151], v[196:199], v[82:85]
	v_mfma_f32_16x16x32_bf16 v[110:113], v[152:155], v[168:171], v[110:113]
	v_mfma_f32_16x16x32_bf16 v[110:113], v[156:159], v[172:175], v[110:113]
	v_mfma_f32_16x16x32_bf16 v[94:97], v[152:155], v[176:179], v[94:97]
	v_mfma_f32_16x16x32_bf16 v[94:97], v[156:159], v[180:183], v[94:97]
	v_mfma_f32_16x16x32_bf16 v[78:81], v[152:155], v[184:187], v[78:81]
	v_mfma_f32_16x16x32_bf16 v[78:81], v[156:159], v[188:191], v[78:81]
	v_mfma_f32_16x16x32_bf16 v[70:73], v[152:155], v[192:195], v[70:73]
	v_mfma_f32_16x16x32_bf16 v[70:73], v[156:159], v[196:199], v[70:73]
	v_mfma_f32_16x16x32_bf16 v[102:105], v[160:163], v[168:171], v[102:105]
	v_mfma_f32_16x16x32_bf16 v[102:105], v[164:167], v[172:175], v[102:105]
	v_mfma_f32_16x16x32_bf16 v[86:89], v[160:163], v[176:179], v[86:89]
	v_mfma_f32_16x16x32_bf16 v[86:89], v[164:167], v[180:183], v[86:89]
	v_mfma_f32_16x16x32_bf16 v[74:77], v[160:163], v[184:187], v[74:77]
	v_mfma_f32_16x16x32_bf16 v[74:77], v[164:167], v[188:191], v[74:77]
	v_mfma_f32_16x16x32_bf16 v[66:69], v[160:163], v[192:195], v[66:69]
	v_mfma_f32_16x16x32_bf16 v[66:69], v[164:167], v[196:199], v[66:69]
	s_setprio 0
	s_barrier
	s_mov_b32 m0, s25
	s_mov_b32 s18, s14
	s_mov_b32 s19, s15
	ds_read_b128 v[168:171], v212 offset:16384
	ds_read_b128 v[172:175], v212 offset:17408
	ds_read_b128 v[176:179], v212 offset:18432
	ds_read_b128 v[180:183], v212 offset:19456
	ds_read_b128 v[184:187], v212 offset:20480
	ds_read_b128 v[188:191], v212 offset:21504
	ds_read_b128 v[192:195], v212 offset:22528
	ds_read_b128 v[196:199], v212 offset:23552
	buffer_load_dwordx4 v209, s[16:19], s82 offen lds
	s_add_i32 s83, s82, 0x158000
	s_mov_b32 m0, s27
	s_nop 0
	buffer_load_dwordx4 v209, s[16:19], s83 offen lds
	s_add_i32 s83, s82, 0x2b0000
	s_mov_b32 m0, s30
	s_nop 0
	buffer_load_dwordx4 v209, s[16:19], s83 offen lds
	s_add_i32 s83, s82, 0x408000
	s_mov_b32 m0, s31
	s_nop 0
	buffer_load_dwordx4 v209, s[16:19], s83 offen lds
	s_mov_b32 m0, s21
	s_add_i32 s83, s80, 0x158000
	buffer_load_dwordx4 v208, s[12:15], s80 offen lds
	s_mov_b32 m0, s48
	s_nop 0
	buffer_load_dwordx4 v208, s[12:15], s83 offen lds
	s_waitcnt vmcnt(8)
	s_waitcnt lgkmcnt(0)
	s_setprio 1
	v_mfma_f32_16x16x32_bf16 v[62:65], v[134:137], v[168:171], v[62:65]
	s_barrier
	v_mfma_f32_16x16x32_bf16 v[62:65], v[138:141], v[172:175], v[62:65]
	v_mfma_f32_16x16x32_bf16 v[54:57], v[134:137], v[176:179], v[54:57]
	v_mfma_f32_16x16x32_bf16 v[54:57], v[138:141], v[180:183], v[54:57]
	v_mfma_f32_16x16x32_bf16 v[42:45], v[134:137], v[184:187], v[42:45]
	v_mfma_f32_16x16x32_bf16 v[42:45], v[138:141], v[188:191], v[42:45]
	v_mfma_f32_16x16x32_bf16 v[26:29], v[134:137], v[192:195], v[26:29]
	v_mfma_f32_16x16x32_bf16 v[26:29], v[138:141], v[196:199], v[26:29]
	v_mfma_f32_16x16x32_bf16 v[58:61], v[142:145], v[168:171], v[58:61]
	v_mfma_f32_16x16x32_bf16 v[58:61], v[148:151], v[172:175], v[58:61]
	v_mfma_f32_16x16x32_bf16 v[50:53], v[142:145], v[176:179], v[50:53]
	v_mfma_f32_16x16x32_bf16 v[50:53], v[148:151], v[180:183], v[50:53]
	v_mfma_f32_16x16x32_bf16 v[34:37], v[142:145], v[184:187], v[34:37]
	v_mfma_f32_16x16x32_bf16 v[34:37], v[148:151], v[188:191], v[34:37]
	v_mfma_f32_16x16x32_bf16 v[18:21], v[142:145], v[192:195], v[18:21]
	v_mfma_f32_16x16x32_bf16 v[18:21], v[148:151], v[196:199], v[18:21]
	v_mfma_f32_16x16x32_bf16 v[46:49], v[152:155], v[168:171], v[46:49]
	v_mfma_f32_16x16x32_bf16 v[46:49], v[156:159], v[172:175], v[46:49]
	v_mfma_f32_16x16x32_bf16 v[30:33], v[152:155], v[176:179], v[30:33]
	v_mfma_f32_16x16x32_bf16 v[30:33], v[156:159], v[180:183], v[30:33]
	v_mfma_f32_16x16x32_bf16 v[14:17], v[152:155], v[184:187], v[14:17]
	v_mfma_f32_16x16x32_bf16 v[14:17], v[156:159], v[188:191], v[14:17]
	v_mfma_f32_16x16x32_bf16 v[6:9], v[152:155], v[192:195], v[6:9]
	v_mfma_f32_16x16x32_bf16 v[6:9], v[156:159], v[196:199], v[6:9]
	v_mfma_f32_16x16x32_bf16 v[38:41], v[160:163], v[168:171], v[38:41]
	v_mfma_f32_16x16x32_bf16 v[38:41], v[164:167], v[172:175], v[38:41]
	v_mfma_f32_16x16x32_bf16 v[22:25], v[160:163], v[176:179], v[22:25]
	v_mfma_f32_16x16x32_bf16 v[22:25], v[164:167], v[180:183], v[22:25]
	v_mfma_f32_16x16x32_bf16 v[10:13], v[160:163], v[184:187], v[10:13]
	v_mfma_f32_16x16x32_bf16 v[10:13], v[164:167], v[188:191], v[10:13]
	v_mfma_f32_16x16x32_bf16 v[2:5], v[160:163], v[192:195], v[2:5]
	v_mfma_f32_16x16x32_bf16 v[2:5], v[164:167], v[196:199], v[2:5]
	s_setprio 0
	s_barrier
	ds_read_b128 v[134:137], v213
	ds_read_b128 v[138:141], v213 offset:1024
	ds_read_b128 v[142:145], v213 offset:2048
	ds_read_b128 v[148:151], v213 offset:3072
	ds_read_b128 v[152:155], v214
	ds_read_b128 v[156:159], v214 offset:1024
	ds_read_b128 v[160:163], v214 offset:2048
	ds_read_b128 v[164:167], v214 offset:3072
	s_mov_b32 m0, s49
	s_add_i32 s83, s80, 0x2b0000
	ds_read_b128 v[168:171], v212 offset:32768
	ds_read_b128 v[172:175], v212 offset:33792
	ds_read_b128 v[176:179], v212 offset:34816
	ds_read_b128 v[180:183], v212 offset:35840
	ds_read_b128 v[184:187], v212 offset:36864
	ds_read_b128 v[188:191], v212 offset:37888
	ds_read_b128 v[192:195], v212 offset:38912
	ds_read_b128 v[196:199], v212 offset:39936
	buffer_load_dwordx4 v208, s[12:15], s83 offen lds
	s_add_i32 s83, s80, 0x408000
	s_mov_b32 m0, s50
	s_nop 0
	buffer_load_dwordx4 v208, s[12:15], s83 offen lds
	s_waitcnt vmcnt(8)
	s_waitcnt lgkmcnt(0)
	s_setprio 1
	v_mfma_f32_16x16x32_bf16 v[126:129], v[134:137], v[168:171], v[126:129]
	s_barrier
	v_mfma_f32_16x16x32_bf16 v[126:129], v[138:141], v[172:175], v[126:129]
	v_mfma_f32_16x16x32_bf16 v[118:121], v[134:137], v[176:179], v[118:121]
	v_mfma_f32_16x16x32_bf16 v[118:121], v[138:141], v[180:183], v[118:121]
	v_mfma_f32_16x16x32_bf16 v[106:109], v[134:137], v[184:187], v[106:109]
	v_mfma_f32_16x16x32_bf16 v[106:109], v[138:141], v[188:191], v[106:109]
	v_mfma_f32_16x16x32_bf16 v[90:93], v[134:137], v[192:195], v[90:93]
	v_mfma_f32_16x16x32_bf16 v[90:93], v[138:141], v[196:199], v[90:93]
	v_mfma_f32_16x16x32_bf16 v[122:125], v[142:145], v[168:171], v[122:125]
	v_mfma_f32_16x16x32_bf16 v[122:125], v[148:151], v[172:175], v[122:125]
	v_mfma_f32_16x16x32_bf16 v[114:117], v[142:145], v[176:179], v[114:117]
	v_mfma_f32_16x16x32_bf16 v[114:117], v[148:151], v[180:183], v[114:117]
	v_mfma_f32_16x16x32_bf16 v[98:101], v[142:145], v[184:187], v[98:101]
	v_mfma_f32_16x16x32_bf16 v[98:101], v[148:151], v[188:191], v[98:101]
	v_mfma_f32_16x16x32_bf16 v[82:85], v[142:145], v[192:195], v[82:85]
	v_mfma_f32_16x16x32_bf16 v[82:85], v[148:151], v[196:199], v[82:85]
	v_mfma_f32_16x16x32_bf16 v[110:113], v[152:155], v[168:171], v[110:113]
	v_mfma_f32_16x16x32_bf16 v[110:113], v[156:159], v[172:175], v[110:113]
	v_mfma_f32_16x16x32_bf16 v[94:97], v[152:155], v[176:179], v[94:97]
	v_mfma_f32_16x16x32_bf16 v[94:97], v[156:159], v[180:183], v[94:97]
	v_mfma_f32_16x16x32_bf16 v[78:81], v[152:155], v[184:187], v[78:81]
	v_mfma_f32_16x16x32_bf16 v[78:81], v[156:159], v[188:191], v[78:81]
	v_mfma_f32_16x16x32_bf16 v[70:73], v[152:155], v[192:195], v[70:73]
	v_mfma_f32_16x16x32_bf16 v[70:73], v[156:159], v[196:199], v[70:73]
	v_mfma_f32_16x16x32_bf16 v[102:105], v[160:163], v[168:171], v[102:105]
	v_mfma_f32_16x16x32_bf16 v[102:105], v[164:167], v[172:175], v[102:105]
	v_mfma_f32_16x16x32_bf16 v[86:89], v[160:163], v[176:179], v[86:89]
	v_mfma_f32_16x16x32_bf16 v[86:89], v[164:167], v[180:183], v[86:89]
	v_mfma_f32_16x16x32_bf16 v[74:77], v[160:163], v[184:187], v[74:77]
	v_mfma_f32_16x16x32_bf16 v[74:77], v[164:167], v[188:191], v[74:77]
	v_mfma_f32_16x16x32_bf16 v[66:69], v[160:163], v[192:195], v[66:69]
	v_mfma_f32_16x16x32_bf16 v[66:69], v[164:167], v[196:199], v[66:69]
	s_setprio 0
	s_barrier
	s_mov_b32 m0, s54
	s_or_b32 s83, s82, 0x80
	ds_read_b128 v[168:171], v212 offset:49152
	ds_read_b128 v[172:175], v212 offset:50176
	ds_read_b128 v[176:179], v212 offset:51200
	ds_read_b128 v[180:183], v212 offset:52224
	ds_read_b128 v[184:187], v212 offset:53248
	ds_read_b128 v[188:191], v212 offset:54272
	ds_read_b128 v[192:195], v212 offset:55296
	ds_read_b128 v[196:199], v212 offset:56320
	buffer_load_dwordx4 v209, s[16:19], s83 offen lds
	s_add_i32 s83, s82, 0x158080
	s_mov_b32 m0, s55
	s_add_i32 s80, s80, 0x158080
	buffer_load_dwordx4 v209, s[16:19], s83 offen lds
	s_add_i32 s83, s82, 0x2b0080
	s_mov_b32 m0, s58
	s_add_i32 s82, s82, 0x408080
	buffer_load_dwordx4 v209, s[16:19], s83 offen lds
	s_mov_b32 m0, s59
	s_nop 0
	buffer_load_dwordx4 v209, s[16:19], s82 offen lds
	s_mov_b32 m0, s56
	s_nop 0
	buffer_load_dwordx4 v208, s[12:15], s81 offen lds
	s_mov_b32 m0, s57
	s_nop 0
	buffer_load_dwordx4 v208, s[12:15], s80 offen lds
	s_waitcnt vmcnt(8)
	s_waitcnt lgkmcnt(0)
	s_setprio 1
	v_mfma_f32_16x16x32_bf16 v[62:65], v[134:137], v[168:171], v[62:65]
	s_barrier
	v_mfma_f32_16x16x32_bf16 v[62:65], v[138:141], v[172:175], v[62:65]
	v_mfma_f32_16x16x32_bf16 v[54:57], v[134:137], v[176:179], v[54:57]
	v_mfma_f32_16x16x32_bf16 v[54:57], v[138:141], v[180:183], v[54:57]
	v_mfma_f32_16x16x32_bf16 v[42:45], v[134:137], v[184:187], v[42:45]
	v_mfma_f32_16x16x32_bf16 v[42:45], v[138:141], v[188:191], v[42:45]
	v_mfma_f32_16x16x32_bf16 v[26:29], v[134:137], v[192:195], v[26:29]
	v_mfma_f32_16x16x32_bf16 v[26:29], v[138:141], v[196:199], v[26:29]
	v_mfma_f32_16x16x32_bf16 v[58:61], v[142:145], v[168:171], v[58:61]
	v_mfma_f32_16x16x32_bf16 v[58:61], v[148:151], v[172:175], v[58:61]
	v_mfma_f32_16x16x32_bf16 v[50:53], v[142:145], v[176:179], v[50:53]
	v_mfma_f32_16x16x32_bf16 v[50:53], v[148:151], v[180:183], v[50:53]
	v_mfma_f32_16x16x32_bf16 v[34:37], v[142:145], v[184:187], v[34:37]
	v_mfma_f32_16x16x32_bf16 v[34:37], v[148:151], v[188:191], v[34:37]
	v_mfma_f32_16x16x32_bf16 v[18:21], v[142:145], v[192:195], v[18:21]
	v_mfma_f32_16x16x32_bf16 v[18:21], v[148:151], v[196:199], v[18:21]
	v_mfma_f32_16x16x32_bf16 v[46:49], v[152:155], v[168:171], v[46:49]
	v_mfma_f32_16x16x32_bf16 v[46:49], v[156:159], v[172:175], v[46:49]
	v_mfma_f32_16x16x32_bf16 v[30:33], v[152:155], v[176:179], v[30:33]
	v_mfma_f32_16x16x32_bf16 v[30:33], v[156:159], v[180:183], v[30:33]
	v_mfma_f32_16x16x32_bf16 v[14:17], v[152:155], v[184:187], v[14:17]
	v_mfma_f32_16x16x32_bf16 v[14:17], v[156:159], v[188:191], v[14:17]
	v_mfma_f32_16x16x32_bf16 v[6:9], v[152:155], v[192:195], v[6:9]
	v_mfma_f32_16x16x32_bf16 v[6:9], v[156:159], v[196:199], v[6:9]
	v_mfma_f32_16x16x32_bf16 v[38:41], v[160:163], v[168:171], v[38:41]
	v_mfma_f32_16x16x32_bf16 v[38:41], v[164:167], v[172:175], v[38:41]
	v_mfma_f32_16x16x32_bf16 v[22:25], v[160:163], v[176:179], v[22:25]
	v_mfma_f32_16x16x32_bf16 v[22:25], v[164:167], v[180:183], v[22:25]
	v_mfma_f32_16x16x32_bf16 v[10:13], v[160:163], v[184:187], v[10:13]
	v_mfma_f32_16x16x32_bf16 v[10:13], v[164:167], v[188:191], v[10:13]
	v_mfma_f32_16x16x32_bf16 v[2:5], v[160:163], v[192:195], v[2:5]
	v_mfma_f32_16x16x32_bf16 v[2:5], v[164:167], v[196:199], v[2:5]
	s_setprio 0
	s_barrier
	s_add_i32 s79, s79, 2
	s_addk_i32 s77, 0x100
	s_addk_i32 s78, 0x100
	s_cmp_ge_i32 s79, s3
	s_cbranch_scc0 .LBB0_799
	v_pk_mul_f32 v[184:185], v[128:129], 0.5 op_sel_hi:[1,0]
	v_pk_mul_f32 v[186:187], v[126:127], 0.5 op_sel_hi:[1,0]
	v_pk_mul_f32 v[188:189], v[124:125], 0.5 op_sel_hi:[1,0]
	v_pk_mul_f32 v[190:191], v[122:123], 0.5 op_sel_hi:[1,0]
	v_pk_mul_f32 v[198:199], v[112:113], 0.5 op_sel_hi:[1,0]
	v_pk_mul_f32 v[196:197], v[110:111], 0.5 op_sel_hi:[1,0]
	v_pk_mul_f32 v[194:195], v[104:105], 0.5 op_sel_hi:[1,0]
	v_pk_mul_f32 v[192:193], v[102:103], 0.5 op_sel_hi:[1,0]
	v_pk_mul_f32 v[182:183], v[120:121], 0.5 op_sel_hi:[1,0]
	v_pk_mul_f32 v[180:181], v[118:119], 0.5 op_sel_hi:[1,0]
	v_pk_mul_f32 v[178:179], v[116:117], 0.5 op_sel_hi:[1,0]
	v_pk_mul_f32 v[176:177], v[114:115], 0.5 op_sel_hi:[1,0]
	v_pk_mul_f32 v[172:173], v[96:97], 0.5 op_sel_hi:[1,0]
	v_pk_mul_f32 v[170:171], v[94:95], 0.5 op_sel_hi:[1,0]
	v_pk_mul_f32 v[168:169], v[88:89], 0.5 op_sel_hi:[1,0]
	v_pk_mul_f32 v[166:167], v[86:87], 0.5 op_sel_hi:[1,0]
	v_pk_mul_f32 v[164:165], v[108:109], 0.5 op_sel_hi:[1,0]
	v_pk_mul_f32 v[162:163], v[106:107], 0.5 op_sel_hi:[1,0]
	v_pk_mul_f32 v[160:161], v[100:101], 0.5 op_sel_hi:[1,0]
	v_pk_mul_f32 v[158:159], v[98:99], 0.5 op_sel_hi:[1,0]
	v_pk_mul_f32 v[156:157], v[80:81], 0.5 op_sel_hi:[1,0]
	v_pk_mul_f32 v[154:155], v[78:79], 0.5 op_sel_hi:[1,0]
	v_pk_mul_f32 v[152:153], v[76:77], 0.5 op_sel_hi:[1,0]
	v_pk_mul_f32 v[150:151], v[74:75], 0.5 op_sel_hi:[1,0]
	v_pk_mul_f32 v[144:145], v[92:93], 0.5 op_sel_hi:[1,0]
	v_pk_mul_f32 v[142:143], v[90:91], 0.5 op_sel_hi:[1,0]
	v_pk_mul_f32 v[140:141], v[84:85], 0.5 op_sel_hi:[1,0]
	v_pk_mul_f32 v[138:139], v[82:83], 0.5 op_sel_hi:[1,0]
	v_pk_mul_f32 v[136:137], v[72:73], 0.5 op_sel_hi:[1,0]
	v_pk_mul_f32 v[134:135], v[70:71], 0.5 op_sel_hi:[1,0]
	v_pk_mul_f32 v[128:129], v[68:69], 0.5 op_sel_hi:[1,0]
	v_pk_mul_f32 v[126:127], v[66:67], 0.5 op_sel_hi:[1,0]
	v_pk_mul_f32 v[122:123], v[64:65], 0.5 op_sel_hi:[1,0]
	v_pk_mul_f32 v[120:121], v[62:63], 0.5 op_sel_hi:[1,0]
	v_pk_mul_f32 v[118:119], v[60:61], 0.5 op_sel_hi:[1,0]
	v_pk_mul_f32 v[116:117], v[58:59], 0.5 op_sel_hi:[1,0]
	v_pk_mul_f32 v[112:113], v[48:49], 0.5 op_sel_hi:[1,0]
	v_pk_mul_f32 v[110:111], v[46:47], 0.5 op_sel_hi:[1,0]
	v_pk_mul_f32 v[108:109], v[40:41], 0.5 op_sel_hi:[1,0]
	v_pk_mul_f32 v[106:107], v[38:39], 0.5 op_sel_hi:[1,0]
	v_pk_mul_f32 v[104:105], v[56:57], 0.5 op_sel_hi:[1,0]
	v_pk_mul_f32 v[102:103], v[54:55], 0.5 op_sel_hi:[1,0]
	v_pk_mul_f32 v[100:101], v[52:53], 0.5 op_sel_hi:[1,0]
	v_pk_mul_f32 v[98:99], v[50:51], 0.5 op_sel_hi:[1,0]
	v_pk_mul_f32 v[96:97], v[32:33], 0.5 op_sel_hi:[1,0]
	v_pk_mul_f32 v[94:95], v[30:31], 0.5 op_sel_hi:[1,0]
	v_pk_mul_f32 v[92:93], v[24:25], 0.5 op_sel_hi:[1,0]
	v_pk_mul_f32 v[90:91], v[22:23], 0.5 op_sel_hi:[1,0]
	v_pk_mul_f32 v[88:89], v[44:45], 0.5 op_sel_hi:[1,0]
	v_pk_mul_f32 v[86:87], v[42:43], 0.5 op_sel_hi:[1,0]
	v_pk_mul_f32 v[84:85], v[36:37], 0.5 op_sel_hi:[1,0]
	v_pk_mul_f32 v[82:83], v[34:35], 0.5 op_sel_hi:[1,0]
	v_pk_mul_f32 v[80:81], v[16:17], 0.5 op_sel_hi:[1,0]
	v_pk_mul_f32 v[78:79], v[14:15], 0.5 op_sel_hi:[1,0]
	v_pk_mul_f32 v[76:77], v[12:13], 0.5 op_sel_hi:[1,0]
	v_pk_mul_f32 v[74:75], v[10:11], 0.5 op_sel_hi:[1,0]
	v_pk_mul_f32 v[72:73], v[28:29], 0.5 op_sel_hi:[1,0]
	v_pk_mul_f32 v[70:71], v[26:27], 0.5 op_sel_hi:[1,0]
	v_pk_mul_f32 v[68:69], v[20:21], 0.5 op_sel_hi:[1,0]
	v_pk_mul_f32 v[66:67], v[18:19], 0.5 op_sel_hi:[1,0]
	v_pk_mul_f32 v[64:65], v[8:9], 0.5 op_sel_hi:[1,0]
	v_pk_mul_f32 v[62:63], v[6:7], 0.5 op_sel_hi:[1,0]
	v_pk_mul_f32 v[60:61], v[4:5], 0.5 op_sel_hi:[1,0]
	v_pk_mul_f32 v[58:59], v[2:3], 0.5 op_sel_hi:[1,0]
	s_and_b64 vcc, exec, s[38:39]
	s_cbranch_vccz .LBB0_802

.LBB0_892:
	ds_read_b128 v[130:133], v172
	ds_read_b128 v[134:137], v172 offset:1024
	ds_read_b128 v[148:151], v172 offset:2048
	ds_read_b128 v[152:155], v172 offset:3072
	ds_read_b128 v[156:159], v173
	ds_read_b128 v[160:163], v173 offset:1024
	ds_read_b128 v[164:167], v173 offset:2048
	ds_read_b128 v[180:183], v173 offset:3072
	s_add_i32 s18, s8, 0xffe80080
	s_cmp_eq_u32 s77, s52
	s_cselect_b32 s53, s6, s18
	s_cselect_b32 s58, s7, s9
	s_or_b32 s57, s53, 0x80
	s_add_i32 s18, s8, 0xfff80000
	s_mov_b32 m0, s78
	ds_read_b128 v[184:187], v174
	ds_read_b128 v[188:191], v174 offset:1024
	ds_read_b128 v[192:195], v174 offset:2048
	ds_read_b128 v[196:199], v174 offset:3072
	ds_read_b128 v[200:203], v174 offset:4096
	ds_read_b128 v[204:207], v174 offset:5120
	ds_read_b128 v[208:211], v174 offset:6144
	ds_read_b128 v[212:215], v174 offset:7168
	buffer_load_dwordx4 v170, s[12:15], s18 offen lds
	s_mov_b32 m0, s79
	s_nop 0
	buffer_load_dwordx4 v170, s[12:15], s8 offen lds
	s_waitcnt vmcnt(8)
	s_waitcnt lgkmcnt(0)
	s_setprio 1
	v_mfma_f32_16x16x32_bf16 v[126:129], v[130:133], v[184:187], v[126:129]
	s_barrier
	v_mfma_f32_16x16x32_bf16 v[126:129], v[134:137], v[188:191], v[126:129]
	v_mfma_f32_16x16x32_bf16 v[110:113], v[130:133], v[192:195], v[110:113]
	v_mfma_f32_16x16x32_bf16 v[110:113], v[134:137], v[196:199], v[110:113]
	v_mfma_f32_16x16x32_bf16 v[94:97], v[130:133], v[200:203], v[94:97]
	v_mfma_f32_16x16x32_bf16 v[94:97], v[134:137], v[204:207], v[94:97]
	v_mfma_f32_16x16x32_bf16 v[78:81], v[130:133], v[208:211], v[78:81]
	v_mfma_f32_16x16x32_bf16 v[78:81], v[134:137], v[212:215], v[78:81]
	v_mfma_f32_16x16x32_bf16 v[118:121], v[148:151], v[184:187], v[118:121]
	v_mfma_f32_16x16x32_bf16 v[118:121], v[152:155], v[188:191], v[118:121]
	v_mfma_f32_16x16x32_bf16 v[102:105], v[148:151], v[192:195], v[102:105]
	v_mfma_f32_16x16x32_bf16 v[102:105], v[152:155], v[196:199], v[102:105]
	v_mfma_f32_16x16x32_bf16 v[90:93], v[148:151], v[200:203], v[90:93]
	v_mfma_f32_16x16x32_bf16 v[90:93], v[152:155], v[204:207], v[90:93]
	v_mfma_f32_16x16x32_bf16 v[70:73], v[148:151], v[208:211], v[70:73]
	v_mfma_f32_16x16x32_bf16 v[70:73], v[152:155], v[212:215], v[70:73]
	v_mfma_f32_16x16x32_bf16 v[122:125], v[156:159], v[184:187], v[122:125]
	v_mfma_f32_16x16x32_bf16 v[122:125], v[160:163], v[188:191], v[122:125]
	v_mfma_f32_16x16x32_bf16 v[106:109], v[156:159], v[192:195], v[106:109]
	v_mfma_f32_16x16x32_bf16 v[106:109], v[160:163], v[196:199], v[106:109]
	v_mfma_f32_16x16x32_bf16 v[86:89], v[156:159], v[200:203], v[86:89]
	v_mfma_f32_16x16x32_bf16 v[86:89], v[160:163], v[204:207], v[86:89]
	v_mfma_f32_16x16x32_bf16 v[74:77], v[156:159], v[208:211], v[74:77]
	v_mfma_f32_16x16x32_bf16 v[74:77], v[160:163], v[212:215], v[74:77]
	v_mfma_f32_16x16x32_bf16 v[114:117], v[164:167], v[184:187], v[114:117]
	v_mfma_f32_16x16x32_bf16 v[114:117], v[180:183], v[188:191], v[114:117]
	v_mfma_f32_16x16x32_bf16 v[98:101], v[164:167], v[192:195], v[98:101]
	v_mfma_f32_16x16x32_bf16 v[98:101], v[180:183], v[196:199], v[98:101]
	v_mfma_f32_16x16x32_bf16 v[82:85], v[164:167], v[200:203], v[82:85]
	v_mfma_f32_16x16x32_bf16 v[82:85], v[180:183], v[204:207], v[82:85]
	v_mfma_f32_16x16x32_bf16 v[66:69], v[164:167], v[208:211], v[66:69]
	v_mfma_f32_16x16x32_bf16 v[66:69], v[180:183], v[212:215], v[66:69]
	s_setprio 0
	s_barrier
	s_mov_b32 m0, s27
	s_mov_b32 s18, s14
	s_mov_b32 s19, s15
	ds_read_b128 v[184:187], v174 offset:16384
	ds_read_b128 v[188:191], v174 offset:17408
	ds_read_b128 v[192:195], v174 offset:18432
	ds_read_b128 v[196:199], v174 offset:19456
	ds_read_b128 v[200:203], v174 offset:20480
	ds_read_b128 v[204:207], v174 offset:21504
	ds_read_b128 v[208:211], v174 offset:22528
	ds_read_b128 v[212:215], v174 offset:23552
	buffer_load_dwordx4 v171, s[16:19], s58 offen lds
	s_add_i32 s59, s58, 0x80000
	s_mov_b32 m0, s60
	s_nop 0
	buffer_load_dwordx4 v171, s[16:19], s59 offen lds
	s_add_i32 s59, s58, 0x100000
	s_mov_b32 m0, s61
	s_nop 0
	buffer_load_dwordx4 v171, s[16:19], s59 offen lds
	s_add_i32 s59, s58, 0x180000
	s_mov_b32 m0, s62
	s_nop 0
	buffer_load_dwordx4 v171, s[16:19], s59 offen lds
	s_mov_b32 m0, s25
	s_add_i32 s59, s53, 0x80000
	buffer_load_dwordx4 v170, s[12:15], s53 offen lds
	s_mov_b32 m0, s63
	s_nop 0
	buffer_load_dwordx4 v170, s[12:15], s59 offen lds
	s_waitcnt vmcnt(8)
	s_waitcnt lgkmcnt(0)
	s_setprio 1
	v_mfma_f32_16x16x32_bf16 v[62:65], v[130:133], v[184:187], v[62:65]
	s_barrier
	v_mfma_f32_16x16x32_bf16 v[62:65], v[134:137], v[188:191], v[62:65]
	v_mfma_f32_16x16x32_bf16 v[46:49], v[130:133], v[192:195], v[46:49]
	v_mfma_f32_16x16x32_bf16 v[46:49], v[134:137], v[196:199], v[46:49]
	v_mfma_f32_16x16x32_bf16 v[30:33], v[130:133], v[200:203], v[30:33]
	v_mfma_f32_16x16x32_bf16 v[30:33], v[134:137], v[204:207], v[30:33]
	v_mfma_f32_16x16x32_bf16 v[14:17], v[130:133], v[208:211], v[14:17]
	v_mfma_f32_16x16x32_bf16 v[14:17], v[134:137], v[212:215], v[14:17]
	v_mfma_f32_16x16x32_bf16 v[54:57], v[148:151], v[184:187], v[54:57]
	v_mfma_f32_16x16x32_bf16 v[54:57], v[152:155], v[188:191], v[54:57]
	v_mfma_f32_16x16x32_bf16 v[38:41], v[148:151], v[192:195], v[38:41]
	v_mfma_f32_16x16x32_bf16 v[38:41], v[152:155], v[196:199], v[38:41]
	v_mfma_f32_16x16x32_bf16 v[22:25], v[148:151], v[200:203], v[22:25]
	v_mfma_f32_16x16x32_bf16 v[22:25], v[152:155], v[204:207], v[22:25]
	v_mfma_f32_16x16x32_bf16 v[6:9], v[148:151], v[208:211], v[6:9]
	v_mfma_f32_16x16x32_bf16 v[6:9], v[152:155], v[212:215], v[6:9]
	v_mfma_f32_16x16x32_bf16 v[58:61], v[156:159], v[184:187], v[58:61]
	v_mfma_f32_16x16x32_bf16 v[58:61], v[160:163], v[188:191], v[58:61]
	v_mfma_f32_16x16x32_bf16 v[42:45], v[156:159], v[192:195], v[42:45]
	v_mfma_f32_16x16x32_bf16 v[42:45], v[160:163], v[196:199], v[42:45]
	v_mfma_f32_16x16x32_bf16 v[26:29], v[156:159], v[200:203], v[26:29]
	v_mfma_f32_16x16x32_bf16 v[26:29], v[160:163], v[204:207], v[26:29]
	v_mfma_f32_16x16x32_bf16 v[10:13], v[156:159], v[208:211], v[10:13]
	v_mfma_f32_16x16x32_bf16 v[10:13], v[160:163], v[212:215], v[10:13]
	v_mfma_f32_16x16x32_bf16 v[50:53], v[164:167], v[184:187], v[50:53]
	v_mfma_f32_16x16x32_bf16 v[50:53], v[180:183], v[188:191], v[50:53]
	v_mfma_f32_16x16x32_bf16 v[34:37], v[164:167], v[192:195], v[34:37]
	v_mfma_f32_16x16x32_bf16 v[34:37], v[180:183], v[196:199], v[34:37]
	v_mfma_f32_16x16x32_bf16 v[18:21], v[164:167], v[200:203], v[18:21]
	v_mfma_f32_16x16x32_bf16 v[18:21], v[180:183], v[204:207], v[18:21]
	v_mfma_f32_16x16x32_bf16 v[2:5], v[164:167], v[208:211], v[2:5]
	v_mfma_f32_16x16x32_bf16 v[2:5], v[180:183], v[212:215], v[2:5]
	s_setprio 0
	s_barrier
	ds_read_b128 v[130:133], v175
	ds_read_b128 v[134:137], v175 offset:1024
	ds_read_b128 v[148:151], v175 offset:2048
	ds_read_b128 v[152:155], v175 offset:3072
	ds_read_b128 v[156:159], v176
	ds_read_b128 v[160:163], v176 offset:1024
	ds_read_b128 v[164:167], v176 offset:2048
	ds_read_b128 v[180:183], v176 offset:3072
	s_mov_b32 m0, s64
	s_add_i32 s59, s53, 0x100000
	ds_read_b128 v[184:187], v174 offset:32768
	ds_read_b128 v[188:191], v174 offset:33792
	ds_read_b128 v[192:195], v174 offset:34816
	ds_read_b128 v[196:199], v174 offset:35840
	ds_read_b128 v[200:203], v174 offset:36864
	ds_read_b128 v[204:207], v174 offset:37888
	ds_read_b128 v[208:211], v174 offset:38912
	ds_read_b128 v[212:215], v174 offset:39936
	buffer_load_dwordx4 v170, s[12:15], s59 offen lds
	s_add_i32 s59, s53, 0x180000
	s_mov_b32 m0, s65
	s_nop 0
	buffer_load_dwordx4 v170, s[12:15], s59 offen lds
	s_waitcnt vmcnt(8)
	s_waitcnt lgkmcnt(0)
	s_setprio 1
	v_mfma_f32_16x16x32_bf16 v[126:129], v[130:133], v[184:187], v[126:129]
	s_barrier
	v_mfma_f32_16x16x32_bf16 v[126:129], v[134:137], v[188:191], v[126:129]
	v_mfma_f32_16x16x32_bf16 v[110:113], v[130:133], v[192:195], v[110:113]
	v_mfma_f32_16x16x32_bf16 v[110:113], v[134:137], v[196:199], v[110:113]
	v_mfma_f32_16x16x32_bf16 v[94:97], v[130:133], v[200:203], v[94:97]
	v_mfma_f32_16x16x32_bf16 v[94:97], v[134:137], v[204:207], v[94:97]
	v_mfma_f32_16x16x32_bf16 v[78:81], v[130:133], v[208:211], v[78:81]
	v_mfma_f32_16x16x32_bf16 v[78:81], v[134:137], v[212:215], v[78:81]
	v_mfma_f32_16x16x32_bf16 v[118:121], v[148:151], v[184:187], v[118:121]
	v_mfma_f32_16x16x32_bf16 v[118:121], v[152:155], v[188:191], v[118:121]
	v_mfma_f32_16x16x32_bf16 v[102:105], v[148:151], v[192:195], v[102:105]
	v_mfma_f32_16x16x32_bf16 v[102:105], v[152:155], v[196:199], v[102:105]
	v_mfma_f32_16x16x32_bf16 v[90:93], v[148:151], v[200:203], v[90:93]
	v_mfma_f32_16x16x32_bf16 v[90:93], v[152:155], v[204:207], v[90:93]
	v_mfma_f32_16x16x32_bf16 v[70:73], v[148:151], v[208:211], v[70:73]
	v_mfma_f32_16x16x32_bf16 v[70:73], v[152:155], v[212:215], v[70:73]
	v_mfma_f32_16x16x32_bf16 v[122:125], v[156:159], v[184:187], v[122:125]
	v_mfma_f32_16x16x32_bf16 v[122:125], v[160:163], v[188:191], v[122:125]
	v_mfma_f32_16x16x32_bf16 v[106:109], v[156:159], v[192:195], v[106:109]
	v_mfma_f32_16x16x32_bf16 v[106:109], v[160:163], v[196:199], v[106:109]
	v_mfma_f32_16x16x32_bf16 v[86:89], v[156:159], v[200:203], v[86:89]
	v_mfma_f32_16x16x32_bf16 v[86:89], v[160:163], v[204:207], v[86:89]
	v_mfma_f32_16x16x32_bf16 v[74:77], v[156:159], v[208:211], v[74:77]
	v_mfma_f32_16x16x32_bf16 v[74:77], v[160:163], v[212:215], v[74:77]
	v_mfma_f32_16x16x32_bf16 v[114:117], v[164:167], v[184:187], v[114:117]
	v_mfma_f32_16x16x32_bf16 v[114:117], v[180:183], v[188:191], v[114:117]
	v_mfma_f32_16x16x32_bf16 v[98:101], v[164:167], v[192:195], v[98:101]
	v_mfma_f32_16x16x32_bf16 v[98:101], v[180:183], v[196:199], v[98:101]
	v_mfma_f32_16x16x32_bf16 v[82:85], v[164:167], v[200:203], v[82:85]
	v_mfma_f32_16x16x32_bf16 v[82:85], v[180:183], v[204:207], v[82:85]
	v_mfma_f32_16x16x32_bf16 v[66:69], v[164:167], v[208:211], v[66:69]
	v_mfma_f32_16x16x32_bf16 v[66:69], v[180:183], v[212:215], v[66:69]
	s_setprio 0
	s_barrier
	s_mov_b32 m0, s70
	s_or_b32 s59, s58, 0x80
	ds_read_b128 v[184:187], v174 offset:49152
	ds_read_b128 v[188:191], v174 offset:50176
	ds_read_b128 v[192:195], v174 offset:51200
	ds_read_b128 v[196:199], v174 offset:52224
	ds_read_b128 v[200:203], v174 offset:53248
	ds_read_b128 v[204:207], v174 offset:54272
	ds_read_b128 v[208:211], v174 offset:55296
	ds_read_b128 v[212:215], v174 offset:56320
	buffer_load_dwordx4 v171, s[16:19], s59 offen lds
	s_add_i32 s59, s58, 0x80080
	s_mov_b32 m0, s71
	s_add_i32 s53, s53, 0x80080
	buffer_load_dwordx4 v171, s[16:19], s59 offen lds
	s_add_i32 s59, s58, 0x100080
	s_mov_b32 m0, s74
	s_add_i32 s58, s58, 0x180080
	buffer_load_dwordx4 v171, s[16:19], s59 offen lds
	s_mov_b32 m0, s75
	s_nop 0
	buffer_load_dwordx4 v171, s[16:19], s58 offen lds
	s_mov_b32 m0, s72
	s_nop 0
	buffer_load_dwordx4 v170, s[12:15], s57 offen lds
	s_mov_b32 m0, s73
	s_nop 0
	buffer_load_dwordx4 v170, s[12:15], s53 offen lds
	s_waitcnt vmcnt(8)
	s_waitcnt lgkmcnt(0)
	s_setprio 1
	v_mfma_f32_16x16x32_bf16 v[62:65], v[130:133], v[184:187], v[62:65]
	s_barrier
	v_mfma_f32_16x16x32_bf16 v[62:65], v[134:137], v[188:191], v[62:65]
	v_mfma_f32_16x16x32_bf16 v[46:49], v[130:133], v[192:195], v[46:49]
	v_mfma_f32_16x16x32_bf16 v[46:49], v[134:137], v[196:199], v[46:49]
	v_mfma_f32_16x16x32_bf16 v[30:33], v[130:133], v[200:203], v[30:33]
	v_mfma_f32_16x16x32_bf16 v[30:33], v[134:137], v[204:207], v[30:33]
	v_mfma_f32_16x16x32_bf16 v[14:17], v[130:133], v[208:211], v[14:17]
	v_mfma_f32_16x16x32_bf16 v[14:17], v[134:137], v[212:215], v[14:17]
	v_mfma_f32_16x16x32_bf16 v[54:57], v[148:151], v[184:187], v[54:57]
	v_mfma_f32_16x16x32_bf16 v[54:57], v[152:155], v[188:191], v[54:57]
	v_mfma_f32_16x16x32_bf16 v[38:41], v[148:151], v[192:195], v[38:41]
	v_mfma_f32_16x16x32_bf16 v[38:41], v[152:155], v[196:199], v[38:41]
	v_mfma_f32_16x16x32_bf16 v[22:25], v[148:151], v[200:203], v[22:25]
	v_mfma_f32_16x16x32_bf16 v[22:25], v[152:155], v[204:207], v[22:25]
	v_mfma_f32_16x16x32_bf16 v[6:9], v[148:151], v[208:211], v[6:9]
	v_mfma_f32_16x16x32_bf16 v[6:9], v[152:155], v[212:215], v[6:9]
	v_mfma_f32_16x16x32_bf16 v[58:61], v[156:159], v[184:187], v[58:61]
	v_mfma_f32_16x16x32_bf16 v[58:61], v[160:163], v[188:191], v[58:61]
	v_mfma_f32_16x16x32_bf16 v[42:45], v[156:159], v[192:195], v[42:45]
	v_mfma_f32_16x16x32_bf16 v[42:45], v[160:163], v[196:199], v[42:45]
	v_mfma_f32_16x16x32_bf16 v[26:29], v[156:159], v[200:203], v[26:29]
	v_mfma_f32_16x16x32_bf16 v[26:29], v[160:163], v[204:207], v[26:29]
	v_mfma_f32_16x16x32_bf16 v[10:13], v[156:159], v[208:211], v[10:13]
	v_mfma_f32_16x16x32_bf16 v[10:13], v[160:163], v[212:215], v[10:13]
	v_mfma_f32_16x16x32_bf16 v[50:53], v[164:167], v[184:187], v[50:53]
	v_mfma_f32_16x16x32_bf16 v[50:53], v[180:183], v[188:191], v[50:53]
	v_mfma_f32_16x16x32_bf16 v[34:37], v[164:167], v[192:195], v[34:37]
	v_mfma_f32_16x16x32_bf16 v[34:37], v[180:183], v[196:199], v[34:37]
	v_mfma_f32_16x16x32_bf16 v[18:21], v[164:167], v[200:203], v[18:21]
	v_mfma_f32_16x16x32_bf16 v[18:21], v[180:183], v[204:207], v[18:21]
	v_mfma_f32_16x16x32_bf16 v[2:5], v[164:167], v[208:211], v[2:5]
	v_mfma_f32_16x16x32_bf16 v[2:5], v[180:183], v[212:215], v[2:5]
	s_setprio 0
	s_barrier
	s_add_i32 s52, s52, 2
	s_addk_i32 s8, 0x100
	s_addk_i32 s9, 0x100
	s_cmp_ge_i32 s52, s21
	s_cbranch_scc0 .LBB0_892
	s_and_b64 vcc, exec, s[48:49]
	s_cbranch_vccz .LBB0_895

.LBB0_1020:
	v_add_u32_e32 v142, 0x10000, v162
	v_add_u32_e32 v150, 0x14000, v162
	ds_read_b128 v[130:133], v142
	ds_read_b128 v[134:137], v142 offset:1024
	ds_read_b128 v[138:141], v142 offset:2048
	ds_read_b128 v[142:145], v142 offset:3072
	ds_read_b128 v[154:157], v150
	ds_read_b128 v[164:167], v150 offset:1024
	ds_read_b128 v[168:171], v150 offset:2048
	ds_read_b128 v[172:175], v150 offset:3072
	s_add_i32 s90, s6, 0x100
	s_add_i32 s7, s88, s6
	s_cmp_eq_u32 s81, s89
	s_cselect_b32 s91, 0, s90
	s_cselect_b32 s93, s87, s7
	s_add_i32 s91, s91, s70
	s_or_b32 s92, s91, 0x80
	s_add_i32 s6, s3, s6
	s_mov_b32 m0, s82
	s_add_i32 s7, s6, 0x20080
	ds_read_b128 v[176:179], v163
	ds_read_b128 v[180:183], v163 offset:1024
	ds_read_b128 v[184:187], v163 offset:2048
	ds_read_b128 v[188:191], v163 offset:3072
	ds_read_b128 v[192:195], v163 offset:4096
	ds_read_b128 v[196:199], v163 offset:5120
	ds_read_b128 v[200:203], v163 offset:6144
	ds_read_b128 v[204:207], v163 offset:7168
	buffer_load_dwordx4 v161, s[12:15], s7 offen lds
	s_add_i32 s6, s6, 0x30080
	s_mov_b32 m0, s83
	s_nop 0
	buffer_load_dwordx4 v161, s[12:15], s6 offen lds
	s_waitcnt vmcnt(8)
	s_waitcnt lgkmcnt(0)
	s_setprio 1
	v_mfma_f32_16x16x32_bf16 v[126:129], v[130:133], v[176:179], v[126:129]
	s_barrier
	v_mfma_f32_16x16x32_bf16 v[126:129], v[134:137], v[180:183], v[126:129]
	v_mfma_f32_16x16x32_bf16 v[110:113], v[130:133], v[184:187], v[110:113]
	v_mfma_f32_16x16x32_bf16 v[110:113], v[134:137], v[188:191], v[110:113]
	v_mfma_f32_16x16x32_bf16 v[94:97], v[130:133], v[192:195], v[94:97]
	v_mfma_f32_16x16x32_bf16 v[94:97], v[134:137], v[196:199], v[94:97]
	v_mfma_f32_16x16x32_bf16 v[78:81], v[130:133], v[200:203], v[78:81]
	v_mfma_f32_16x16x32_bf16 v[78:81], v[134:137], v[204:207], v[78:81]
	v_mfma_f32_16x16x32_bf16 v[122:125], v[138:141], v[176:179], v[122:125]
	v_mfma_f32_16x16x32_bf16 v[122:125], v[142:145], v[180:183], v[122:125]
	v_mfma_f32_16x16x32_bf16 v[106:109], v[138:141], v[184:187], v[106:109]
	v_mfma_f32_16x16x32_bf16 v[106:109], v[142:145], v[188:191], v[106:109]
	v_mfma_f32_16x16x32_bf16 v[90:93], v[138:141], v[192:195], v[90:93]
	v_mfma_f32_16x16x32_bf16 v[90:93], v[142:145], v[196:199], v[90:93]
	v_mfma_f32_16x16x32_bf16 v[74:77], v[138:141], v[200:203], v[74:77]
	v_mfma_f32_16x16x32_bf16 v[74:77], v[142:145], v[204:207], v[74:77]
	v_mfma_f32_16x16x32_bf16 v[118:121], v[154:157], v[176:179], v[118:121]
	v_mfma_f32_16x16x32_bf16 v[118:121], v[164:167], v[180:183], v[118:121]
	v_mfma_f32_16x16x32_bf16 v[102:105], v[154:157], v[184:187], v[102:105]
	v_mfma_f32_16x16x32_bf16 v[102:105], v[164:167], v[188:191], v[102:105]
	v_mfma_f32_16x16x32_bf16 v[86:89], v[154:157], v[192:195], v[86:89]
	v_mfma_f32_16x16x32_bf16 v[86:89], v[164:167], v[196:199], v[86:89]
	v_mfma_f32_16x16x32_bf16 v[70:73], v[154:157], v[200:203], v[70:73]
	v_mfma_f32_16x16x32_bf16 v[70:73], v[164:167], v[204:207], v[70:73]
	v_mfma_f32_16x16x32_bf16 v[114:117], v[168:171], v[176:179], v[114:117]
	v_mfma_f32_16x16x32_bf16 v[114:117], v[172:175], v[180:183], v[114:117]
	v_mfma_f32_16x16x32_bf16 v[98:101], v[168:171], v[184:187], v[98:101]
	v_mfma_f32_16x16x32_bf16 v[98:101], v[172:175], v[188:191], v[98:101]
	v_mfma_f32_16x16x32_bf16 v[82:85], v[168:171], v[192:195], v[82:85]
	v_mfma_f32_16x16x32_bf16 v[82:85], v[172:175], v[196:199], v[82:85]
	v_mfma_f32_16x16x32_bf16 v[66:69], v[168:171], v[200:203], v[66:69]
	v_mfma_f32_16x16x32_bf16 v[66:69], v[172:175], v[204:207], v[66:69]
	s_setprio 0
	s_barrier
	s_mov_b32 m0, s66
	s_mov_b32 s6, s14
	s_mov_b32 s7, s15
	ds_read_b128 v[176:179], v163 offset:16384
	ds_read_b128 v[180:183], v163 offset:17408
	ds_read_b128 v[184:187], v163 offset:18432
	ds_read_b128 v[188:191], v163 offset:19456
	ds_read_b128 v[192:195], v163 offset:20480
	ds_read_b128 v[196:199], v163 offset:21504
	ds_read_b128 v[200:203], v163 offset:22528
	ds_read_b128 v[204:207], v163 offset:23552
	buffer_load_dwordx4 v160, s[4:7], s93 offen lds
	s_add_i32 s94, s93, 0x10000
	s_mov_b32 m0, s67
	s_nop 0
	buffer_load_dwordx4 v160, s[4:7], s94 offen lds
	s_add_i32 s94, s93, 0x20000
	s_mov_b32 m0, s68
	s_nop 0
	buffer_load_dwordx4 v160, s[4:7], s94 offen lds
	s_add_i32 s94, s93, 0x30000
	s_mov_b32 m0, s69
	s_nop 0
	buffer_load_dwordx4 v160, s[4:7], s94 offen lds
	s_mov_b32 m0, s65
	s_add_i32 s94, s91, 0x10000
	buffer_load_dwordx4 v161, s[12:15], s91 offen lds
	s_mov_b32 m0, s71
	s_nop 0
	buffer_load_dwordx4 v161, s[12:15], s94 offen lds
	s_waitcnt vmcnt(8)
	s_waitcnt lgkmcnt(0)
	s_setprio 1
	v_mfma_f32_16x16x32_bf16 v[62:65], v[130:133], v[176:179], v[62:65]
	s_barrier
	v_mfma_f32_16x16x32_bf16 v[62:65], v[134:137], v[180:183], v[62:65]
	v_mfma_f32_16x16x32_bf16 v[46:49], v[130:133], v[184:187], v[46:49]
	v_mfma_f32_16x16x32_bf16 v[46:49], v[134:137], v[188:191], v[46:49]
	v_mfma_f32_16x16x32_bf16 v[30:33], v[130:133], v[192:195], v[30:33]
	v_mfma_f32_16x16x32_bf16 v[30:33], v[134:137], v[196:199], v[30:33]
	v_mfma_f32_16x16x32_bf16 v[14:17], v[130:133], v[200:203], v[14:17]
	v_mfma_f32_16x16x32_bf16 v[14:17], v[134:137], v[204:207], v[14:17]
	v_mfma_f32_16x16x32_bf16 v[58:61], v[138:141], v[176:179], v[58:61]
	v_mfma_f32_16x16x32_bf16 v[58:61], v[142:145], v[180:183], v[58:61]
	v_mfma_f32_16x16x32_bf16 v[42:45], v[138:141], v[184:187], v[42:45]
	v_mfma_f32_16x16x32_bf16 v[42:45], v[142:145], v[188:191], v[42:45]
	v_mfma_f32_16x16x32_bf16 v[26:29], v[138:141], v[192:195], v[26:29]
	v_mfma_f32_16x16x32_bf16 v[26:29], v[142:145], v[196:199], v[26:29]
	v_mfma_f32_16x16x32_bf16 v[10:13], v[138:141], v[200:203], v[10:13]
	v_mfma_f32_16x16x32_bf16 v[10:13], v[142:145], v[204:207], v[10:13]
	v_mfma_f32_16x16x32_bf16 v[54:57], v[154:157], v[176:179], v[54:57]
	v_mfma_f32_16x16x32_bf16 v[54:57], v[164:167], v[180:183], v[54:57]
	v_mfma_f32_16x16x32_bf16 v[38:41], v[154:157], v[184:187], v[38:41]
	v_mfma_f32_16x16x32_bf16 v[38:41], v[164:167], v[188:191], v[38:41]
	v_mfma_f32_16x16x32_bf16 v[22:25], v[154:157], v[192:195], v[22:25]
	v_mfma_f32_16x16x32_bf16 v[22:25], v[164:167], v[196:199], v[22:25]
	v_mfma_f32_16x16x32_bf16 v[6:9], v[154:157], v[200:203], v[6:9]
	v_mfma_f32_16x16x32_bf16 v[6:9], v[164:167], v[204:207], v[6:9]
	v_mfma_f32_16x16x32_bf16 v[50:53], v[168:171], v[176:179], v[50:53]
	v_mfma_f32_16x16x32_bf16 v[50:53], v[172:175], v[180:183], v[50:53]
	v_mfma_f32_16x16x32_bf16 v[34:37], v[168:171], v[184:187], v[34:37]
	v_mfma_f32_16x16x32_bf16 v[34:37], v[172:175], v[188:191], v[34:37]
	v_mfma_f32_16x16x32_bf16 v[18:21], v[168:171], v[192:195], v[18:21]
	v_mfma_f32_16x16x32_bf16 v[18:21], v[172:175], v[196:199], v[18:21]
	v_mfma_f32_16x16x32_bf16 v[2:5], v[168:171], v[200:203], v[2:5]
	v_mfma_f32_16x16x32_bf16 v[2:5], v[172:175], v[204:207], v[2:5]
	s_setprio 0
	s_barrier
	v_add_u32_e32 v142, 0x18000, v162
	v_add_u32_e32 v150, 0x1c000, v162
	ds_read_b128 v[130:133], v142
	ds_read_b128 v[134:137], v142 offset:1024
	ds_read_b128 v[138:141], v142 offset:2048
	ds_read_b128 v[142:145], v142 offset:3072
	ds_read_b128 v[154:157], v150
	ds_read_b128 v[164:167], v150 offset:1024
	ds_read_b128 v[168:171], v150 offset:2048
	ds_read_b128 v[172:175], v150 offset:3072
	s_mov_b32 m0, s72
	s_add_i32 s94, s91, 0x20000
	ds_read_b128 v[176:179], v163 offset:32768
	ds_read_b128 v[180:183], v163 offset:33792
	ds_read_b128 v[184:187], v163 offset:34816
	ds_read_b128 v[188:191], v163 offset:35840
	ds_read_b128 v[192:195], v163 offset:36864
	ds_read_b128 v[196:199], v163 offset:37888
	ds_read_b128 v[200:203], v163 offset:38912
	ds_read_b128 v[204:207], v163 offset:39936
	buffer_load_dwordx4 v161, s[12:15], s94 offen lds
	s_add_i32 s94, s91, 0x30000
	s_mov_b32 m0, s73
	s_nop 0
	buffer_load_dwordx4 v161, s[12:15], s94 offen lds
	s_waitcnt vmcnt(8)
	s_waitcnt lgkmcnt(0)
	s_setprio 1
	v_mfma_f32_16x16x32_bf16 v[126:129], v[130:133], v[176:179], v[126:129]
	s_barrier
	v_mfma_f32_16x16x32_bf16 v[126:129], v[134:137], v[180:183], v[126:129]
	v_mfma_f32_16x16x32_bf16 v[110:113], v[130:133], v[184:187], v[110:113]
	v_mfma_f32_16x16x32_bf16 v[110:113], v[134:137], v[188:191], v[110:113]
	v_mfma_f32_16x16x32_bf16 v[94:97], v[130:133], v[192:195], v[94:97]
	v_mfma_f32_16x16x32_bf16 v[94:97], v[134:137], v[196:199], v[94:97]
	v_mfma_f32_16x16x32_bf16 v[78:81], v[130:133], v[200:203], v[78:81]
	v_mfma_f32_16x16x32_bf16 v[78:81], v[134:137], v[204:207], v[78:81]
	v_mfma_f32_16x16x32_bf16 v[122:125], v[138:141], v[176:179], v[122:125]
	v_mfma_f32_16x16x32_bf16 v[122:125], v[142:145], v[180:183], v[122:125]
	v_mfma_f32_16x16x32_bf16 v[106:109], v[138:141], v[184:187], v[106:109]
	v_mfma_f32_16x16x32_bf16 v[106:109], v[142:145], v[188:191], v[106:109]
	v_mfma_f32_16x16x32_bf16 v[90:93], v[138:141], v[192:195], v[90:93]
	v_mfma_f32_16x16x32_bf16 v[90:93], v[142:145], v[196:199], v[90:93]
	v_mfma_f32_16x16x32_bf16 v[74:77], v[138:141], v[200:203], v[74:77]
	v_mfma_f32_16x16x32_bf16 v[74:77], v[142:145], v[204:207], v[74:77]
	v_mfma_f32_16x16x32_bf16 v[118:121], v[154:157], v[176:179], v[118:121]
	v_mfma_f32_16x16x32_bf16 v[118:121], v[164:167], v[180:183], v[118:121]
	v_mfma_f32_16x16x32_bf16 v[102:105], v[154:157], v[184:187], v[102:105]
	v_mfma_f32_16x16x32_bf16 v[102:105], v[164:167], v[188:191], v[102:105]
	v_mfma_f32_16x16x32_bf16 v[86:89], v[154:157], v[192:195], v[86:89]
	v_mfma_f32_16x16x32_bf16 v[86:89], v[164:167], v[196:199], v[86:89]
	v_mfma_f32_16x16x32_bf16 v[70:73], v[154:157], v[200:203], v[70:73]
	v_mfma_f32_16x16x32_bf16 v[70:73], v[164:167], v[204:207], v[70:73]
	v_mfma_f32_16x16x32_bf16 v[114:117], v[168:171], v[176:179], v[114:117]
	v_mfma_f32_16x16x32_bf16 v[114:117], v[172:175], v[180:183], v[114:117]
	v_mfma_f32_16x16x32_bf16 v[98:101], v[168:171], v[184:187], v[98:101]
	v_mfma_f32_16x16x32_bf16 v[98:101], v[172:175], v[188:191], v[98:101]
	v_mfma_f32_16x16x32_bf16 v[82:85], v[168:171], v[192:195], v[82:85]
	v_mfma_f32_16x16x32_bf16 v[82:85], v[172:175], v[196:199], v[82:85]
	v_mfma_f32_16x16x32_bf16 v[66:69], v[168:171], v[200:203], v[66:69]
	v_mfma_f32_16x16x32_bf16 v[66:69], v[172:175], v[204:207], v[66:69]
	s_setprio 0
	s_barrier
	s_mov_b32 m0, s74
	s_or_b32 s94, s93, 0x80
	ds_read_b128 v[176:179], v163 offset:49152
	ds_read_b128 v[180:183], v163 offset:50176
	ds_read_b128 v[184:187], v163 offset:51200
	ds_read_b128 v[188:191], v163 offset:52224
	ds_read_b128 v[192:195], v163 offset:53248
	ds_read_b128 v[196:199], v163 offset:54272
	ds_read_b128 v[200:203], v163 offset:55296
	ds_read_b128 v[204:207], v163 offset:56320
	buffer_load_dwordx4 v160, s[4:7], s94 offen lds
	s_add_i32 s94, s93, 0x10080
	s_mov_b32 m0, s75
	s_add_i32 s91, s91, 0x10080
	buffer_load_dwordx4 v160, s[4:7], s94 offen lds
	s_add_i32 s94, s93, 0x20080
	s_mov_b32 m0, s78
	s_add_i32 s93, s93, 0x30080
	buffer_load_dwordx4 v160, s[4:7], s94 offen lds
	s_mov_b32 m0, s79
	s_nop 0
	buffer_load_dwordx4 v160, s[4:7], s93 offen lds
	s_mov_b32 m0, s76
	s_nop 0
	buffer_load_dwordx4 v161, s[12:15], s92 offen lds
	s_mov_b32 m0, s77
	s_nop 0
	buffer_load_dwordx4 v161, s[12:15], s91 offen lds
	s_waitcnt vmcnt(8)
	s_waitcnt lgkmcnt(0)
	s_setprio 1
	v_mfma_f32_16x16x32_bf16 v[62:65], v[130:133], v[176:179], v[62:65]
	s_barrier
	v_mfma_f32_16x16x32_bf16 v[62:65], v[134:137], v[180:183], v[62:65]
	v_mfma_f32_16x16x32_bf16 v[46:49], v[130:133], v[184:187], v[46:49]
	v_mfma_f32_16x16x32_bf16 v[46:49], v[134:137], v[188:191], v[46:49]
	v_mfma_f32_16x16x32_bf16 v[30:33], v[130:133], v[192:195], v[30:33]
	v_mfma_f32_16x16x32_bf16 v[30:33], v[134:137], v[196:199], v[30:33]
	v_mfma_f32_16x16x32_bf16 v[14:17], v[130:133], v[200:203], v[14:17]
	v_mfma_f32_16x16x32_bf16 v[14:17], v[134:137], v[204:207], v[14:17]
	v_mfma_f32_16x16x32_bf16 v[58:61], v[138:141], v[176:179], v[58:61]
	v_mfma_f32_16x16x32_bf16 v[58:61], v[142:145], v[180:183], v[58:61]
	v_mfma_f32_16x16x32_bf16 v[42:45], v[138:141], v[184:187], v[42:45]
	v_mfma_f32_16x16x32_bf16 v[42:45], v[142:145], v[188:191], v[42:45]
	v_mfma_f32_16x16x32_bf16 v[26:29], v[138:141], v[192:195], v[26:29]
	v_mfma_f32_16x16x32_bf16 v[26:29], v[142:145], v[196:199], v[26:29]
	v_mfma_f32_16x16x32_bf16 v[10:13], v[138:141], v[200:203], v[10:13]
	v_mfma_f32_16x16x32_bf16 v[10:13], v[142:145], v[204:207], v[10:13]
	v_mfma_f32_16x16x32_bf16 v[54:57], v[154:157], v[176:179], v[54:57]
	v_mfma_f32_16x16x32_bf16 v[54:57], v[164:167], v[180:183], v[54:57]
	v_mfma_f32_16x16x32_bf16 v[38:41], v[154:157], v[184:187], v[38:41]
	v_mfma_f32_16x16x32_bf16 v[38:41], v[164:167], v[188:191], v[38:41]
	v_mfma_f32_16x16x32_bf16 v[22:25], v[154:157], v[192:195], v[22:25]
	v_mfma_f32_16x16x32_bf16 v[22:25], v[164:167], v[196:199], v[22:25]
	v_mfma_f32_16x16x32_bf16 v[6:9], v[154:157], v[200:203], v[6:9]
	v_mfma_f32_16x16x32_bf16 v[6:9], v[164:167], v[204:207], v[6:9]
	v_mfma_f32_16x16x32_bf16 v[50:53], v[168:171], v[176:179], v[50:53]
	v_mfma_f32_16x16x32_bf16 v[50:53], v[172:175], v[180:183], v[50:53]
	v_mfma_f32_16x16x32_bf16 v[34:37], v[168:171], v[184:187], v[34:37]
	v_mfma_f32_16x16x32_bf16 v[34:37], v[172:175], v[188:191], v[34:37]
	v_mfma_f32_16x16x32_bf16 v[18:21], v[168:171], v[192:195], v[18:21]
	v_mfma_f32_16x16x32_bf16 v[18:21], v[172:175], v[196:199], v[18:21]
	v_mfma_f32_16x16x32_bf16 v[2:5], v[168:171], v[200:203], v[2:5]
	v_mfma_f32_16x16x32_bf16 v[2:5], v[172:175], v[204:207], v[2:5]
	s_setprio 0
	s_barrier
	s_add_i32 s89, s89, 2
	s_cmp_ge_i32 s89, s63
	s_mov_b32 s6, s90
	s_cbranch_scc0 .LBB0_1020
	s_and_b64 vcc, exec, s[54:55]
	s_cbranch_vccz .LBB0_1023

.LBB0_1035:
	ds_read_b128 v[140:143], v134
	ds_read_b128 v[148:151], v134 offset:1024
	ds_read_b128 v[152:155], v134 offset:2048
	ds_read_b128 v[156:159], v134 offset:3072
	ds_read_b128 v[160:163], v135
	ds_read_b128 v[164:167], v135 offset:1024
	ds_read_b128 v[168:171], v135 offset:2048
	ds_read_b128 v[172:175], v135 offset:3072
	s_add_i32 s73, s70, 0xfffb8080
	s_cmp_eq_u32 s53, s72
	s_cselect_b32 s73, s68, s73
	s_cselect_b32 s75, s69, s71
	s_add_i32 s74, s73, 0x80
	s_add_i32 s76, s70, 0xfffe8000
	s_mov_b32 m0, s54
	ds_read_b128 v[176:179], v136
	ds_read_b128 v[180:183], v136 offset:1024
	ds_read_b128 v[184:187], v136 offset:2048
	ds_read_b128 v[188:191], v136 offset:3072
	ds_read_b128 v[192:195], v136 offset:4096
	ds_read_b128 v[196:199], v136 offset:5120
	ds_read_b128 v[200:203], v136 offset:6144
	ds_read_b128 v[204:207], v136 offset:7168
	buffer_load_dwordx4 v132, s[12:15], s76 offen lds
	s_mov_b32 m0, s55
	s_nop 0
	buffer_load_dwordx4 v132, s[12:15], s70 offen lds
	s_waitcnt vmcnt(8)
	s_waitcnt lgkmcnt(0)
	s_setprio 1
	v_mfma_f32_16x16x32_bf16 v[126:129], v[140:143], v[176:179], v[126:129]
	s_barrier
	v_mfma_f32_16x16x32_bf16 v[126:129], v[148:151], v[180:183], v[126:129]
	v_mfma_f32_16x16x32_bf16 v[110:113], v[140:143], v[184:187], v[110:113]
	v_mfma_f32_16x16x32_bf16 v[110:113], v[148:151], v[188:191], v[110:113]
	v_mfma_f32_16x16x32_bf16 v[94:97], v[140:143], v[192:195], v[94:97]
	v_mfma_f32_16x16x32_bf16 v[94:97], v[148:151], v[196:199], v[94:97]
	v_mfma_f32_16x16x32_bf16 v[78:81], v[140:143], v[200:203], v[78:81]
	v_mfma_f32_16x16x32_bf16 v[78:81], v[148:151], v[204:207], v[78:81]
	v_mfma_f32_16x16x32_bf16 v[122:125], v[152:155], v[176:179], v[122:125]
	v_mfma_f32_16x16x32_bf16 v[122:125], v[156:159], v[180:183], v[122:125]
	v_mfma_f32_16x16x32_bf16 v[106:109], v[152:155], v[184:187], v[106:109]
	v_mfma_f32_16x16x32_bf16 v[106:109], v[156:159], v[188:191], v[106:109]
	v_mfma_f32_16x16x32_bf16 v[90:93], v[152:155], v[192:195], v[90:93]
	v_mfma_f32_16x16x32_bf16 v[90:93], v[156:159], v[196:199], v[90:93]
	v_mfma_f32_16x16x32_bf16 v[74:77], v[152:155], v[200:203], v[74:77]
	v_mfma_f32_16x16x32_bf16 v[74:77], v[156:159], v[204:207], v[74:77]
	v_mfma_f32_16x16x32_bf16 v[118:121], v[160:163], v[176:179], v[118:121]
	v_mfma_f32_16x16x32_bf16 v[118:121], v[164:167], v[180:183], v[118:121]
	v_mfma_f32_16x16x32_bf16 v[102:105], v[160:163], v[184:187], v[102:105]
	v_mfma_f32_16x16x32_bf16 v[102:105], v[164:167], v[188:191], v[102:105]
	v_mfma_f32_16x16x32_bf16 v[86:89], v[160:163], v[192:195], v[86:89]
	v_mfma_f32_16x16x32_bf16 v[86:89], v[164:167], v[196:199], v[86:89]
	v_mfma_f32_16x16x32_bf16 v[70:73], v[160:163], v[200:203], v[70:73]
	v_mfma_f32_16x16x32_bf16 v[70:73], v[164:167], v[204:207], v[70:73]
	v_mfma_f32_16x16x32_bf16 v[114:117], v[168:171], v[176:179], v[114:117]
	v_mfma_f32_16x16x32_bf16 v[114:117], v[172:175], v[180:183], v[114:117]
	v_mfma_f32_16x16x32_bf16 v[98:101], v[168:171], v[184:187], v[98:101]
	v_mfma_f32_16x16x32_bf16 v[98:101], v[172:175], v[188:191], v[98:101]
	v_mfma_f32_16x16x32_bf16 v[82:85], v[168:171], v[192:195], v[82:85]
	v_mfma_f32_16x16x32_bf16 v[82:85], v[172:175], v[196:199], v[82:85]
	v_mfma_f32_16x16x32_bf16 v[66:69], v[168:171], v[200:203], v[66:69]
	v_mfma_f32_16x16x32_bf16 v[66:69], v[172:175], v[204:207], v[66:69]
	s_setprio 0
	s_barrier
	s_mov_b32 m0, s30
	ds_read_b128 v[176:179], v136 offset:16384
	ds_read_b128 v[180:183], v136 offset:17408
	ds_read_b128 v[184:187], v136 offset:18432
	ds_read_b128 v[188:191], v136 offset:19456
	ds_read_b128 v[192:195], v136 offset:20480
	ds_read_b128 v[196:199], v136 offset:21504
	ds_read_b128 v[200:203], v136 offset:22528
	ds_read_b128 v[204:207], v136 offset:23552
	buffer_load_dwordx4 v133, s[16:19], s75 offen lds
	s_add_i32 s76, s75, 0x200000
	s_mov_b32 m0, s31
	s_nop 0
	buffer_load_dwordx4 v133, s[16:19], s76 offen lds
	s_add_i32 s76, s75, 0x400000
	s_mov_b32 m0, s35
	s_nop 0
	buffer_load_dwordx4 v133, s[16:19], s76 offen lds
	s_add_i32 s76, s75, 0x600000
	s_mov_b32 m0, s42
	s_nop 0
	buffer_load_dwordx4 v133, s[16:19], s76 offen lds
	s_mov_b32 m0, s27
	s_add_i32 s76, s73, 0x18000
	buffer_load_dwordx4 v132, s[12:15], s73 offen lds
	s_mov_b32 m0, s43
	s_nop 0
	buffer_load_dwordx4 v132, s[12:15], s76 offen lds
	s_waitcnt vmcnt(8)
	s_waitcnt lgkmcnt(0)
	s_setprio 1
	v_mfma_f32_16x16x32_bf16 v[62:65], v[140:143], v[176:179], v[62:65]
	s_barrier
	v_mfma_f32_16x16x32_bf16 v[62:65], v[148:151], v[180:183], v[62:65]
	v_mfma_f32_16x16x32_bf16 v[46:49], v[140:143], v[184:187], v[46:49]
	v_mfma_f32_16x16x32_bf16 v[46:49], v[148:151], v[188:191], v[46:49]
	v_mfma_f32_16x16x32_bf16 v[30:33], v[140:143], v[192:195], v[30:33]
	v_mfma_f32_16x16x32_bf16 v[30:33], v[148:151], v[196:199], v[30:33]
	v_mfma_f32_16x16x32_bf16 v[14:17], v[140:143], v[200:203], v[14:17]
	v_mfma_f32_16x16x32_bf16 v[14:17], v[148:151], v[204:207], v[14:17]
	v_mfma_f32_16x16x32_bf16 v[58:61], v[152:155], v[176:179], v[58:61]
	v_mfma_f32_16x16x32_bf16 v[58:61], v[156:159], v[180:183], v[58:61]
	v_mfma_f32_16x16x32_bf16 v[42:45], v[152:155], v[184:187], v[42:45]
	v_mfma_f32_16x16x32_bf16 v[42:45], v[156:159], v[188:191], v[42:45]
	v_mfma_f32_16x16x32_bf16 v[26:29], v[152:155], v[192:195], v[26:29]
	v_mfma_f32_16x16x32_bf16 v[26:29], v[156:159], v[196:199], v[26:29]
	v_mfma_f32_16x16x32_bf16 v[10:13], v[152:155], v[200:203], v[10:13]
	v_mfma_f32_16x16x32_bf16 v[10:13], v[156:159], v[204:207], v[10:13]
	v_mfma_f32_16x16x32_bf16 v[54:57], v[160:163], v[176:179], v[54:57]
	v_mfma_f32_16x16x32_bf16 v[54:57], v[164:167], v[180:183], v[54:57]
	v_mfma_f32_16x16x32_bf16 v[38:41], v[160:163], v[184:187], v[38:41]
	v_mfma_f32_16x16x32_bf16 v[38:41], v[164:167], v[188:191], v[38:41]
	v_mfma_f32_16x16x32_bf16 v[22:25], v[160:163], v[192:195], v[22:25]
	v_mfma_f32_16x16x32_bf16 v[22:25], v[164:167], v[196:199], v[22:25]
	v_mfma_f32_16x16x32_bf16 v[6:9], v[160:163], v[200:203], v[6:9]
	v_mfma_f32_16x16x32_bf16 v[6:9], v[164:167], v[204:207], v[6:9]
	v_mfma_f32_16x16x32_bf16 v[50:53], v[168:171], v[176:179], v[50:53]
	v_mfma_f32_16x16x32_bf16 v[50:53], v[172:175], v[180:183], v[50:53]
	v_mfma_f32_16x16x32_bf16 v[34:37], v[168:171], v[184:187], v[34:37]
	v_mfma_f32_16x16x32_bf16 v[34:37], v[172:175], v[188:191], v[34:37]
	v_mfma_f32_16x16x32_bf16 v[18:21], v[168:171], v[192:195], v[18:21]
	v_mfma_f32_16x16x32_bf16 v[18:21], v[172:175], v[196:199], v[18:21]
	v_mfma_f32_16x16x32_bf16 v[2:5], v[168:171], v[200:203], v[2:5]
	v_mfma_f32_16x16x32_bf16 v[2:5], v[172:175], v[204:207], v[2:5]
	s_setprio 0
	s_barrier
	ds_read_b128 v[140:143], v137
	ds_read_b128 v[148:151], v137 offset:1024
	ds_read_b128 v[152:155], v137 offset:2048
	ds_read_b128 v[156:159], v137 offset:3072
	ds_read_b128 v[160:163], v138
	ds_read_b128 v[164:167], v138 offset:1024
	ds_read_b128 v[168:171], v138 offset:2048
	ds_read_b128 v[172:175], v138 offset:3072
	s_mov_b32 m0, s44
	s_add_i32 s76, s73, 0x30000
	ds_read_b128 v[176:179], v136 offset:32768
	ds_read_b128 v[180:183], v136 offset:33792
	ds_read_b128 v[184:187], v136 offset:34816
	ds_read_b128 v[188:191], v136 offset:35840
	ds_read_b128 v[192:195], v136 offset:36864
	ds_read_b128 v[196:199], v136 offset:37888
	ds_read_b128 v[200:203], v136 offset:38912
	ds_read_b128 v[204:207], v136 offset:39936
	buffer_load_dwordx4 v132, s[12:15], s76 offen lds
	s_add_i32 s76, s73, 0x48000
	s_mov_b32 m0, s45
	s_nop 0
	buffer_load_dwordx4 v132, s[12:15], s76 offen lds
	s_waitcnt vmcnt(8)
	s_waitcnt lgkmcnt(0)
	s_setprio 1
	v_mfma_f32_16x16x32_bf16 v[126:129], v[140:143], v[176:179], v[126:129]
	s_barrier
	v_mfma_f32_16x16x32_bf16 v[126:129], v[148:151], v[180:183], v[126:129]
	v_mfma_f32_16x16x32_bf16 v[110:113], v[140:143], v[184:187], v[110:113]
	v_mfma_f32_16x16x32_bf16 v[110:113], v[148:151], v[188:191], v[110:113]
	v_mfma_f32_16x16x32_bf16 v[94:97], v[140:143], v[192:195], v[94:97]
	v_mfma_f32_16x16x32_bf16 v[94:97], v[148:151], v[196:199], v[94:97]
	v_mfma_f32_16x16x32_bf16 v[78:81], v[140:143], v[200:203], v[78:81]
	v_mfma_f32_16x16x32_bf16 v[78:81], v[148:151], v[204:207], v[78:81]
	v_mfma_f32_16x16x32_bf16 v[122:125], v[152:155], v[176:179], v[122:125]
	v_mfma_f32_16x16x32_bf16 v[122:125], v[156:159], v[180:183], v[122:125]
	v_mfma_f32_16x16x32_bf16 v[106:109], v[152:155], v[184:187], v[106:109]
	v_mfma_f32_16x16x32_bf16 v[106:109], v[156:159], v[188:191], v[106:109]
	v_mfma_f32_16x16x32_bf16 v[90:93], v[152:155], v[192:195], v[90:93]
	v_mfma_f32_16x16x32_bf16 v[90:93], v[156:159], v[196:199], v[90:93]
	v_mfma_f32_16x16x32_bf16 v[74:77], v[152:155], v[200:203], v[74:77]
	v_mfma_f32_16x16x32_bf16 v[74:77], v[156:159], v[204:207], v[74:77]
	v_mfma_f32_16x16x32_bf16 v[118:121], v[160:163], v[176:179], v[118:121]
	v_mfma_f32_16x16x32_bf16 v[118:121], v[164:167], v[180:183], v[118:121]
	v_mfma_f32_16x16x32_bf16 v[102:105], v[160:163], v[184:187], v[102:105]
	v_mfma_f32_16x16x32_bf16 v[102:105], v[164:167], v[188:191], v[102:105]
	v_mfma_f32_16x16x32_bf16 v[86:89], v[160:163], v[192:195], v[86:89]
	v_mfma_f32_16x16x32_bf16 v[86:89], v[164:167], v[196:199], v[86:89]
	v_mfma_f32_16x16x32_bf16 v[70:73], v[160:163], v[200:203], v[70:73]
	v_mfma_f32_16x16x32_bf16 v[70:73], v[164:167], v[204:207], v[70:73]
	v_mfma_f32_16x16x32_bf16 v[114:117], v[168:171], v[176:179], v[114:117]
	v_mfma_f32_16x16x32_bf16 v[114:117], v[172:175], v[180:183], v[114:117]
	v_mfma_f32_16x16x32_bf16 v[98:101], v[168:171], v[184:187], v[98:101]
	v_mfma_f32_16x16x32_bf16 v[98:101], v[172:175], v[188:191], v[98:101]
	v_mfma_f32_16x16x32_bf16 v[82:85], v[168:171], v[192:195], v[82:85]
	v_mfma_f32_16x16x32_bf16 v[82:85], v[172:175], v[196:199], v[82:85]
	v_mfma_f32_16x16x32_bf16 v[66:69], v[168:171], v[200:203], v[66:69]
	v_mfma_f32_16x16x32_bf16 v[66:69], v[172:175], v[204:207], v[66:69]
	s_setprio 0
	s_barrier
	s_mov_b32 m0, s46
	s_add_i32 s76, s75, 0x80
	ds_read_b128 v[176:179], v136 offset:49152
	ds_read_b128 v[180:183], v136 offset:50176
	ds_read_b128 v[184:187], v136 offset:51200
	ds_read_b128 v[188:191], v136 offset:52224
	ds_read_b128 v[192:195], v136 offset:53248
	ds_read_b128 v[196:199], v136 offset:54272
	ds_read_b128 v[200:203], v136 offset:55296
	ds_read_b128 v[204:207], v136 offset:56320
	buffer_load_dwordx4 v133, s[16:19], s76 offen lds
	s_add_i32 s76, s75, 0x200080
	s_mov_b32 m0, s47
	s_add_i32 s73, s73, 0x18080
	buffer_load_dwordx4 v133, s[16:19], s76 offen lds
	s_add_i32 s76, s75, 0x400080
	s_mov_b32 m0, s50
	s_add_i32 s75, s75, 0x600080
	buffer_load_dwordx4 v133, s[16:19], s76 offen lds
	s_mov_b32 m0, s51
	s_nop 0
	buffer_load_dwordx4 v133, s[16:19], s75 offen lds
	s_mov_b32 m0, s48
	s_nop 0
	buffer_load_dwordx4 v132, s[12:15], s74 offen lds
	s_mov_b32 m0, s49
	s_nop 0
	buffer_load_dwordx4 v132, s[12:15], s73 offen lds
	s_waitcnt vmcnt(8)
	s_waitcnt lgkmcnt(0)
	s_setprio 1
	v_mfma_f32_16x16x32_bf16 v[62:65], v[140:143], v[176:179], v[62:65]
	s_barrier
	v_mfma_f32_16x16x32_bf16 v[62:65], v[148:151], v[180:183], v[62:65]
	v_mfma_f32_16x16x32_bf16 v[46:49], v[140:143], v[184:187], v[46:49]
	v_mfma_f32_16x16x32_bf16 v[46:49], v[148:151], v[188:191], v[46:49]
	v_mfma_f32_16x16x32_bf16 v[30:33], v[140:143], v[192:195], v[30:33]
	v_mfma_f32_16x16x32_bf16 v[30:33], v[148:151], v[196:199], v[30:33]
	v_mfma_f32_16x16x32_bf16 v[14:17], v[140:143], v[200:203], v[14:17]
	v_mfma_f32_16x16x32_bf16 v[14:17], v[148:151], v[204:207], v[14:17]
	v_mfma_f32_16x16x32_bf16 v[58:61], v[152:155], v[176:179], v[58:61]
	v_mfma_f32_16x16x32_bf16 v[58:61], v[156:159], v[180:183], v[58:61]
	v_mfma_f32_16x16x32_bf16 v[42:45], v[152:155], v[184:187], v[42:45]
	v_mfma_f32_16x16x32_bf16 v[42:45], v[156:159], v[188:191], v[42:45]
	v_mfma_f32_16x16x32_bf16 v[26:29], v[152:155], v[192:195], v[26:29]
	v_mfma_f32_16x16x32_bf16 v[26:29], v[156:159], v[196:199], v[26:29]
	v_mfma_f32_16x16x32_bf16 v[10:13], v[152:155], v[200:203], v[10:13]
	v_mfma_f32_16x16x32_bf16 v[10:13], v[156:159], v[204:207], v[10:13]
	v_mfma_f32_16x16x32_bf16 v[54:57], v[160:163], v[176:179], v[54:57]
	v_mfma_f32_16x16x32_bf16 v[54:57], v[164:167], v[180:183], v[54:57]
	v_mfma_f32_16x16x32_bf16 v[38:41], v[160:163], v[184:187], v[38:41]
	v_mfma_f32_16x16x32_bf16 v[38:41], v[164:167], v[188:191], v[38:41]
	v_mfma_f32_16x16x32_bf16 v[22:25], v[160:163], v[192:195], v[22:25]
	v_mfma_f32_16x16x32_bf16 v[22:25], v[164:167], v[196:199], v[22:25]
	v_mfma_f32_16x16x32_bf16 v[6:9], v[160:163], v[200:203], v[6:9]
	v_mfma_f32_16x16x32_bf16 v[6:9], v[164:167], v[204:207], v[6:9]
	v_mfma_f32_16x16x32_bf16 v[50:53], v[168:171], v[176:179], v[50:53]
	v_mfma_f32_16x16x32_bf16 v[50:53], v[172:175], v[180:183], v[50:53]
	v_mfma_f32_16x16x32_bf16 v[34:37], v[168:171], v[184:187], v[34:37]
	v_mfma_f32_16x16x32_bf16 v[34:37], v[172:175], v[188:191], v[34:37]
	v_mfma_f32_16x16x32_bf16 v[18:21], v[168:171], v[192:195], v[18:21]
	v_mfma_f32_16x16x32_bf16 v[18:21], v[172:175], v[196:199], v[18:21]
	v_mfma_f32_16x16x32_bf16 v[2:5], v[168:171], v[200:203], v[2:5]
	v_mfma_f32_16x16x32_bf16 v[2:5], v[172:175], v[204:207], v[2:5]
	s_setprio 0
	s_barrier
	s_add_i32 s72, s72, 2
	s_addk_i32 s70, 0x100
	s_addk_i32 s71, 0x100
	s_cmp_ge_i32 s72, s21
	s_cbranch_scc0 .LBB0_1035

.LBB0_1050:
	ds_read_b128 v[132:135], v142
	ds_read_b128 v[136:139], v142 offset:1024
	ds_read_b128 v[148:151], v142 offset:2048
	ds_read_b128 v[152:155], v142 offset:3072
	ds_read_b128 v[156:159], v143
	ds_read_b128 v[160:163], v143 offset:1024
	ds_read_b128 v[164:167], v143 offset:2048
	ds_read_b128 v[168:171], v143 offset:3072
	s_add_i32 s18, s61, 0xfff40080
	s_cmp_eq_u32 s54, s62
	s_cselect_b32 s64, s35, s18
	s_add_i32 s63, s64, 0x80
	s_add_i32 s18, s61, 0xfffc0000
	s_mov_b32 m0, s55
	ds_read_b128 v[172:175], v144
	ds_read_b128 v[176:179], v144 offset:1024
	ds_read_b128 v[180:183], v144 offset:2048
	ds_read_b128 v[184:187], v144 offset:3072
	ds_read_b128 v[188:191], v144 offset:4096
	ds_read_b128 v[192:195], v144 offset:5120
	ds_read_b128 v[196:199], v144 offset:6144
	ds_read_b128 v[200:203], v144 offset:7168
	buffer_load_dwordx4 v140, s[12:15], s18 offen lds
	s_mov_b32 m0, s56
	s_nop 0
	buffer_load_dwordx4 v140, s[12:15], s61 offen lds
	s_waitcnt vmcnt(8)
	s_waitcnt lgkmcnt(0)
	s_setprio 1
	v_mfma_f32_16x16x32_bf16 v[126:129], v[132:135], v[172:175], v[126:129]
	s_barrier
	v_mfma_f32_16x16x32_bf16 v[126:129], v[136:139], v[176:179], v[126:129]
	v_mfma_f32_16x16x32_bf16 v[110:113], v[132:135], v[180:183], v[110:113]
	v_mfma_f32_16x16x32_bf16 v[110:113], v[136:139], v[184:187], v[110:113]
	v_mfma_f32_16x16x32_bf16 v[94:97], v[132:135], v[188:191], v[94:97]
	v_mfma_f32_16x16x32_bf16 v[94:97], v[136:139], v[192:195], v[94:97]
	v_mfma_f32_16x16x32_bf16 v[78:81], v[132:135], v[196:199], v[78:81]
	v_mfma_f32_16x16x32_bf16 v[78:81], v[136:139], v[200:203], v[78:81]
	v_mfma_f32_16x16x32_bf16 v[122:125], v[148:151], v[172:175], v[122:125]
	v_mfma_f32_16x16x32_bf16 v[122:125], v[152:155], v[176:179], v[122:125]
	v_mfma_f32_16x16x32_bf16 v[106:109], v[148:151], v[180:183], v[106:109]
	v_mfma_f32_16x16x32_bf16 v[106:109], v[152:155], v[184:187], v[106:109]
	v_mfma_f32_16x16x32_bf16 v[90:93], v[148:151], v[188:191], v[90:93]
	v_mfma_f32_16x16x32_bf16 v[90:93], v[152:155], v[192:195], v[90:93]
	v_mfma_f32_16x16x32_bf16 v[74:77], v[148:151], v[196:199], v[74:77]
	v_mfma_f32_16x16x32_bf16 v[74:77], v[152:155], v[200:203], v[74:77]
	v_mfma_f32_16x16x32_bf16 v[118:121], v[156:159], v[172:175], v[118:121]
	v_mfma_f32_16x16x32_bf16 v[118:121], v[160:163], v[176:179], v[118:121]
	v_mfma_f32_16x16x32_bf16 v[102:105], v[156:159], v[180:183], v[102:105]
	v_mfma_f32_16x16x32_bf16 v[102:105], v[160:163], v[184:187], v[102:105]
	v_mfma_f32_16x16x32_bf16 v[86:89], v[156:159], v[188:191], v[86:89]
	v_mfma_f32_16x16x32_bf16 v[86:89], v[160:163], v[192:195], v[86:89]
	v_mfma_f32_16x16x32_bf16 v[70:73], v[156:159], v[196:199], v[70:73]
	v_mfma_f32_16x16x32_bf16 v[70:73], v[160:163], v[200:203], v[70:73]
	v_mfma_f32_16x16x32_bf16 v[114:117], v[164:167], v[172:175], v[114:117]
	v_mfma_f32_16x16x32_bf16 v[114:117], v[168:171], v[176:179], v[114:117]
	v_mfma_f32_16x16x32_bf16 v[98:101], v[164:167], v[180:183], v[98:101]
	v_mfma_f32_16x16x32_bf16 v[98:101], v[168:171], v[184:187], v[98:101]
	v_mfma_f32_16x16x32_bf16 v[82:85], v[164:167], v[188:191], v[82:85]
	v_mfma_f32_16x16x32_bf16 v[82:85], v[168:171], v[192:195], v[82:85]
	v_mfma_f32_16x16x32_bf16 v[66:69], v[164:167], v[196:199], v[66:69]
	v_mfma_f32_16x16x32_bf16 v[66:69], v[168:171], v[200:203], v[66:69]
	s_setprio 0
	s_barrier
	s_mov_b32 m0, s25
	s_mov_b32 s18, s14
	s_mov_b32 s19, s15
	ds_read_b128 v[172:175], v144 offset:16384
	ds_read_b128 v[176:179], v144 offset:17408
	ds_read_b128 v[180:183], v144 offset:18432
	ds_read_b128 v[184:187], v144 offset:19456
	ds_read_b128 v[188:191], v144 offset:20480
	ds_read_b128 v[192:195], v144 offset:21504
	ds_read_b128 v[196:199], v144 offset:22528
	ds_read_b128 v[200:203], v144 offset:23552
	buffer_load_dwordx4 v141, s[16:19], s64 offen lds
	s_add_i32 s65, s64, 0x40000
	s_mov_b32 m0, s27
	s_add_i32 s66, s64, 0x80000
	buffer_load_dwordx4 v141, s[16:19], s65 offen lds
	s_mov_b32 m0, s30
	s_add_i32 s67, s64, 0xc0000
	buffer_load_dwordx4 v141, s[16:19], s66 offen lds
	s_mov_b32 m0, s31
	s_nop 0
	buffer_load_dwordx4 v141, s[16:19], s67 offen lds
	s_mov_b32 m0, s21
	s_nop 0
	buffer_load_dwordx4 v140, s[12:15], s64 offen lds
	s_mov_b32 m0, s38
	s_nop 0
	buffer_load_dwordx4 v140, s[12:15], s65 offen lds
	s_waitcnt vmcnt(8)
	s_waitcnt lgkmcnt(0)
	s_setprio 1
	v_mfma_f32_16x16x32_bf16 v[62:65], v[132:135], v[172:175], v[62:65]
	s_barrier
	v_mfma_f32_16x16x32_bf16 v[62:65], v[136:139], v[176:179], v[62:65]
	v_mfma_f32_16x16x32_bf16 v[46:49], v[132:135], v[180:183], v[46:49]
	v_mfma_f32_16x16x32_bf16 v[46:49], v[136:139], v[184:187], v[46:49]
	v_mfma_f32_16x16x32_bf16 v[30:33], v[132:135], v[188:191], v[30:33]
	v_mfma_f32_16x16x32_bf16 v[30:33], v[136:139], v[192:195], v[30:33]
	v_mfma_f32_16x16x32_bf16 v[14:17], v[132:135], v[196:199], v[14:17]
	v_mfma_f32_16x16x32_bf16 v[14:17], v[136:139], v[200:203], v[14:17]
	v_mfma_f32_16x16x32_bf16 v[58:61], v[148:151], v[172:175], v[58:61]
	v_mfma_f32_16x16x32_bf16 v[58:61], v[152:155], v[176:179], v[58:61]
	v_mfma_f32_16x16x32_bf16 v[42:45], v[148:151], v[180:183], v[42:45]
	v_mfma_f32_16x16x32_bf16 v[42:45], v[152:155], v[184:187], v[42:45]
	v_mfma_f32_16x16x32_bf16 v[26:29], v[148:151], v[188:191], v[26:29]
	v_mfma_f32_16x16x32_bf16 v[26:29], v[152:155], v[192:195], v[26:29]
	v_mfma_f32_16x16x32_bf16 v[10:13], v[148:151], v[196:199], v[10:13]
	v_mfma_f32_16x16x32_bf16 v[10:13], v[152:155], v[200:203], v[10:13]
	v_mfma_f32_16x16x32_bf16 v[54:57], v[156:159], v[172:175], v[54:57]
	v_mfma_f32_16x16x32_bf16 v[54:57], v[160:163], v[176:179], v[54:57]
	v_mfma_f32_16x16x32_bf16 v[38:41], v[156:159], v[180:183], v[38:41]
	v_mfma_f32_16x16x32_bf16 v[38:41], v[160:163], v[184:187], v[38:41]
	v_mfma_f32_16x16x32_bf16 v[22:25], v[156:159], v[188:191], v[22:25]
	v_mfma_f32_16x16x32_bf16 v[22:25], v[160:163], v[192:195], v[22:25]
	v_mfma_f32_16x16x32_bf16 v[6:9], v[156:159], v[196:199], v[6:9]
	v_mfma_f32_16x16x32_bf16 v[6:9], v[160:163], v[200:203], v[6:9]
	v_mfma_f32_16x16x32_bf16 v[50:53], v[164:167], v[172:175], v[50:53]
	v_mfma_f32_16x16x32_bf16 v[50:53], v[168:171], v[176:179], v[50:53]
	v_mfma_f32_16x16x32_bf16 v[34:37], v[164:167], v[180:183], v[34:37]
	v_mfma_f32_16x16x32_bf16 v[34:37], v[168:171], v[184:187], v[34:37]
	v_mfma_f32_16x16x32_bf16 v[18:21], v[164:167], v[188:191], v[18:21]
	v_mfma_f32_16x16x32_bf16 v[18:21], v[168:171], v[192:195], v[18:21]
	v_mfma_f32_16x16x32_bf16 v[2:5], v[164:167], v[196:199], v[2:5]
	v_mfma_f32_16x16x32_bf16 v[2:5], v[168:171], v[200:203], v[2:5]
	s_setprio 0
	s_barrier
	ds_read_b128 v[132:135], v145
	ds_read_b128 v[136:139], v145 offset:1024
	ds_read_b128 v[148:151], v145 offset:2048
	ds_read_b128 v[152:155], v145 offset:3072
	ds_read_b128 v[156:159], v147
	ds_read_b128 v[160:163], v147 offset:1024
	ds_read_b128 v[164:167], v147 offset:2048
	ds_read_b128 v[168:171], v147 offset:3072
	s_mov_b32 m0, s39
	ds_read_b128 v[172:175], v144 offset:32768
	ds_read_b128 v[176:179], v144 offset:33792
	ds_read_b128 v[180:183], v144 offset:34816
	ds_read_b128 v[184:187], v144 offset:35840
	ds_read_b128 v[188:191], v144 offset:36864
	ds_read_b128 v[192:195], v144 offset:37888
	ds_read_b128 v[196:199], v144 offset:38912
	ds_read_b128 v[200:203], v144 offset:39936
	buffer_load_dwordx4 v140, s[12:15], s66 offen lds
	s_mov_b32 m0, s40
	s_nop 0
	buffer_load_dwordx4 v140, s[12:15], s67 offen lds
	s_waitcnt vmcnt(8)
	s_waitcnt lgkmcnt(0)
	s_setprio 1
	v_mfma_f32_16x16x32_bf16 v[126:129], v[132:135], v[172:175], v[126:129]
	s_barrier
	v_mfma_f32_16x16x32_bf16 v[126:129], v[136:139], v[176:179], v[126:129]
	v_mfma_f32_16x16x32_bf16 v[110:113], v[132:135], v[180:183], v[110:113]
	v_mfma_f32_16x16x32_bf16 v[110:113], v[136:139], v[184:187], v[110:113]
	v_mfma_f32_16x16x32_bf16 v[94:97], v[132:135], v[188:191], v[94:97]
	v_mfma_f32_16x16x32_bf16 v[94:97], v[136:139], v[192:195], v[94:97]
	v_mfma_f32_16x16x32_bf16 v[78:81], v[132:135], v[196:199], v[78:81]
	v_mfma_f32_16x16x32_bf16 v[78:81], v[136:139], v[200:203], v[78:81]
	v_mfma_f32_16x16x32_bf16 v[122:125], v[148:151], v[172:175], v[122:125]
	v_mfma_f32_16x16x32_bf16 v[122:125], v[152:155], v[176:179], v[122:125]
	v_mfma_f32_16x16x32_bf16 v[106:109], v[148:151], v[180:183], v[106:109]
	v_mfma_f32_16x16x32_bf16 v[106:109], v[152:155], v[184:187], v[106:109]
	v_mfma_f32_16x16x32_bf16 v[90:93], v[148:151], v[188:191], v[90:93]
	v_mfma_f32_16x16x32_bf16 v[90:93], v[152:155], v[192:195], v[90:93]
	v_mfma_f32_16x16x32_bf16 v[74:77], v[148:151], v[196:199], v[74:77]
	v_mfma_f32_16x16x32_bf16 v[74:77], v[152:155], v[200:203], v[74:77]
	v_mfma_f32_16x16x32_bf16 v[118:121], v[156:159], v[172:175], v[118:121]
	v_mfma_f32_16x16x32_bf16 v[118:121], v[160:163], v[176:179], v[118:121]
	v_mfma_f32_16x16x32_bf16 v[102:105], v[156:159], v[180:183], v[102:105]
	v_mfma_f32_16x16x32_bf16 v[102:105], v[160:163], v[184:187], v[102:105]
	v_mfma_f32_16x16x32_bf16 v[86:89], v[156:159], v[188:191], v[86:89]
	v_mfma_f32_16x16x32_bf16 v[86:89], v[160:163], v[192:195], v[86:89]
	v_mfma_f32_16x16x32_bf16 v[70:73], v[156:159], v[196:199], v[70:73]
	v_mfma_f32_16x16x32_bf16 v[70:73], v[160:163], v[200:203], v[70:73]
	v_mfma_f32_16x16x32_bf16 v[114:117], v[164:167], v[172:175], v[114:117]
	v_mfma_f32_16x16x32_bf16 v[114:117], v[168:171], v[176:179], v[114:117]
	v_mfma_f32_16x16x32_bf16 v[98:101], v[164:167], v[180:183], v[98:101]
	v_mfma_f32_16x16x32_bf16 v[98:101], v[168:171], v[184:187], v[98:101]
	v_mfma_f32_16x16x32_bf16 v[82:85], v[164:167], v[188:191], v[82:85]
	v_mfma_f32_16x16x32_bf16 v[82:85], v[168:171], v[192:195], v[82:85]
	v_mfma_f32_16x16x32_bf16 v[66:69], v[164:167], v[196:199], v[66:69]
	v_mfma_f32_16x16x32_bf16 v[66:69], v[168:171], v[200:203], v[66:69]
	s_setprio 0
	s_barrier
	s_mov_b32 m0, s48
	ds_read_b128 v[172:175], v144 offset:49152
	ds_read_b128 v[176:179], v144 offset:50176
	ds_read_b128 v[180:183], v144 offset:51200
	ds_read_b128 v[184:187], v144 offset:52224
	ds_read_b128 v[188:191], v144 offset:53248
	ds_read_b128 v[192:195], v144 offset:54272
	ds_read_b128 v[196:199], v144 offset:55296
	ds_read_b128 v[200:203], v144 offset:56320
	buffer_load_dwordx4 v141, s[16:19], s63 offen lds
	s_add_i32 s65, s64, 0x40080
	s_mov_b32 m0, s49
	s_add_i32 s66, s64, 0x80080
	buffer_load_dwordx4 v141, s[16:19], s65 offen lds
	s_mov_b32 m0, s52
	s_add_i32 s64, s64, 0xc0080
	buffer_load_dwordx4 v141, s[16:19], s66 offen lds
	s_mov_b32 m0, s53
	s_nop 0
	buffer_load_dwordx4 v141, s[16:19], s64 offen lds
	s_mov_b32 m0, s50
	s_nop 0
	buffer_load_dwordx4 v140, s[12:15], s63 offen lds
	s_mov_b32 m0, s51
	s_nop 0
	buffer_load_dwordx4 v140, s[12:15], s65 offen lds
	s_waitcnt vmcnt(8)
	s_waitcnt lgkmcnt(0)
	s_setprio 1
	v_mfma_f32_16x16x32_bf16 v[62:65], v[132:135], v[172:175], v[62:65]
	s_barrier
	v_mfma_f32_16x16x32_bf16 v[62:65], v[136:139], v[176:179], v[62:65]
	v_mfma_f32_16x16x32_bf16 v[46:49], v[132:135], v[180:183], v[46:49]
	v_mfma_f32_16x16x32_bf16 v[46:49], v[136:139], v[184:187], v[46:49]
	v_mfma_f32_16x16x32_bf16 v[30:33], v[132:135], v[188:191], v[30:33]
	v_mfma_f32_16x16x32_bf16 v[30:33], v[136:139], v[192:195], v[30:33]
	v_mfma_f32_16x16x32_bf16 v[14:17], v[132:135], v[196:199], v[14:17]
	v_mfma_f32_16x16x32_bf16 v[14:17], v[136:139], v[200:203], v[14:17]
	v_mfma_f32_16x16x32_bf16 v[58:61], v[148:151], v[172:175], v[58:61]
	v_mfma_f32_16x16x32_bf16 v[58:61], v[152:155], v[176:179], v[58:61]
	v_mfma_f32_16x16x32_bf16 v[42:45], v[148:151], v[180:183], v[42:45]
	v_mfma_f32_16x16x32_bf16 v[42:45], v[152:155], v[184:187], v[42:45]
	v_mfma_f32_16x16x32_bf16 v[26:29], v[148:151], v[188:191], v[26:29]
	v_mfma_f32_16x16x32_bf16 v[26:29], v[152:155], v[192:195], v[26:29]
	v_mfma_f32_16x16x32_bf16 v[10:13], v[148:151], v[196:199], v[10:13]
	v_mfma_f32_16x16x32_bf16 v[10:13], v[152:155], v[200:203], v[10:13]
	v_mfma_f32_16x16x32_bf16 v[54:57], v[156:159], v[172:175], v[54:57]
	v_mfma_f32_16x16x32_bf16 v[54:57], v[160:163], v[176:179], v[54:57]
	v_mfma_f32_16x16x32_bf16 v[38:41], v[156:159], v[180:183], v[38:41]
	v_mfma_f32_16x16x32_bf16 v[38:41], v[160:163], v[184:187], v[38:41]
	v_mfma_f32_16x16x32_bf16 v[22:25], v[156:159], v[188:191], v[22:25]
	v_mfma_f32_16x16x32_bf16 v[22:25], v[160:163], v[192:195], v[22:25]
	v_mfma_f32_16x16x32_bf16 v[6:9], v[156:159], v[196:199], v[6:9]
	v_mfma_f32_16x16x32_bf16 v[6:9], v[160:163], v[200:203], v[6:9]
	v_mfma_f32_16x16x32_bf16 v[50:53], v[164:167], v[172:175], v[50:53]
	v_mfma_f32_16x16x32_bf16 v[50:53], v[168:171], v[176:179], v[50:53]
	v_mfma_f32_16x16x32_bf16 v[34:37], v[164:167], v[180:183], v[34:37]
	v_mfma_f32_16x16x32_bf16 v[34:37], v[168:171], v[184:187], v[34:37]
	v_mfma_f32_16x16x32_bf16 v[18:21], v[164:167], v[188:191], v[18:21]
	v_mfma_f32_16x16x32_bf16 v[18:21], v[168:171], v[192:195], v[18:21]
	v_mfma_f32_16x16x32_bf16 v[2:5], v[164:167], v[196:199], v[2:5]
	v_mfma_f32_16x16x32_bf16 v[2:5], v[168:171], v[200:203], v[2:5]
	s_setprio 0
	s_barrier
	s_add_i32 s62, s62, 2
	s_addk_i32 s61, 0x100
	s_cmp_ge_i32 s62, s3
	s_cbranch_scc0 .LBB0_1050

.LBB0_1181:
	v_add_u32_e32 v2, 0x10000, v232
	ds_read_b128 v[134:137], v2
	ds_read_b128 v[138:141], v2 offset:1024
	ds_read_b128 v[142:145], v2 offset:2048
	ds_read_b128 v[146:149], v2 offset:3072
	v_add_u32_e32 v2, 0x14000, v232
	ds_read_b128 v[150:153], v2
	ds_read_b128 v[154:157], v2 offset:1024
	ds_read_b128 v[158:161], v2 offset:2048
	ds_read_b128 v[162:165], v2 offset:3072
	s_add_i32 s50, s47, s90
	s_and_b64 s[18:19], exec, s[18:19]
	s_cselect_b32 s51, s88, s50
	s_add_i32 s50, s92, 0x80
	s_or_b32 s52, s51, 0x80
	s_add_i32 s18, s89, s93
	s_add_i32 s94, s94, 0x1bfffc80
	s_cmp_lt_u32 s91, 8
	s_cselect_b32 s18, s18, s94
	s_mov_b32 m0, s74
	s_add_i32 s19, s18, 0x80000
	ds_read_b128 v[166:169], v233
	ds_read_b128 v[170:173], v233 offset:1024
	ds_read_b128 v[174:177], v233 offset:2048
	ds_read_b128 v[178:181], v233 offset:3072
	ds_read_b128 v[182:185], v233 offset:4096
	ds_read_b128 v[186:189], v233 offset:5120
	ds_read_b128 v[190:193], v233 offset:6144
	ds_read_b128 v[194:197], v233 offset:7168
	buffer_load_dwordx4 v230, s[12:15], s19 offen lds
	s_add_i32 s18, s18, 0xc0000
	s_mov_b32 m0, s75
	s_nop 0
	buffer_load_dwordx4 v230, s[12:15], s18 offen lds
	s_waitcnt vmcnt(8)
	s_waitcnt lgkmcnt(0)
	s_setprio 1
	v_mfma_f32_16x16x32_bf16 v[130:133], v[134:137], v[166:169], v[130:133]
	s_barrier
	v_mfma_f32_16x16x32_bf16 v[130:133], v[138:141], v[170:173], v[130:133]
	v_mfma_f32_16x16x32_bf16 v[114:117], v[134:137], v[174:177], v[114:117]
	v_mfma_f32_16x16x32_bf16 v[114:117], v[138:141], v[178:181], v[114:117]
	v_mfma_f32_16x16x32_bf16 v[98:101], v[134:137], v[182:185], v[98:101]
	v_mfma_f32_16x16x32_bf16 v[98:101], v[138:141], v[186:189], v[98:101]
	v_mfma_f32_16x16x32_bf16 v[82:85], v[134:137], v[190:193], v[82:85]
	v_mfma_f32_16x16x32_bf16 v[82:85], v[138:141], v[194:197], v[82:85]
	v_mfma_f32_16x16x32_bf16 v[126:129], v[142:145], v[166:169], v[126:129]
	v_mfma_f32_16x16x32_bf16 v[126:129], v[146:149], v[170:173], v[126:129]
	v_mfma_f32_16x16x32_bf16 v[110:113], v[142:145], v[174:177], v[110:113]
	v_mfma_f32_16x16x32_bf16 v[110:113], v[146:149], v[178:181], v[110:113]
	v_mfma_f32_16x16x32_bf16 v[94:97], v[142:145], v[182:185], v[94:97]
	v_mfma_f32_16x16x32_bf16 v[94:97], v[146:149], v[186:189], v[94:97]
	v_mfma_f32_16x16x32_bf16 v[78:81], v[142:145], v[190:193], v[78:81]
	v_mfma_f32_16x16x32_bf16 v[78:81], v[146:149], v[194:197], v[78:81]
	v_mfma_f32_16x16x32_bf16 v[122:125], v[150:153], v[166:169], v[122:125]
	v_mfma_f32_16x16x32_bf16 v[122:125], v[154:157], v[170:173], v[122:125]
	v_mfma_f32_16x16x32_bf16 v[106:109], v[150:153], v[174:177], v[106:109]
	v_mfma_f32_16x16x32_bf16 v[106:109], v[154:157], v[178:181], v[106:109]
	v_mfma_f32_16x16x32_bf16 v[90:93], v[150:153], v[182:185], v[90:93]
	v_mfma_f32_16x16x32_bf16 v[90:93], v[154:157], v[186:189], v[90:93]
	v_mfma_f32_16x16x32_bf16 v[74:77], v[150:153], v[190:193], v[74:77]
	v_mfma_f32_16x16x32_bf16 v[74:77], v[154:157], v[194:197], v[74:77]
	v_mfma_f32_16x16x32_bf16 v[118:121], v[158:161], v[166:169], v[118:121]
	v_mfma_f32_16x16x32_bf16 v[118:121], v[162:165], v[170:173], v[118:121]
	v_mfma_f32_16x16x32_bf16 v[102:105], v[158:161], v[174:177], v[102:105]
	v_mfma_f32_16x16x32_bf16 v[102:105], v[162:165], v[178:181], v[102:105]
	v_mfma_f32_16x16x32_bf16 v[86:89], v[158:161], v[182:185], v[86:89]
	v_mfma_f32_16x16x32_bf16 v[86:89], v[162:165], v[186:189], v[86:89]
	v_mfma_f32_16x16x32_bf16 v[70:73], v[158:161], v[190:193], v[70:73]
	v_mfma_f32_16x16x32_bf16 v[70:73], v[162:165], v[194:197], v[70:73]
	s_setprio 0
	s_barrier
	s_mov_b32 m0, s27
	s_mov_b32 s18, s14
	s_mov_b32 s19, s15
	ds_read_b128 v[166:169], v233 offset:16384
	ds_read_b128 v[170:173], v233 offset:17408
	ds_read_b128 v[174:177], v233 offset:18432
	ds_read_b128 v[178:181], v233 offset:19456
	ds_read_b128 v[182:185], v233 offset:20480
	ds_read_b128 v[186:189], v233 offset:21504
	ds_read_b128 v[190:193], v233 offset:22528
	ds_read_b128 v[194:197], v233 offset:23552
	buffer_load_dwordx4 v231, s[16:19], s51 offen lds
	s_add_i32 s53, s51, 0x18000
	s_mov_b32 m0, s30
	s_nop 0
	buffer_load_dwordx4 v231, s[16:19], s53 offen lds
	s_add_i32 s53, s51, 0x30000
	s_mov_b32 m0, s31
	s_nop 0
	buffer_load_dwordx4 v231, s[16:19], s53 offen lds
	s_add_i32 s53, s51, 0x48000
	s_mov_b32 m0, s54
	s_nop 0
	buffer_load_dwordx4 v231, s[16:19], s53 offen lds
	s_mov_b32 m0, s25
	s_add_i32 s53, s92, 0x40000
	buffer_load_dwordx4 v230, s[12:15], s92 offen lds
	s_mov_b32 m0, s55
	s_nop 0
	buffer_load_dwordx4 v230, s[12:15], s53 offen lds
	s_waitcnt vmcnt(8)
	s_waitcnt lgkmcnt(0)
	s_setprio 1
	v_mfma_f32_16x16x32_bf16 v[66:69], v[134:137], v[166:169], v[66:69]
	s_barrier
	v_mfma_f32_16x16x32_bf16 v[62:65], v[142:145], v[166:169], v[62:65]
	v_mfma_f32_16x16x32_bf16 v[50:53], v[134:137], v[174:177], v[50:53]
	v_mfma_f32_16x16x32_bf16 v[46:49], v[142:145], v[174:177], v[46:49]
	v_mfma_f32_16x16x32_bf16 v[34:37], v[134:137], v[182:185], v[34:37]
	v_mfma_f32_16x16x32_bf16 v[30:33], v[142:145], v[182:185], v[30:33]
	v_mfma_f32_16x16x32_bf16 v[18:21], v[134:137], v[190:193], v[18:21]
	v_mfma_f32_16x16x32_bf16 v[14:17], v[142:145], v[190:193], v[14:17]
	v_mfma_f32_16x16x32_bf16 v[58:61], v[150:153], v[166:169], v[58:61]
	v_mfma_f32_16x16x32_bf16 v[54:57], v[158:161], v[166:169], v[54:57]
	v_mfma_f32_16x16x32_bf16 v[42:45], v[150:153], v[174:177], v[42:45]
	v_mfma_f32_16x16x32_bf16 v[38:41], v[158:161], v[174:177], v[38:41]
	v_mfma_f32_16x16x32_bf16 v[26:29], v[150:153], v[182:185], v[26:29]
	v_mfma_f32_16x16x32_bf16 v[22:25], v[158:161], v[182:185], v[22:25]
	v_mfma_f32_16x16x32_bf16 v[10:13], v[150:153], v[190:193], v[10:13]
	v_mfma_f32_16x16x32_bf16 v[4:7], v[158:161], v[190:193], v[6:9]
	v_mfma_f32_16x16x32_bf16 v[66:69], v[138:141], v[170:173], v[66:69]
	v_mfma_f32_16x16x32_bf16 v[62:65], v[146:149], v[170:173], v[62:65]
	v_mfma_f32_16x16x32_bf16 v[50:53], v[138:141], v[178:181], v[50:53]
	v_mfma_f32_16x16x32_bf16 v[46:49], v[146:149], v[178:181], v[46:49]
	v_mfma_f32_16x16x32_bf16 v[34:37], v[138:141], v[186:189], v[34:37]
	v_mfma_f32_16x16x32_bf16 v[30:33], v[146:149], v[186:189], v[30:33]
	v_mfma_f32_16x16x32_bf16 v[18:21], v[138:141], v[194:197], v[18:21]
	v_mfma_f32_16x16x32_bf16 v[14:17], v[146:149], v[194:197], v[14:17]
	v_mfma_f32_16x16x32_bf16 v[58:61], v[154:157], v[170:173], v[58:61]
	v_mfma_f32_16x16x32_bf16 v[54:57], v[162:165], v[170:173], v[54:57]
	v_mfma_f32_16x16x32_bf16 v[42:45], v[154:157], v[178:181], v[42:45]
	v_mfma_f32_16x16x32_bf16 v[38:41], v[162:165], v[178:181], v[38:41]
	v_mfma_f32_16x16x32_bf16 v[26:29], v[154:157], v[186:189], v[26:29]
	v_mfma_f32_16x16x32_bf16 v[22:25], v[162:165], v[186:189], v[22:25]
	v_mfma_f32_16x16x32_bf16 v[10:13], v[154:157], v[194:197], v[10:13]
	v_mfma_f32_16x16x32_bf16 v[4:7], v[162:165], v[194:197], v[4:7]
	s_setprio 0
	s_barrier
	v_add_u32_e32 v2, 0x18000, v232
	ds_read_b128 v[134:137], v2
	ds_read_b128 v[138:141], v2 offset:1024
	ds_read_b128 v[142:145], v2 offset:2048
	ds_read_b128 v[146:149], v2 offset:3072
	v_add_u32_e32 v2, 0x1c000, v232
	ds_read_b128 v[150:153], v2
	ds_read_b128 v[154:157], v2 offset:1024
	ds_read_b128 v[158:161], v2 offset:2048
	ds_read_b128 v[162:165], v2 offset:3072
	s_mov_b32 m0, s56
	s_add_i32 s53, s92, 0x80000
	ds_read_b128 v[166:169], v233 offset:32768
	ds_read_b128 v[170:173], v233 offset:33792
	ds_read_b128 v[174:177], v233 offset:34816
	ds_read_b128 v[178:181], v233 offset:35840
	ds_read_b128 v[182:185], v233 offset:36864
	ds_read_b128 v[186:189], v233 offset:37888
	ds_read_b128 v[190:193], v233 offset:38912
	ds_read_b128 v[194:197], v233 offset:39936
	buffer_load_dwordx4 v230, s[12:15], s53 offen lds
	s_add_i32 s53, s92, 0xc0000
	s_mov_b32 m0, s57
	s_nop 0
	buffer_load_dwordx4 v230, s[12:15], s53 offen lds
	s_waitcnt vmcnt(8)
	s_waitcnt lgkmcnt(0)
	s_setprio 1
	v_mfma_f32_16x16x32_bf16 v[130:133], v[134:137], v[166:169], v[130:133]
	s_barrier
	v_mfma_f32_16x16x32_bf16 v[130:133], v[138:141], v[170:173], v[130:133]
	v_mfma_f32_16x16x32_bf16 v[114:117], v[134:137], v[174:177], v[114:117]
	v_mfma_f32_16x16x32_bf16 v[114:117], v[138:141], v[178:181], v[114:117]
	v_mfma_f32_16x16x32_bf16 v[98:101], v[134:137], v[182:185], v[98:101]
	v_mfma_f32_16x16x32_bf16 v[98:101], v[138:141], v[186:189], v[98:101]
	v_mfma_f32_16x16x32_bf16 v[82:85], v[134:137], v[190:193], v[82:85]
	v_mfma_f32_16x16x32_bf16 v[82:85], v[138:141], v[194:197], v[82:85]
	v_mfma_f32_16x16x32_bf16 v[126:129], v[142:145], v[166:169], v[126:129]
	v_mfma_f32_16x16x32_bf16 v[126:129], v[146:149], v[170:173], v[126:129]
	v_mfma_f32_16x16x32_bf16 v[110:113], v[142:145], v[174:177], v[110:113]
	v_mfma_f32_16x16x32_bf16 v[110:113], v[146:149], v[178:181], v[110:113]
	v_mfma_f32_16x16x32_bf16 v[94:97], v[142:145], v[182:185], v[94:97]
	v_mfma_f32_16x16x32_bf16 v[94:97], v[146:149], v[186:189], v[94:97]
	v_mfma_f32_16x16x32_bf16 v[78:81], v[142:145], v[190:193], v[78:81]
	v_mfma_f32_16x16x32_bf16 v[78:81], v[146:149], v[194:197], v[78:81]
	v_mfma_f32_16x16x32_bf16 v[122:125], v[150:153], v[166:169], v[122:125]
	v_mfma_f32_16x16x32_bf16 v[122:125], v[154:157], v[170:173], v[122:125]
	v_mfma_f32_16x16x32_bf16 v[106:109], v[150:153], v[174:177], v[106:109]
	v_mfma_f32_16x16x32_bf16 v[106:109], v[154:157], v[178:181], v[106:109]
	v_mfma_f32_16x16x32_bf16 v[90:93], v[150:153], v[182:185], v[90:93]
	v_mfma_f32_16x16x32_bf16 v[90:93], v[154:157], v[186:189], v[90:93]
	v_mfma_f32_16x16x32_bf16 v[74:77], v[150:153], v[190:193], v[74:77]
	v_mfma_f32_16x16x32_bf16 v[74:77], v[154:157], v[194:197], v[74:77]
	v_mfma_f32_16x16x32_bf16 v[118:121], v[158:161], v[166:169], v[118:121]
	v_mfma_f32_16x16x32_bf16 v[118:121], v[162:165], v[170:173], v[118:121]
	v_mfma_f32_16x16x32_bf16 v[102:105], v[158:161], v[174:177], v[102:105]
	v_mfma_f32_16x16x32_bf16 v[102:105], v[162:165], v[178:181], v[102:105]
	v_mfma_f32_16x16x32_bf16 v[86:89], v[158:161], v[182:185], v[86:89]
	v_mfma_f32_16x16x32_bf16 v[86:89], v[162:165], v[186:189], v[86:89]
	v_mfma_f32_16x16x32_bf16 v[70:73], v[158:161], v[190:193], v[70:73]
	v_mfma_f32_16x16x32_bf16 v[70:73], v[162:165], v[194:197], v[70:73]
	s_setprio 0
	s_barrier
	s_mov_b32 m0, s64
	ds_read_b128 v[166:169], v233 offset:49152
	ds_read_b128 v[170:173], v233 offset:50176
	ds_read_b128 v[174:177], v233 offset:51200
	ds_read_b128 v[178:181], v233 offset:52224
	ds_read_b128 v[182:185], v233 offset:53248
	ds_read_b128 v[186:189], v233 offset:54272
	ds_read_b128 v[190:193], v233 offset:55296
	ds_read_b128 v[194:197], v233 offset:56320
	buffer_load_dwordx4 v231, s[16:19], s52 offen lds
	s_add_i32 s52, s51, 0x18080
	s_mov_b32 m0, s65
	s_nop 0
	buffer_load_dwordx4 v231, s[16:19], s52 offen lds
	s_add_i32 s52, s51, 0x30080
	s_mov_b32 m0, s68
	s_add_i32 s51, s51, 0x48080
	buffer_load_dwordx4 v231, s[16:19], s52 offen lds
	s_mov_b32 m0, s69
	s_nop 0
	buffer_load_dwordx4 v231, s[16:19], s51 offen lds
	s_mov_b32 m0, s66
	s_add_i32 s18, s92, 0x40080
	buffer_load_dwordx4 v230, s[12:15], s50 offen lds
	s_mov_b32 m0, s67
	s_nop 0
	buffer_load_dwordx4 v230, s[12:15], s18 offen lds
	s_waitcnt vmcnt(8)
	s_waitcnt lgkmcnt(0)
	s_setprio 1
	v_mfma_f32_16x16x32_bf16 v[66:69], v[134:137], v[166:169], v[66:69]
	s_barrier
	v_mfma_f32_16x16x32_bf16 v[62:65], v[142:145], v[166:169], v[62:65]
	v_mfma_f32_16x16x32_bf16 v[50:53], v[134:137], v[174:177], v[50:53]
	v_mfma_f32_16x16x32_bf16 v[46:49], v[142:145], v[174:177], v[46:49]
	v_mfma_f32_16x16x32_bf16 v[34:37], v[134:137], v[182:185], v[34:37]
	v_mfma_f32_16x16x32_bf16 v[30:33], v[142:145], v[182:185], v[30:33]
	v_mfma_f32_16x16x32_bf16 v[18:21], v[134:137], v[190:193], v[18:21]
	v_mfma_f32_16x16x32_bf16 v[14:17], v[142:145], v[190:193], v[14:17]
	v_mfma_f32_16x16x32_bf16 v[58:61], v[150:153], v[166:169], v[58:61]
	v_mfma_f32_16x16x32_bf16 v[54:57], v[158:161], v[166:169], v[54:57]
	v_mfma_f32_16x16x32_bf16 v[42:45], v[150:153], v[174:177], v[42:45]
	v_mfma_f32_16x16x32_bf16 v[38:41], v[158:161], v[174:177], v[38:41]
	v_mfma_f32_16x16x32_bf16 v[26:29], v[150:153], v[182:185], v[26:29]
	v_mfma_f32_16x16x32_bf16 v[22:25], v[158:161], v[182:185], v[22:25]
	v_mfma_f32_16x16x32_bf16 v[8:11], v[150:153], v[190:193], v[10:13]
	v_mfma_f32_16x16x32_bf16 v[4:7], v[158:161], v[190:193], v[4:7]
	v_mfma_f32_16x16x32_bf16 v[66:69], v[138:141], v[170:173], v[66:69]
	v_mfma_f32_16x16x32_bf16 v[62:65], v[146:149], v[170:173], v[62:65]
	v_mfma_f32_16x16x32_bf16 v[50:53], v[138:141], v[178:181], v[50:53]
	v_mfma_f32_16x16x32_bf16 v[46:49], v[146:149], v[178:181], v[46:49]
	v_mfma_f32_16x16x32_bf16 v[34:37], v[138:141], v[186:189], v[34:37]
	v_mfma_f32_16x16x32_bf16 v[30:33], v[146:149], v[186:189], v[30:33]
	v_mfma_f32_16x16x32_bf16 v[18:21], v[138:141], v[194:197], v[18:21]
	v_mfma_f32_16x16x32_bf16 v[14:17], v[146:149], v[194:197], v[14:17]
	v_mfma_f32_16x16x32_bf16 v[58:61], v[154:157], v[170:173], v[58:61]
	v_mfma_f32_16x16x32_bf16 v[54:57], v[162:165], v[170:173], v[54:57]
	v_mfma_f32_16x16x32_bf16 v[42:45], v[154:157], v[178:181], v[42:45]
	v_mfma_f32_16x16x32_bf16 v[38:41], v[162:165], v[178:181], v[38:41]
	v_mfma_f32_16x16x32_bf16 v[26:29], v[154:157], v[186:189], v[26:29]
	v_mfma_f32_16x16x32_bf16 v[22:25], v[162:165], v[186:189], v[22:25]
	v_mfma_f32_16x16x32_bf16 v[10:13], v[154:157], v[194:197], v[8:11]
	v_mfma_f32_16x16x32_bf16 v[6:9], v[162:165], v[194:197], v[4:7]
	s_setprio 0
	s_barrier
	s_add_i32 s91, s91, 2
	s_addk_i32 s90, 0x100
	s_cmp_ge_i32 s91, s3
	s_cbranch_scc1 .LBB0_1193

.LBB0_1290:
	ds_read_b128 v[106:109], v224
	ds_read_b128 v[118:121], v224 offset:1024
	ds_read_b128 v[130:133], v224 offset:2048
	ds_read_b128 v[138:141], v224 offset:3072
	ds_read_b128 v[146:149], v225
	ds_read_b128 v[150:153], v225 offset:1024
	ds_read_b128 v[154:157], v225 offset:2048
	ds_read_b128 v[158:161], v225 offset:3072
	s_add_i32 s18, s72, 0xffe80080
	s_cmp_eq_u32 s56, s74
	s_cselect_b32 s75, s6, s18
	s_cselect_b32 s77, s7, s73
	s_or_b32 s76, s75, 0x80
	s_add_i32 s18, s72, 0xfff80000
	s_mov_b32 m0, s57
	ds_read_b128 v[162:165], v226
	ds_read_b128 v[166:169], v226 offset:1024
	ds_read_b128 v[170:173], v226 offset:2048
	ds_read_b128 v[174:177], v226 offset:3072
	ds_read_b128 v[178:181], v226 offset:4096
	ds_read_b128 v[182:185], v226 offset:5120
	ds_read_b128 v[190:193], v226 offset:6144
	ds_read_b128 v[194:197], v226 offset:7168
	buffer_load_dwordx4 v222, s[12:15], s18 offen lds
	s_mov_b32 m0, s60
	s_nop 0
	buffer_load_dwordx4 v222, s[12:15], s72 offen lds
	s_waitcnt vmcnt(8)
	s_waitcnt lgkmcnt(0)
	s_setprio 1
	v_mfma_f32_16x16x32_bf16 v[142:145], v[106:109], v[162:165], v[142:145]
	s_barrier
	v_mfma_f32_16x16x32_bf16 v[142:145], v[118:121], v[166:169], v[142:145]
	v_mfma_f32_16x16x32_bf16 v[114:117], v[106:109], v[170:173], v[114:117]
	v_mfma_f32_16x16x32_bf16 v[114:117], v[118:121], v[174:177], v[114:117]
	v_mfma_f32_16x16x32_bf16 v[94:97], v[106:109], v[178:181], v[94:97]
	v_mfma_f32_16x16x32_bf16 v[94:97], v[118:121], v[182:185], v[94:97]
	v_mfma_f32_16x16x32_bf16 v[78:81], v[106:109], v[190:193], v[78:81]
	v_mfma_f32_16x16x32_bf16 v[78:81], v[118:121], v[194:197], v[78:81]
	v_mfma_f32_16x16x32_bf16 v[134:137], v[130:133], v[162:165], v[134:137]
	v_mfma_f32_16x16x32_bf16 v[134:137], v[138:141], v[166:169], v[134:137]
	v_mfma_f32_16x16x32_bf16 v[110:113], v[130:133], v[170:173], v[110:113]
	v_mfma_f32_16x16x32_bf16 v[110:113], v[138:141], v[174:177], v[110:113]
	v_mfma_f32_16x16x32_bf16 v[90:93], v[130:133], v[178:181], v[90:93]
	v_mfma_f32_16x16x32_bf16 v[90:93], v[138:141], v[182:185], v[90:93]
	v_mfma_f32_16x16x32_bf16 v[74:77], v[130:133], v[190:193], v[74:77]
	v_mfma_f32_16x16x32_bf16 v[74:77], v[138:141], v[194:197], v[74:77]
	v_mfma_f32_16x16x32_bf16 v[126:129], v[146:149], v[162:165], v[126:129]
	v_mfma_f32_16x16x32_bf16 v[126:129], v[150:153], v[166:169], v[126:129]
	v_mfma_f32_16x16x32_bf16 v[102:105], v[146:149], v[170:173], v[102:105]
	v_mfma_f32_16x16x32_bf16 v[102:105], v[150:153], v[174:177], v[102:105]
	v_mfma_f32_16x16x32_bf16 v[86:89], v[146:149], v[178:181], v[86:89]
	v_mfma_f32_16x16x32_bf16 v[86:89], v[150:153], v[182:185], v[86:89]
	v_mfma_f32_16x16x32_bf16 v[70:73], v[146:149], v[190:193], v[70:73]
	v_mfma_f32_16x16x32_bf16 v[70:73], v[150:153], v[194:197], v[70:73]
	v_mfma_f32_16x16x32_bf16 v[122:125], v[154:157], v[162:165], v[122:125]
	v_mfma_f32_16x16x32_bf16 v[122:125], v[158:161], v[166:169], v[122:125]
	v_mfma_f32_16x16x32_bf16 v[98:101], v[154:157], v[170:173], v[98:101]
	v_mfma_f32_16x16x32_bf16 v[98:101], v[158:161], v[174:177], v[98:101]
	v_mfma_f32_16x16x32_bf16 v[82:85], v[154:157], v[178:181], v[82:85]
	v_mfma_f32_16x16x32_bf16 v[82:85], v[158:161], v[182:185], v[82:85]
	v_mfma_f32_16x16x32_bf16 v[66:69], v[154:157], v[190:193], v[66:69]
	v_mfma_f32_16x16x32_bf16 v[66:69], v[158:161], v[194:197], v[66:69]
	s_setprio 0
	s_barrier
	s_mov_b32 m0, s27
	s_mov_b32 s18, s14
	s_mov_b32 s19, s15
	ds_read_b128 v[162:165], v226 offset:16384
	ds_read_b128 v[166:169], v226 offset:17408
	ds_read_b128 v[170:173], v226 offset:18432
	ds_read_b128 v[174:177], v226 offset:19456
	ds_read_b128 v[178:181], v226 offset:20480
	ds_read_b128 v[182:185], v226 offset:21504
	ds_read_b128 v[190:193], v226 offset:22528
	ds_read_b128 v[194:197], v226 offset:23552
	buffer_load_dwordx4 v223, s[16:19], s77 offen lds
	s_add_i32 s78, s77, 0x80000
	s_mov_b32 m0, s30
	s_nop 0
	buffer_load_dwordx4 v223, s[16:19], s78 offen lds
	s_add_i32 s78, s77, 0x100000
	s_mov_b32 m0, s31
	s_nop 0
	buffer_load_dwordx4 v223, s[16:19], s78 offen lds
	s_add_i32 s78, s77, 0x180000
	s_mov_b32 m0, s41
	s_nop 0
	buffer_load_dwordx4 v223, s[16:19], s78 offen lds
	s_mov_b32 m0, s25
	s_add_i32 s78, s75, 0x80000
	buffer_load_dwordx4 v222, s[12:15], s75 offen lds
	s_mov_b32 m0, s42
	s_nop 0
	buffer_load_dwordx4 v222, s[12:15], s78 offen lds
	s_waitcnt vmcnt(8)
	s_waitcnt lgkmcnt(0)
	s_setprio 1
	v_mfma_f32_16x16x32_bf16 v[62:65], v[106:109], v[162:165], v[62:65]
	s_barrier
	v_mfma_f32_16x16x32_bf16 v[62:65], v[118:121], v[166:169], v[62:65]
	v_mfma_f32_16x16x32_bf16 v[46:49], v[106:109], v[170:173], v[46:49]
	v_mfma_f32_16x16x32_bf16 v[46:49], v[118:121], v[174:177], v[46:49]
	v_mfma_f32_16x16x32_bf16 v[30:33], v[106:109], v[178:181], v[30:33]
	v_mfma_f32_16x16x32_bf16 v[30:33], v[118:121], v[182:185], v[30:33]
	v_mfma_f32_16x16x32_bf16 v[14:17], v[106:109], v[190:193], v[14:17]
	v_mfma_f32_16x16x32_bf16 v[14:17], v[118:121], v[194:197], v[14:17]
	v_mfma_f32_16x16x32_bf16 v[58:61], v[130:133], v[162:165], v[58:61]
	v_mfma_f32_16x16x32_bf16 v[58:61], v[138:141], v[166:169], v[58:61]
	v_mfma_f32_16x16x32_bf16 v[42:45], v[130:133], v[170:173], v[42:45]
	v_mfma_f32_16x16x32_bf16 v[42:45], v[138:141], v[174:177], v[42:45]
	v_mfma_f32_16x16x32_bf16 v[26:29], v[130:133], v[178:181], v[26:29]
	v_mfma_f32_16x16x32_bf16 v[26:29], v[138:141], v[182:185], v[26:29]
	v_mfma_f32_16x16x32_bf16 v[10:13], v[130:133], v[190:193], v[10:13]
	v_mfma_f32_16x16x32_bf16 v[10:13], v[138:141], v[194:197], v[10:13]
	v_mfma_f32_16x16x32_bf16 v[54:57], v[146:149], v[162:165], v[54:57]
	v_mfma_f32_16x16x32_bf16 v[54:57], v[150:153], v[166:169], v[54:57]
	v_mfma_f32_16x16x32_bf16 v[38:41], v[146:149], v[170:173], v[38:41]
	v_mfma_f32_16x16x32_bf16 v[38:41], v[150:153], v[174:177], v[38:41]
	v_mfma_f32_16x16x32_bf16 v[22:25], v[146:149], v[178:181], v[22:25]
	v_mfma_f32_16x16x32_bf16 v[22:25], v[150:153], v[182:185], v[22:25]
	v_mfma_f32_16x16x32_bf16 v[6:9], v[146:149], v[190:193], v[6:9]
	v_mfma_f32_16x16x32_bf16 v[6:9], v[150:153], v[194:197], v[6:9]
	v_mfma_f32_16x16x32_bf16 v[50:53], v[154:157], v[162:165], v[50:53]
	v_mfma_f32_16x16x32_bf16 v[50:53], v[158:161], v[166:169], v[50:53]
	v_mfma_f32_16x16x32_bf16 v[34:37], v[154:157], v[170:173], v[34:37]
	v_mfma_f32_16x16x32_bf16 v[34:37], v[158:161], v[174:177], v[34:37]
	v_mfma_f32_16x16x32_bf16 v[18:21], v[154:157], v[178:181], v[18:21]
	v_mfma_f32_16x16x32_bf16 v[18:21], v[158:161], v[182:185], v[18:21]
	v_mfma_f32_16x16x32_bf16 v[2:5], v[154:157], v[190:193], v[2:5]
	v_mfma_f32_16x16x32_bf16 v[2:5], v[158:161], v[194:197], v[2:5]
	s_setprio 0
	s_barrier
	ds_read_b128 v[106:109], v227
	ds_read_b128 v[118:121], v227 offset:1024
	ds_read_b128 v[130:133], v227 offset:2048
	ds_read_b128 v[138:141], v227 offset:3072
	ds_read_b128 v[146:149], v228
	ds_read_b128 v[150:153], v228 offset:1024
	ds_read_b128 v[154:157], v228 offset:2048
	ds_read_b128 v[158:161], v228 offset:3072
	s_mov_b32 m0, s43
	s_add_i32 s78, s75, 0x100000
	ds_read_b128 v[162:165], v226 offset:32768
	ds_read_b128 v[166:169], v226 offset:33792
	ds_read_b128 v[170:173], v226 offset:34816
	ds_read_b128 v[174:177], v226 offset:35840
	ds_read_b128 v[178:181], v226 offset:36864
	ds_read_b128 v[182:185], v226 offset:37888
	ds_read_b128 v[190:193], v226 offset:38912
	ds_read_b128 v[194:197], v226 offset:39936
	buffer_load_dwordx4 v222, s[12:15], s78 offen lds
	s_add_i32 s78, s75, 0x180000
	s_mov_b32 m0, s44
	s_nop 0
	buffer_load_dwordx4 v222, s[12:15], s78 offen lds
	s_waitcnt vmcnt(8)
	s_waitcnt lgkmcnt(0)
	s_setprio 1
	v_mfma_f32_16x16x32_bf16 v[142:145], v[106:109], v[162:165], v[142:145]
	s_barrier
	v_mfma_f32_16x16x32_bf16 v[142:145], v[118:121], v[166:169], v[142:145]
	v_mfma_f32_16x16x32_bf16 v[114:117], v[106:109], v[170:173], v[114:117]
	v_mfma_f32_16x16x32_bf16 v[114:117], v[118:121], v[174:177], v[114:117]
	v_mfma_f32_16x16x32_bf16 v[94:97], v[106:109], v[178:181], v[94:97]
	v_mfma_f32_16x16x32_bf16 v[94:97], v[118:121], v[182:185], v[94:97]
	v_mfma_f32_16x16x32_bf16 v[78:81], v[106:109], v[190:193], v[78:81]
	v_mfma_f32_16x16x32_bf16 v[78:81], v[118:121], v[194:197], v[78:81]
	v_mfma_f32_16x16x32_bf16 v[134:137], v[130:133], v[162:165], v[134:137]
	v_mfma_f32_16x16x32_bf16 v[134:137], v[138:141], v[166:169], v[134:137]
	v_mfma_f32_16x16x32_bf16 v[110:113], v[130:133], v[170:173], v[110:113]
	v_mfma_f32_16x16x32_bf16 v[110:113], v[138:141], v[174:177], v[110:113]
	v_mfma_f32_16x16x32_bf16 v[90:93], v[130:133], v[178:181], v[90:93]
	v_mfma_f32_16x16x32_bf16 v[90:93], v[138:141], v[182:185], v[90:93]
	v_mfma_f32_16x16x32_bf16 v[74:77], v[130:133], v[190:193], v[74:77]
	v_mfma_f32_16x16x32_bf16 v[74:77], v[138:141], v[194:197], v[74:77]
	v_mfma_f32_16x16x32_bf16 v[126:129], v[146:149], v[162:165], v[126:129]
	v_mfma_f32_16x16x32_bf16 v[126:129], v[150:153], v[166:169], v[126:129]
	v_mfma_f32_16x16x32_bf16 v[102:105], v[146:149], v[170:173], v[102:105]
	v_mfma_f32_16x16x32_bf16 v[102:105], v[150:153], v[174:177], v[102:105]
	v_mfma_f32_16x16x32_bf16 v[86:89], v[146:149], v[178:181], v[86:89]
	v_mfma_f32_16x16x32_bf16 v[86:89], v[150:153], v[182:185], v[86:89]
	v_mfma_f32_16x16x32_bf16 v[70:73], v[146:149], v[190:193], v[70:73]
	v_mfma_f32_16x16x32_bf16 v[70:73], v[150:153], v[194:197], v[70:73]
	v_mfma_f32_16x16x32_bf16 v[122:125], v[154:157], v[162:165], v[122:125]
	v_mfma_f32_16x16x32_bf16 v[122:125], v[158:161], v[166:169], v[122:125]
	v_mfma_f32_16x16x32_bf16 v[98:101], v[154:157], v[170:173], v[98:101]
	v_mfma_f32_16x16x32_bf16 v[98:101], v[158:161], v[174:177], v[98:101]
	v_mfma_f32_16x16x32_bf16 v[82:85], v[154:157], v[178:181], v[82:85]
	v_mfma_f32_16x16x32_bf16 v[82:85], v[158:161], v[182:185], v[82:85]
	v_mfma_f32_16x16x32_bf16 v[66:69], v[154:157], v[190:193], v[66:69]
	v_mfma_f32_16x16x32_bf16 v[66:69], v[158:161], v[194:197], v[66:69]
	s_setprio 0
	s_barrier
	s_mov_b32 m0, s48
	s_or_b32 s78, s77, 0x80
	ds_read_b128 v[162:165], v226 offset:49152
	ds_read_b128 v[166:169], v226 offset:50176
	ds_read_b128 v[170:173], v226 offset:51200
	ds_read_b128 v[174:177], v226 offset:52224
	ds_read_b128 v[178:181], v226 offset:53248
	ds_read_b128 v[182:185], v226 offset:54272
	ds_read_b128 v[190:193], v226 offset:55296
	ds_read_b128 v[194:197], v226 offset:56320
	buffer_load_dwordx4 v223, s[16:19], s78 offen lds
	s_add_i32 s78, s77, 0x80080
	s_mov_b32 m0, s49
	s_add_i32 s75, s75, 0x80080
	buffer_load_dwordx4 v223, s[16:19], s78 offen lds
	s_add_i32 s78, s77, 0x100080
	s_mov_b32 m0, s52
	s_add_i32 s77, s77, 0x180080
	buffer_load_dwordx4 v223, s[16:19], s78 offen lds
	s_mov_b32 m0, s53
	s_nop 0
	buffer_load_dwordx4 v223, s[16:19], s77 offen lds
	s_mov_b32 m0, s50
	s_nop 0
	buffer_load_dwordx4 v222, s[12:15], s76 offen lds
	s_mov_b32 m0, s51
	s_nop 0
	buffer_load_dwordx4 v222, s[12:15], s75 offen lds
	s_waitcnt vmcnt(8)
	s_waitcnt lgkmcnt(0)
	s_setprio 1
	v_mfma_f32_16x16x32_bf16 v[62:65], v[106:109], v[162:165], v[62:65]
	s_barrier
	v_mfma_f32_16x16x32_bf16 v[62:65], v[118:121], v[166:169], v[62:65]
	v_mfma_f32_16x16x32_bf16 v[46:49], v[106:109], v[170:173], v[46:49]
	v_mfma_f32_16x16x32_bf16 v[46:49], v[118:121], v[174:177], v[46:49]
	v_mfma_f32_16x16x32_bf16 v[30:33], v[106:109], v[178:181], v[30:33]
	v_mfma_f32_16x16x32_bf16 v[30:33], v[118:121], v[182:185], v[30:33]
	v_mfma_f32_16x16x32_bf16 v[14:17], v[106:109], v[190:193], v[14:17]
	v_mfma_f32_16x16x32_bf16 v[14:17], v[118:121], v[194:197], v[14:17]
	v_mfma_f32_16x16x32_bf16 v[58:61], v[130:133], v[162:165], v[58:61]
	v_mfma_f32_16x16x32_bf16 v[58:61], v[138:141], v[166:169], v[58:61]
	v_mfma_f32_16x16x32_bf16 v[42:45], v[130:133], v[170:173], v[42:45]
	v_mfma_f32_16x16x32_bf16 v[42:45], v[138:141], v[174:177], v[42:45]
	v_mfma_f32_16x16x32_bf16 v[26:29], v[130:133], v[178:181], v[26:29]
	v_mfma_f32_16x16x32_bf16 v[26:29], v[138:141], v[182:185], v[26:29]
	v_mfma_f32_16x16x32_bf16 v[10:13], v[130:133], v[190:193], v[10:13]
	v_mfma_f32_16x16x32_bf16 v[10:13], v[138:141], v[194:197], v[10:13]
	v_mfma_f32_16x16x32_bf16 v[54:57], v[146:149], v[162:165], v[54:57]
	v_mfma_f32_16x16x32_bf16 v[54:57], v[150:153], v[166:169], v[54:57]
	v_mfma_f32_16x16x32_bf16 v[38:41], v[146:149], v[170:173], v[38:41]
	v_mfma_f32_16x16x32_bf16 v[38:41], v[150:153], v[174:177], v[38:41]
	v_mfma_f32_16x16x32_bf16 v[22:25], v[146:149], v[178:181], v[22:25]
	v_mfma_f32_16x16x32_bf16 v[22:25], v[150:153], v[182:185], v[22:25]
	v_mfma_f32_16x16x32_bf16 v[6:9], v[146:149], v[190:193], v[6:9]
	v_mfma_f32_16x16x32_bf16 v[6:9], v[150:153], v[194:197], v[6:9]
	v_mfma_f32_16x16x32_bf16 v[50:53], v[154:157], v[162:165], v[50:53]
	v_mfma_f32_16x16x32_bf16 v[50:53], v[158:161], v[166:169], v[50:53]
	v_mfma_f32_16x16x32_bf16 v[34:37], v[154:157], v[170:173], v[34:37]
	v_mfma_f32_16x16x32_bf16 v[34:37], v[158:161], v[174:177], v[34:37]
	v_mfma_f32_16x16x32_bf16 v[18:21], v[154:157], v[178:181], v[18:21]
	v_mfma_f32_16x16x32_bf16 v[18:21], v[158:161], v[182:185], v[18:21]
	v_mfma_f32_16x16x32_bf16 v[2:5], v[154:157], v[190:193], v[2:5]
	v_mfma_f32_16x16x32_bf16 v[2:5], v[158:161], v[194:197], v[2:5]
	s_setprio 0
	s_barrier
	s_add_i32 s74, s74, 2
	s_addk_i32 s72, 0x100
	s_addk_i32 s73, 0x100
	s_cmp_ge_i32 s74, s3
	s_cbranch_scc0 .LBB0_1290
	s_and_b64 vcc, exec, s[38:39]
	s_cbranch_vccz .LBB0_1293

.LBB0_1382:
	ds_read_b128 v[144:147], v138
	ds_read_b128 v[148:151], v138 offset:1024
	ds_read_b128 v[152:155], v138 offset:2048
	ds_read_b128 v[156:159], v138 offset:3072
	ds_read_b128 v[160:163], v139
	ds_read_b128 v[164:167], v139 offset:1024
	ds_read_b128 v[168:171], v139 offset:2048
	ds_read_b128 v[172:175], v139 offset:3072
	s_add_i32 s14, s74, 0xffe80080
	s_cmp_eq_u32 s61, s76
	s_cselect_b32 s77, s72, s14
	s_cselect_b32 s79, s73, s75
	s_or_b32 s78, s77, 0x80
	s_add_i32 s14, s74, 0xfff80000
	s_mov_b32 m0, s62
	ds_read_b128 v[176:179], v140
	ds_read_b128 v[180:183], v140 offset:1024
	ds_read_b128 v[184:187], v140 offset:2048
	ds_read_b128 v[188:191], v140 offset:3072
	ds_read_b128 v[192:195], v140 offset:4096
	ds_read_b128 v[196:199], v140 offset:5120
	ds_read_b128 v[200:203], v140 offset:6144
	ds_read_b128 v[204:207], v140 offset:7168
	buffer_load_dwordx4 v136, s[16:19], s14 offen lds
	s_mov_b32 m0, s63
	s_nop 0
	buffer_load_dwordx4 v136, s[16:19], s74 offen lds
	s_waitcnt vmcnt(8)
	s_waitcnt lgkmcnt(0)
	s_setprio 1
	v_mfma_f32_16x16x32_bf16 v[118:121], v[144:147], v[176:179], v[118:121]
	s_barrier
	v_mfma_f32_16x16x32_bf16 v[118:121], v[148:151], v[180:183], v[118:121]
	v_mfma_f32_16x16x32_bf16 v[110:113], v[144:147], v[184:187], v[110:113]
	v_mfma_f32_16x16x32_bf16 v[110:113], v[148:151], v[188:191], v[110:113]
	v_mfma_f32_16x16x32_bf16 v[94:97], v[144:147], v[192:195], v[94:97]
	v_mfma_f32_16x16x32_bf16 v[94:97], v[148:151], v[196:199], v[94:97]
	v_mfma_f32_16x16x32_bf16 v[78:81], v[144:147], v[200:203], v[78:81]
	v_mfma_f32_16x16x32_bf16 v[78:81], v[148:151], v[204:207], v[78:81]
	v_mfma_f32_16x16x32_bf16 v[114:117], v[152:155], v[176:179], v[114:117]
	v_mfma_f32_16x16x32_bf16 v[114:117], v[156:159], v[180:183], v[114:117]
	v_mfma_f32_16x16x32_bf16 v[102:105], v[152:155], v[184:187], v[102:105]
	v_mfma_f32_16x16x32_bf16 v[102:105], v[156:159], v[188:191], v[102:105]
	v_mfma_f32_16x16x32_bf16 v[86:89], v[152:155], v[192:195], v[86:89]
	v_mfma_f32_16x16x32_bf16 v[86:89], v[156:159], v[196:199], v[86:89]
	v_mfma_f32_16x16x32_bf16 v[66:69], v[152:155], v[200:203], v[66:69]
	v_mfma_f32_16x16x32_bf16 v[66:69], v[156:159], v[204:207], v[66:69]
	v_mfma_f32_16x16x32_bf16 v[126:129], v[160:163], v[176:179], v[126:129]
	v_mfma_f32_16x16x32_bf16 v[126:129], v[164:167], v[180:183], v[126:129]
	v_mfma_f32_16x16x32_bf16 v[106:109], v[160:163], v[184:187], v[106:109]
	v_mfma_f32_16x16x32_bf16 v[106:109], v[164:167], v[188:191], v[106:109]
	v_mfma_f32_16x16x32_bf16 v[90:93], v[160:163], v[192:195], v[90:93]
	v_mfma_f32_16x16x32_bf16 v[90:93], v[164:167], v[196:199], v[90:93]
	v_mfma_f32_16x16x32_bf16 v[74:77], v[160:163], v[200:203], v[74:77]
	v_mfma_f32_16x16x32_bf16 v[74:77], v[164:167], v[204:207], v[74:77]
	v_mfma_f32_16x16x32_bf16 v[122:125], v[168:171], v[176:179], v[122:125]
	v_mfma_f32_16x16x32_bf16 v[122:125], v[172:175], v[180:183], v[122:125]
	v_mfma_f32_16x16x32_bf16 v[98:101], v[168:171], v[184:187], v[98:101]
	v_mfma_f32_16x16x32_bf16 v[98:101], v[172:175], v[188:191], v[98:101]
	v_mfma_f32_16x16x32_bf16 v[82:85], v[168:171], v[192:195], v[82:85]
	v_mfma_f32_16x16x32_bf16 v[82:85], v[172:175], v[196:199], v[82:85]
	v_mfma_f32_16x16x32_bf16 v[70:73], v[168:171], v[200:203], v[70:73]
	v_mfma_f32_16x16x32_bf16 v[70:73], v[172:175], v[204:207], v[70:73]
	s_setprio 0
	s_barrier
	s_mov_b32 m0, s45
	s_mov_b32 s14, s18
	s_mov_b32 s15, s19
	ds_read_b128 v[176:179], v140 offset:16384
	ds_read_b128 v[180:183], v140 offset:17408
	ds_read_b128 v[184:187], v140 offset:18432
	ds_read_b128 v[188:191], v140 offset:19456
	ds_read_b128 v[192:195], v140 offset:20480
	ds_read_b128 v[196:199], v140 offset:21504
	ds_read_b128 v[200:203], v140 offset:22528
	ds_read_b128 v[204:207], v140 offset:23552
	buffer_load_dwordx4 v137, s[12:15], s79 offen lds
	s_add_i32 s80, s79, 0x80000
	s_mov_b32 m0, s46
	s_nop 0
	buffer_load_dwordx4 v137, s[12:15], s80 offen lds
	s_add_i32 s80, s79, 0x100000
	s_mov_b32 m0, s47
	s_nop 0
	buffer_load_dwordx4 v137, s[12:15], s80 offen lds
	s_add_i32 s80, s79, 0x180000
	s_mov_b32 m0, s48
	s_nop 0
	buffer_load_dwordx4 v137, s[12:15], s80 offen lds
	s_mov_b32 m0, s44
	s_add_i32 s80, s77, 0x80000
	buffer_load_dwordx4 v136, s[16:19], s77 offen lds
	s_mov_b32 m0, s49
	s_nop 0
	buffer_load_dwordx4 v136, s[16:19], s80 offen lds
	s_waitcnt vmcnt(8)
	s_waitcnt lgkmcnt(0)
	s_setprio 1
	v_mfma_f32_16x16x32_bf16 v[62:65], v[144:147], v[176:179], v[62:65]
	s_barrier
	v_mfma_f32_16x16x32_bf16 v[62:65], v[148:151], v[180:183], v[62:65]
	v_mfma_f32_16x16x32_bf16 v[46:49], v[144:147], v[184:187], v[46:49]
	v_mfma_f32_16x16x32_bf16 v[46:49], v[148:151], v[188:191], v[46:49]
	v_mfma_f32_16x16x32_bf16 v[30:33], v[144:147], v[192:195], v[30:33]
	v_mfma_f32_16x16x32_bf16 v[30:33], v[148:151], v[196:199], v[30:33]
	v_mfma_f32_16x16x32_bf16 v[14:17], v[144:147], v[200:203], v[14:17]
	v_mfma_f32_16x16x32_bf16 v[14:17], v[148:151], v[204:207], v[14:17]
	v_mfma_f32_16x16x32_bf16 v[54:57], v[152:155], v[176:179], v[54:57]
	v_mfma_f32_16x16x32_bf16 v[54:57], v[156:159], v[180:183], v[54:57]
	v_mfma_f32_16x16x32_bf16 v[38:41], v[152:155], v[184:187], v[38:41]
	v_mfma_f32_16x16x32_bf16 v[38:41], v[156:159], v[188:191], v[38:41]
	v_mfma_f32_16x16x32_bf16 v[22:25], v[152:155], v[192:195], v[22:25]
	v_mfma_f32_16x16x32_bf16 v[22:25], v[156:159], v[196:199], v[22:25]
	v_mfma_f32_16x16x32_bf16 v[6:9], v[152:155], v[200:203], v[6:9]
	v_mfma_f32_16x16x32_bf16 v[6:9], v[156:159], v[204:207], v[6:9]
	v_mfma_f32_16x16x32_bf16 v[58:61], v[160:163], v[176:179], v[58:61]
	v_mfma_f32_16x16x32_bf16 v[58:61], v[164:167], v[180:183], v[58:61]
	v_mfma_f32_16x16x32_bf16 v[42:45], v[160:163], v[184:187], v[42:45]
	v_mfma_f32_16x16x32_bf16 v[42:45], v[164:167], v[188:191], v[42:45]
	v_mfma_f32_16x16x32_bf16 v[26:29], v[160:163], v[192:195], v[26:29]
	v_mfma_f32_16x16x32_bf16 v[26:29], v[164:167], v[196:199], v[26:29]
	v_mfma_f32_16x16x32_bf16 v[10:13], v[160:163], v[200:203], v[10:13]
	v_mfma_f32_16x16x32_bf16 v[10:13], v[164:167], v[204:207], v[10:13]
	v_mfma_f32_16x16x32_bf16 v[50:53], v[168:171], v[176:179], v[50:53]
	v_mfma_f32_16x16x32_bf16 v[50:53], v[172:175], v[180:183], v[50:53]
	v_mfma_f32_16x16x32_bf16 v[34:37], v[168:171], v[184:187], v[34:37]
	v_mfma_f32_16x16x32_bf16 v[34:37], v[172:175], v[188:191], v[34:37]
	v_mfma_f32_16x16x32_bf16 v[18:21], v[168:171], v[192:195], v[18:21]
	v_mfma_f32_16x16x32_bf16 v[18:21], v[172:175], v[196:199], v[18:21]
	v_mfma_f32_16x16x32_bf16 v[2:5], v[168:171], v[200:203], v[2:5]
	v_mfma_f32_16x16x32_bf16 v[2:5], v[172:175], v[204:207], v[2:5]
	s_setprio 0
	s_barrier
	ds_read_b128 v[144:147], v141
	ds_read_b128 v[148:151], v141 offset:1024
	ds_read_b128 v[152:155], v141 offset:2048
	ds_read_b128 v[156:159], v141 offset:3072
	ds_read_b128 v[160:163], v142
	ds_read_b128 v[164:167], v142 offset:1024
	ds_read_b128 v[168:171], v142 offset:2048
	ds_read_b128 v[172:175], v142 offset:3072
	s_mov_b32 m0, s50
	s_add_i32 s80, s77, 0x100000
	ds_read_b128 v[176:179], v140 offset:32768
	ds_read_b128 v[180:183], v140 offset:33792
	ds_read_b128 v[184:187], v140 offset:34816
	ds_read_b128 v[188:191], v140 offset:35840
	ds_read_b128 v[192:195], v140 offset:36864
	ds_read_b128 v[196:199], v140 offset:37888
	ds_read_b128 v[200:203], v140 offset:38912
	ds_read_b128 v[204:207], v140 offset:39936
	buffer_load_dwordx4 v136, s[16:19], s80 offen lds
	s_add_i32 s80, s77, 0x180000
	s_mov_b32 m0, s51
	s_nop 0
	buffer_load_dwordx4 v136, s[16:19], s80 offen lds
	s_waitcnt vmcnt(8)
	s_waitcnt lgkmcnt(0)
	s_setprio 1
	v_mfma_f32_16x16x32_bf16 v[118:121], v[144:147], v[176:179], v[118:121]
	s_barrier
	v_mfma_f32_16x16x32_bf16 v[118:121], v[148:151], v[180:183], v[118:121]
	v_mfma_f32_16x16x32_bf16 v[110:113], v[144:147], v[184:187], v[110:113]
	v_mfma_f32_16x16x32_bf16 v[110:113], v[148:151], v[188:191], v[110:113]
	v_mfma_f32_16x16x32_bf16 v[94:97], v[144:147], v[192:195], v[94:97]
	v_mfma_f32_16x16x32_bf16 v[94:97], v[148:151], v[196:199], v[94:97]
	v_mfma_f32_16x16x32_bf16 v[78:81], v[144:147], v[200:203], v[78:81]
	v_mfma_f32_16x16x32_bf16 v[78:81], v[148:151], v[204:207], v[78:81]
	v_mfma_f32_16x16x32_bf16 v[114:117], v[152:155], v[176:179], v[114:117]
	v_mfma_f32_16x16x32_bf16 v[114:117], v[156:159], v[180:183], v[114:117]
	v_mfma_f32_16x16x32_bf16 v[102:105], v[152:155], v[184:187], v[102:105]
	v_mfma_f32_16x16x32_bf16 v[102:105], v[156:159], v[188:191], v[102:105]
	v_mfma_f32_16x16x32_bf16 v[86:89], v[152:155], v[192:195], v[86:89]
	v_mfma_f32_16x16x32_bf16 v[86:89], v[156:159], v[196:199], v[86:89]
	v_mfma_f32_16x16x32_bf16 v[66:69], v[152:155], v[200:203], v[66:69]
	v_mfma_f32_16x16x32_bf16 v[66:69], v[156:159], v[204:207], v[66:69]
	v_mfma_f32_16x16x32_bf16 v[126:129], v[160:163], v[176:179], v[126:129]
	v_mfma_f32_16x16x32_bf16 v[126:129], v[164:167], v[180:183], v[126:129]
	v_mfma_f32_16x16x32_bf16 v[106:109], v[160:163], v[184:187], v[106:109]
	v_mfma_f32_16x16x32_bf16 v[106:109], v[164:167], v[188:191], v[106:109]
	v_mfma_f32_16x16x32_bf16 v[90:93], v[160:163], v[192:195], v[90:93]
	v_mfma_f32_16x16x32_bf16 v[90:93], v[164:167], v[196:199], v[90:93]
	v_mfma_f32_16x16x32_bf16 v[74:77], v[160:163], v[200:203], v[74:77]
	v_mfma_f32_16x16x32_bf16 v[74:77], v[164:167], v[204:207], v[74:77]
	v_mfma_f32_16x16x32_bf16 v[122:125], v[168:171], v[176:179], v[122:125]
	v_mfma_f32_16x16x32_bf16 v[122:125], v[172:175], v[180:183], v[122:125]
	v_mfma_f32_16x16x32_bf16 v[98:101], v[168:171], v[184:187], v[98:101]
	v_mfma_f32_16x16x32_bf16 v[98:101], v[172:175], v[188:191], v[98:101]
	v_mfma_f32_16x16x32_bf16 v[82:85], v[168:171], v[192:195], v[82:85]
	v_mfma_f32_16x16x32_bf16 v[82:85], v[172:175], v[196:199], v[82:85]
	v_mfma_f32_16x16x32_bf16 v[70:73], v[168:171], v[200:203], v[70:73]
	v_mfma_f32_16x16x32_bf16 v[70:73], v[172:175], v[204:207], v[70:73]
	s_setprio 0
	s_barrier
	s_mov_b32 m0, s53
	s_or_b32 s80, s79, 0x80
	ds_read_b128 v[176:179], v140 offset:49152
	ds_read_b128 v[180:183], v140 offset:50176
	ds_read_b128 v[184:187], v140 offset:51200
	ds_read_b128 v[188:191], v140 offset:52224
	ds_read_b128 v[192:195], v140 offset:53248
	ds_read_b128 v[196:199], v140 offset:54272
	ds_read_b128 v[200:203], v140 offset:55296
	ds_read_b128 v[204:207], v140 offset:56320
	buffer_load_dwordx4 v137, s[12:15], s80 offen lds
	s_add_i32 s80, s79, 0x80080
	s_mov_b32 m0, s54
	s_add_i32 s77, s77, 0x80080
	buffer_load_dwordx4 v137, s[12:15], s80 offen lds
	s_add_i32 s80, s79, 0x100080
	s_mov_b32 m0, s57
	s_add_i32 s79, s79, 0x180080
	buffer_load_dwordx4 v137, s[12:15], s80 offen lds
	s_mov_b32 m0, s58
	s_nop 0
	buffer_load_dwordx4 v137, s[12:15], s79 offen lds
	s_mov_b32 m0, s55
	s_nop 0
	buffer_load_dwordx4 v136, s[16:19], s78 offen lds
	s_mov_b32 m0, s56
	s_nop 0
	buffer_load_dwordx4 v136, s[16:19], s77 offen lds
	s_waitcnt vmcnt(8)
	s_waitcnt lgkmcnt(0)
	s_setprio 1
	v_mfma_f32_16x16x32_bf16 v[62:65], v[144:147], v[176:179], v[62:65]
	s_barrier
	v_mfma_f32_16x16x32_bf16 v[62:65], v[148:151], v[180:183], v[62:65]
	v_mfma_f32_16x16x32_bf16 v[46:49], v[144:147], v[184:187], v[46:49]
	v_mfma_f32_16x16x32_bf16 v[46:49], v[148:151], v[188:191], v[46:49]
	v_mfma_f32_16x16x32_bf16 v[30:33], v[144:147], v[192:195], v[30:33]
	v_mfma_f32_16x16x32_bf16 v[30:33], v[148:151], v[196:199], v[30:33]
	v_mfma_f32_16x16x32_bf16 v[14:17], v[144:147], v[200:203], v[14:17]
	v_mfma_f32_16x16x32_bf16 v[14:17], v[148:151], v[204:207], v[14:17]
	v_mfma_f32_16x16x32_bf16 v[54:57], v[152:155], v[176:179], v[54:57]
	v_mfma_f32_16x16x32_bf16 v[54:57], v[156:159], v[180:183], v[54:57]
	v_mfma_f32_16x16x32_bf16 v[38:41], v[152:155], v[184:187], v[38:41]
	v_mfma_f32_16x16x32_bf16 v[38:41], v[156:159], v[188:191], v[38:41]
	v_mfma_f32_16x16x32_bf16 v[22:25], v[152:155], v[192:195], v[22:25]
	v_mfma_f32_16x16x32_bf16 v[22:25], v[156:159], v[196:199], v[22:25]
	v_mfma_f32_16x16x32_bf16 v[6:9], v[152:155], v[200:203], v[6:9]
	v_mfma_f32_16x16x32_bf16 v[6:9], v[156:159], v[204:207], v[6:9]
	v_mfma_f32_16x16x32_bf16 v[58:61], v[160:163], v[176:179], v[58:61]
	v_mfma_f32_16x16x32_bf16 v[58:61], v[164:167], v[180:183], v[58:61]
	v_mfma_f32_16x16x32_bf16 v[42:45], v[160:163], v[184:187], v[42:45]
	v_mfma_f32_16x16x32_bf16 v[42:45], v[164:167], v[188:191], v[42:45]
	v_mfma_f32_16x16x32_bf16 v[26:29], v[160:163], v[192:195], v[26:29]
	v_mfma_f32_16x16x32_bf16 v[26:29], v[164:167], v[196:199], v[26:29]
	v_mfma_f32_16x16x32_bf16 v[10:13], v[160:163], v[200:203], v[10:13]
	v_mfma_f32_16x16x32_bf16 v[10:13], v[164:167], v[204:207], v[10:13]
	v_mfma_f32_16x16x32_bf16 v[50:53], v[168:171], v[176:179], v[50:53]
	v_mfma_f32_16x16x32_bf16 v[50:53], v[172:175], v[180:183], v[50:53]
	v_mfma_f32_16x16x32_bf16 v[34:37], v[168:171], v[184:187], v[34:37]
	v_mfma_f32_16x16x32_bf16 v[34:37], v[172:175], v[188:191], v[34:37]
	v_mfma_f32_16x16x32_bf16 v[18:21], v[168:171], v[192:195], v[18:21]
	v_mfma_f32_16x16x32_bf16 v[18:21], v[172:175], v[196:199], v[18:21]
	v_mfma_f32_16x16x32_bf16 v[2:5], v[168:171], v[200:203], v[2:5]
	v_mfma_f32_16x16x32_bf16 v[2:5], v[172:175], v[204:207], v[2:5]
	s_setprio 0
	s_barrier
	s_add_i32 s76, s76, 2
	s_addk_i32 s74, 0x100
	s_addk_i32 s75, 0x100
	s_cmp_ge_i32 s76, s27
	s_cbranch_scc0 .LBB0_1382
	s_and_b64 vcc, exec, s[42:43]
	s_cbranch_vccz .LBB0_1385

.LBB0_1402:
	ds_read_b128 v[146:149], v138
	ds_read_b128 v[150:153], v138 offset:1024
	ds_read_b128 v[154:157], v138 offset:2048
	ds_read_b128 v[158:161], v138 offset:3072
	ds_read_b128 v[162:165], v139
	ds_read_b128 v[166:169], v139 offset:1024
	ds_read_b128 v[170:173], v139 offset:2048
	ds_read_b128 v[174:177], v139 offset:3072
	s_add_i32 s22, s75, 0xffe80080
	s_cmp_eq_u32 s62, s77
	s_cselect_b32 s78, s73, s22
	s_cselect_b32 s80, s74, s76
	s_or_b32 s79, s78, 0x80
	s_add_i32 s22, s75, 0xfff80000
	s_mov_b32 m0, s63
	ds_read_b128 v[178:181], v140
	ds_read_b128 v[182:185], v140 offset:1024
	ds_read_b128 v[186:189], v140 offset:2048
	ds_read_b128 v[190:193], v140 offset:3072
	ds_read_b128 v[194:197], v140 offset:4096
	ds_read_b128 v[198:201], v140 offset:5120
	ds_read_b128 v[202:205], v140 offset:6144
	ds_read_b128 v[206:209], v140 offset:7168
	buffer_load_dwordx4 v136, s[16:19], s22 offen lds
	s_mov_b32 m0, s64
	s_nop 0
	buffer_load_dwordx4 v136, s[16:19], s75 offen lds
	s_waitcnt vmcnt(8)
	s_waitcnt lgkmcnt(0)
	s_setprio 1
	v_mfma_f32_16x16x32_bf16 v[118:121], v[146:149], v[178:181], v[118:121]
	s_barrier
	v_mfma_f32_16x16x32_bf16 v[118:121], v[150:153], v[182:185], v[118:121]
	v_mfma_f32_16x16x32_bf16 v[110:113], v[146:149], v[186:189], v[110:113]
	v_mfma_f32_16x16x32_bf16 v[110:113], v[150:153], v[190:193], v[110:113]
	v_mfma_f32_16x16x32_bf16 v[94:97], v[146:149], v[194:197], v[94:97]
	v_mfma_f32_16x16x32_bf16 v[94:97], v[150:153], v[198:201], v[94:97]
	v_mfma_f32_16x16x32_bf16 v[78:81], v[146:149], v[202:205], v[78:81]
	v_mfma_f32_16x16x32_bf16 v[78:81], v[150:153], v[206:209], v[78:81]
	v_mfma_f32_16x16x32_bf16 v[114:117], v[154:157], v[178:181], v[114:117]
	v_mfma_f32_16x16x32_bf16 v[114:117], v[158:161], v[182:185], v[114:117]
	v_mfma_f32_16x16x32_bf16 v[102:105], v[154:157], v[186:189], v[102:105]
	v_mfma_f32_16x16x32_bf16 v[102:105], v[158:161], v[190:193], v[102:105]
	v_mfma_f32_16x16x32_bf16 v[86:89], v[154:157], v[194:197], v[86:89]
	v_mfma_f32_16x16x32_bf16 v[86:89], v[158:161], v[198:201], v[86:89]
	v_mfma_f32_16x16x32_bf16 v[66:69], v[154:157], v[202:205], v[66:69]
	v_mfma_f32_16x16x32_bf16 v[66:69], v[158:161], v[206:209], v[66:69]
	v_mfma_f32_16x16x32_bf16 v[126:129], v[162:165], v[178:181], v[126:129]
	v_mfma_f32_16x16x32_bf16 v[126:129], v[166:169], v[182:185], v[126:129]
	v_mfma_f32_16x16x32_bf16 v[106:109], v[162:165], v[186:189], v[106:109]
	v_mfma_f32_16x16x32_bf16 v[106:109], v[166:169], v[190:193], v[106:109]
	v_mfma_f32_16x16x32_bf16 v[90:93], v[162:165], v[194:197], v[90:93]
	v_mfma_f32_16x16x32_bf16 v[90:93], v[166:169], v[198:201], v[90:93]
	v_mfma_f32_16x16x32_bf16 v[74:77], v[162:165], v[202:205], v[74:77]
	v_mfma_f32_16x16x32_bf16 v[74:77], v[166:169], v[206:209], v[74:77]
	v_mfma_f32_16x16x32_bf16 v[122:125], v[170:173], v[178:181], v[122:125]
	v_mfma_f32_16x16x32_bf16 v[122:125], v[174:177], v[182:185], v[122:125]
	v_mfma_f32_16x16x32_bf16 v[98:101], v[170:173], v[186:189], v[98:101]
	v_mfma_f32_16x16x32_bf16 v[98:101], v[174:177], v[190:193], v[98:101]
	v_mfma_f32_16x16x32_bf16 v[82:85], v[170:173], v[194:197], v[82:85]
	v_mfma_f32_16x16x32_bf16 v[82:85], v[174:177], v[198:201], v[82:85]
	v_mfma_f32_16x16x32_bf16 v[70:73], v[170:173], v[202:205], v[70:73]
	v_mfma_f32_16x16x32_bf16 v[70:73], v[174:177], v[206:209], v[70:73]
	s_setprio 0
	s_barrier
	s_mov_b32 m0, s31
	s_mov_b32 s22, s18
	s_mov_b32 s23, s19
	ds_read_b128 v[178:181], v140 offset:16384
	ds_read_b128 v[182:185], v140 offset:17408
	ds_read_b128 v[186:189], v140 offset:18432
	ds_read_b128 v[190:193], v140 offset:19456
	ds_read_b128 v[194:197], v140 offset:20480
	ds_read_b128 v[198:201], v140 offset:21504
	ds_read_b128 v[202:205], v140 offset:22528
	ds_read_b128 v[206:209], v140 offset:23552
	buffer_load_dwordx4 v137, s[20:23], s80 offen lds
	s_add_i32 s81, s80, 0x80000
	s_mov_b32 m0, s48
	s_nop 0
	buffer_load_dwordx4 v137, s[20:23], s81 offen lds
	s_add_i32 s81, s80, 0x100000
	s_mov_b32 m0, s49
	s_nop 0
	buffer_load_dwordx4 v137, s[20:23], s81 offen lds
	s_add_i32 s81, s80, 0x180000
	s_mov_b32 m0, s50
	s_nop 0
	buffer_load_dwordx4 v137, s[20:23], s81 offen lds
	s_mov_b32 m0, s30
	s_add_i32 s81, s78, 0x80000
	buffer_load_dwordx4 v136, s[16:19], s78 offen lds
	s_mov_b32 m0, s51
	s_nop 0
	buffer_load_dwordx4 v136, s[16:19], s81 offen lds
	s_waitcnt vmcnt(8)
	s_waitcnt lgkmcnt(0)
	s_setprio 1
	v_mfma_f32_16x16x32_bf16 v[62:65], v[146:149], v[178:181], v[62:65]
	s_barrier
	v_mfma_f32_16x16x32_bf16 v[62:65], v[150:153], v[182:185], v[62:65]
	v_mfma_f32_16x16x32_bf16 v[46:49], v[146:149], v[186:189], v[46:49]
	v_mfma_f32_16x16x32_bf16 v[46:49], v[150:153], v[190:193], v[46:49]
	v_mfma_f32_16x16x32_bf16 v[30:33], v[146:149], v[194:197], v[30:33]
	v_mfma_f32_16x16x32_bf16 v[30:33], v[150:153], v[198:201], v[30:33]
	v_mfma_f32_16x16x32_bf16 v[14:17], v[146:149], v[202:205], v[14:17]
	v_mfma_f32_16x16x32_bf16 v[14:17], v[150:153], v[206:209], v[14:17]
	v_mfma_f32_16x16x32_bf16 v[54:57], v[154:157], v[178:181], v[54:57]
	v_mfma_f32_16x16x32_bf16 v[54:57], v[158:161], v[182:185], v[54:57]
	v_mfma_f32_16x16x32_bf16 v[38:41], v[154:157], v[186:189], v[38:41]
	v_mfma_f32_16x16x32_bf16 v[38:41], v[158:161], v[190:193], v[38:41]
	v_mfma_f32_16x16x32_bf16 v[22:25], v[154:157], v[194:197], v[22:25]
	v_mfma_f32_16x16x32_bf16 v[22:25], v[158:161], v[198:201], v[22:25]
	v_mfma_f32_16x16x32_bf16 v[6:9], v[154:157], v[202:205], v[6:9]
	v_mfma_f32_16x16x32_bf16 v[6:9], v[158:161], v[206:209], v[6:9]
	v_mfma_f32_16x16x32_bf16 v[58:61], v[162:165], v[178:181], v[58:61]
	v_mfma_f32_16x16x32_bf16 v[58:61], v[166:169], v[182:185], v[58:61]
	v_mfma_f32_16x16x32_bf16 v[42:45], v[162:165], v[186:189], v[42:45]
	v_mfma_f32_16x16x32_bf16 v[42:45], v[166:169], v[190:193], v[42:45]
	v_mfma_f32_16x16x32_bf16 v[26:29], v[162:165], v[194:197], v[26:29]
	v_mfma_f32_16x16x32_bf16 v[26:29], v[166:169], v[198:201], v[26:29]
	v_mfma_f32_16x16x32_bf16 v[10:13], v[162:165], v[202:205], v[10:13]
	v_mfma_f32_16x16x32_bf16 v[10:13], v[166:169], v[206:209], v[10:13]
	v_mfma_f32_16x16x32_bf16 v[50:53], v[170:173], v[178:181], v[50:53]
	v_mfma_f32_16x16x32_bf16 v[50:53], v[174:177], v[182:185], v[50:53]
	v_mfma_f32_16x16x32_bf16 v[34:37], v[170:173], v[186:189], v[34:37]
	v_mfma_f32_16x16x32_bf16 v[34:37], v[174:177], v[190:193], v[34:37]
	v_mfma_f32_16x16x32_bf16 v[18:21], v[170:173], v[194:197], v[18:21]
	v_mfma_f32_16x16x32_bf16 v[18:21], v[174:177], v[198:201], v[18:21]
	v_mfma_f32_16x16x32_bf16 v[2:5], v[170:173], v[202:205], v[2:5]
	v_mfma_f32_16x16x32_bf16 v[2:5], v[174:177], v[206:209], v[2:5]
	s_setprio 0
	s_barrier
	ds_read_b128 v[146:149], v141
	ds_read_b128 v[150:153], v141 offset:1024
	ds_read_b128 v[154:157], v141 offset:2048
	ds_read_b128 v[158:161], v141 offset:3072
	ds_read_b128 v[162:165], v142
	ds_read_b128 v[166:169], v142 offset:1024
	ds_read_b128 v[170:173], v142 offset:2048
	ds_read_b128 v[174:177], v142 offset:3072
	s_mov_b32 m0, s52
	s_add_i32 s81, s78, 0x100000
	ds_read_b128 v[178:181], v140 offset:32768
	ds_read_b128 v[182:185], v140 offset:33792
	ds_read_b128 v[186:189], v140 offset:34816
	ds_read_b128 v[190:193], v140 offset:35840
	ds_read_b128 v[194:197], v140 offset:36864
	ds_read_b128 v[198:201], v140 offset:37888
	ds_read_b128 v[202:205], v140 offset:38912
	ds_read_b128 v[206:209], v140 offset:39936
	buffer_load_dwordx4 v136, s[16:19], s81 offen lds
	s_add_i32 s81, s78, 0x180000
	s_mov_b32 m0, s53
	s_nop 0
	buffer_load_dwordx4 v136, s[16:19], s81 offen lds
	s_waitcnt vmcnt(8)
	s_waitcnt lgkmcnt(0)
	s_setprio 1
	v_mfma_f32_16x16x32_bf16 v[118:121], v[146:149], v[178:181], v[118:121]
	s_barrier
	v_mfma_f32_16x16x32_bf16 v[118:121], v[150:153], v[182:185], v[118:121]
	v_mfma_f32_16x16x32_bf16 v[110:113], v[146:149], v[186:189], v[110:113]
	v_mfma_f32_16x16x32_bf16 v[110:113], v[150:153], v[190:193], v[110:113]
	v_mfma_f32_16x16x32_bf16 v[94:97], v[146:149], v[194:197], v[94:97]
	v_mfma_f32_16x16x32_bf16 v[94:97], v[150:153], v[198:201], v[94:97]
	v_mfma_f32_16x16x32_bf16 v[78:81], v[146:149], v[202:205], v[78:81]
	v_mfma_f32_16x16x32_bf16 v[78:81], v[150:153], v[206:209], v[78:81]
	v_mfma_f32_16x16x32_bf16 v[114:117], v[154:157], v[178:181], v[114:117]
	v_mfma_f32_16x16x32_bf16 v[114:117], v[158:161], v[182:185], v[114:117]
	v_mfma_f32_16x16x32_bf16 v[102:105], v[154:157], v[186:189], v[102:105]
	v_mfma_f32_16x16x32_bf16 v[102:105], v[158:161], v[190:193], v[102:105]
	v_mfma_f32_16x16x32_bf16 v[86:89], v[154:157], v[194:197], v[86:89]
	v_mfma_f32_16x16x32_bf16 v[86:89], v[158:161], v[198:201], v[86:89]
	v_mfma_f32_16x16x32_bf16 v[66:69], v[154:157], v[202:205], v[66:69]
	v_mfma_f32_16x16x32_bf16 v[66:69], v[158:161], v[206:209], v[66:69]
	v_mfma_f32_16x16x32_bf16 v[126:129], v[162:165], v[178:181], v[126:129]
	v_mfma_f32_16x16x32_bf16 v[126:129], v[166:169], v[182:185], v[126:129]
	v_mfma_f32_16x16x32_bf16 v[106:109], v[162:165], v[186:189], v[106:109]
	v_mfma_f32_16x16x32_bf16 v[106:109], v[166:169], v[190:193], v[106:109]
	v_mfma_f32_16x16x32_bf16 v[90:93], v[162:165], v[194:197], v[90:93]
	v_mfma_f32_16x16x32_bf16 v[90:93], v[166:169], v[198:201], v[90:93]
	v_mfma_f32_16x16x32_bf16 v[74:77], v[162:165], v[202:205], v[74:77]
	v_mfma_f32_16x16x32_bf16 v[74:77], v[166:169], v[206:209], v[74:77]
	v_mfma_f32_16x16x32_bf16 v[122:125], v[170:173], v[178:181], v[122:125]
	v_mfma_f32_16x16x32_bf16 v[122:125], v[174:177], v[182:185], v[122:125]
	v_mfma_f32_16x16x32_bf16 v[98:101], v[170:173], v[186:189], v[98:101]
	v_mfma_f32_16x16x32_bf16 v[98:101], v[174:177], v[190:193], v[98:101]
	v_mfma_f32_16x16x32_bf16 v[82:85], v[170:173], v[194:197], v[82:85]
	v_mfma_f32_16x16x32_bf16 v[82:85], v[174:177], v[198:201], v[82:85]
	v_mfma_f32_16x16x32_bf16 v[70:73], v[170:173], v[202:205], v[70:73]
	v_mfma_f32_16x16x32_bf16 v[70:73], v[174:177], v[206:209], v[70:73]
	s_setprio 0
	s_barrier
	s_mov_b32 m0, s54
	s_or_b32 s81, s80, 0x80
	ds_read_b128 v[178:181], v140 offset:49152
	ds_read_b128 v[182:185], v140 offset:50176
	ds_read_b128 v[186:189], v140 offset:51200
	ds_read_b128 v[190:193], v140 offset:52224
	ds_read_b128 v[194:197], v140 offset:53248
	ds_read_b128 v[198:201], v140 offset:54272
	ds_read_b128 v[202:205], v140 offset:55296
	ds_read_b128 v[206:209], v140 offset:56320
	buffer_load_dwordx4 v137, s[20:23], s81 offen lds
	s_add_i32 s81, s80, 0x80080
	s_mov_b32 m0, s55
	s_add_i32 s78, s78, 0x80080
	buffer_load_dwordx4 v137, s[20:23], s81 offen lds
	s_add_i32 s81, s80, 0x100080
	s_mov_b32 m0, s58
	s_add_i32 s80, s80, 0x180080
	buffer_load_dwordx4 v137, s[20:23], s81 offen lds
	s_mov_b32 m0, s59
	s_nop 0
	buffer_load_dwordx4 v137, s[20:23], s80 offen lds
	s_mov_b32 m0, s56
	s_nop 0
	buffer_load_dwordx4 v136, s[16:19], s79 offen lds
	s_mov_b32 m0, s57
	s_nop 0
	buffer_load_dwordx4 v136, s[16:19], s78 offen lds
	s_waitcnt vmcnt(8)
	s_waitcnt lgkmcnt(0)
	s_setprio 1
	v_mfma_f32_16x16x32_bf16 v[62:65], v[146:149], v[178:181], v[62:65]
	s_barrier
	v_mfma_f32_16x16x32_bf16 v[62:65], v[150:153], v[182:185], v[62:65]
	v_mfma_f32_16x16x32_bf16 v[46:49], v[146:149], v[186:189], v[46:49]
	v_mfma_f32_16x16x32_bf16 v[46:49], v[150:153], v[190:193], v[46:49]
	v_mfma_f32_16x16x32_bf16 v[30:33], v[146:149], v[194:197], v[30:33]
	v_mfma_f32_16x16x32_bf16 v[30:33], v[150:153], v[198:201], v[30:33]
	v_mfma_f32_16x16x32_bf16 v[14:17], v[146:149], v[202:205], v[14:17]
	v_mfma_f32_16x16x32_bf16 v[14:17], v[150:153], v[206:209], v[14:17]
	v_mfma_f32_16x16x32_bf16 v[54:57], v[154:157], v[178:181], v[54:57]
	v_mfma_f32_16x16x32_bf16 v[54:57], v[158:161], v[182:185], v[54:57]
	v_mfma_f32_16x16x32_bf16 v[38:41], v[154:157], v[186:189], v[38:41]
	v_mfma_f32_16x16x32_bf16 v[38:41], v[158:161], v[190:193], v[38:41]
	v_mfma_f32_16x16x32_bf16 v[22:25], v[154:157], v[194:197], v[22:25]
	v_mfma_f32_16x16x32_bf16 v[22:25], v[158:161], v[198:201], v[22:25]
	v_mfma_f32_16x16x32_bf16 v[6:9], v[154:157], v[202:205], v[6:9]
	v_mfma_f32_16x16x32_bf16 v[6:9], v[158:161], v[206:209], v[6:9]
	v_mfma_f32_16x16x32_bf16 v[58:61], v[162:165], v[178:181], v[58:61]
	v_mfma_f32_16x16x32_bf16 v[58:61], v[166:169], v[182:185], v[58:61]
	v_mfma_f32_16x16x32_bf16 v[42:45], v[162:165], v[186:189], v[42:45]
	v_mfma_f32_16x16x32_bf16 v[42:45], v[166:169], v[190:193], v[42:45]
	v_mfma_f32_16x16x32_bf16 v[26:29], v[162:165], v[194:197], v[26:29]
	v_mfma_f32_16x16x32_bf16 v[26:29], v[166:169], v[198:201], v[26:29]
	v_mfma_f32_16x16x32_bf16 v[10:13], v[162:165], v[202:205], v[10:13]
	v_mfma_f32_16x16x32_bf16 v[10:13], v[166:169], v[206:209], v[10:13]
	v_mfma_f32_16x16x32_bf16 v[50:53], v[170:173], v[178:181], v[50:53]
	v_mfma_f32_16x16x32_bf16 v[50:53], v[174:177], v[182:185], v[50:53]
	v_mfma_f32_16x16x32_bf16 v[34:37], v[170:173], v[186:189], v[34:37]
	v_mfma_f32_16x16x32_bf16 v[34:37], v[174:177], v[190:193], v[34:37]
	v_mfma_f32_16x16x32_bf16 v[18:21], v[170:173], v[194:197], v[18:21]
	v_mfma_f32_16x16x32_bf16 v[18:21], v[174:177], v[198:201], v[18:21]
	v_mfma_f32_16x16x32_bf16 v[2:5], v[170:173], v[202:205], v[2:5]
	v_mfma_f32_16x16x32_bf16 v[2:5], v[174:177], v[206:209], v[2:5]
	s_setprio 0
	s_barrier
	s_add_i32 s77, s77, 2
	s_addk_i32 s75, 0x100
	s_addk_i32 s76, 0x100
	s_cmp_ge_i32 s77, s13
	s_cbranch_scc0 .LBB0_1402
	s_and_b64 vcc, exec, s[46:47]
	s_cbranch_vccz .LBB0_1405

.LBB0_1519:
	ds_read_b128 v[134:137], v208
	ds_read_b128 v[138:141], v208 offset:1024
	ds_read_b128 v[142:145], v208 offset:2048
	ds_read_b128 v[146:149], v208 offset:3072
	ds_read_b128 v[150:153], v209
	ds_read_b128 v[154:157], v209 offset:1024
	ds_read_b128 v[158:161], v209 offset:2048
	ds_read_b128 v[162:165], v209 offset:3072
	s_add_i32 s18, s80, 0xffbf8080
	s_cmp_eq_u32 s65, s82
	s_cselect_b32 s83, s6, s18
	s_cselect_b32 s85, s7, s81
	s_or_b32 s84, s83, 0x80
	s_add_i32 s18, s80, 0xffea8000
	s_mov_b32 m0, s66
	ds_read_b128 v[166:169], v210
	ds_read_b128 v[170:173], v210 offset:1024
	ds_read_b128 v[174:177], v210 offset:2048
	ds_read_b128 v[178:181], v210 offset:3072
	ds_read_b128 v[182:185], v210 offset:4096
	ds_read_b128 v[186:189], v210 offset:5120
	ds_read_b128 v[190:193], v210 offset:6144
	ds_read_b128 v[194:197], v210 offset:7168
	buffer_load_dwordx4 v206, s[12:15], s18 offen lds
	s_mov_b32 m0, s69
	s_nop 0
	buffer_load_dwordx4 v206, s[12:15], s80 offen lds
	s_waitcnt vmcnt(8)
	s_waitcnt lgkmcnt(0)
	s_setprio 1
	v_mfma_f32_16x16x32_bf16 v[126:129], v[134:137], v[166:169], v[126:129]
	s_barrier
	v_mfma_f32_16x16x32_bf16 v[126:129], v[138:141], v[170:173], v[126:129]
	v_mfma_f32_16x16x32_bf16 v[118:121], v[134:137], v[174:177], v[118:121]
	v_mfma_f32_16x16x32_bf16 v[118:121], v[138:141], v[178:181], v[118:121]
	v_mfma_f32_16x16x32_bf16 v[106:109], v[134:137], v[182:185], v[106:109]
	v_mfma_f32_16x16x32_bf16 v[106:109], v[138:141], v[186:189], v[106:109]
	v_mfma_f32_16x16x32_bf16 v[90:93], v[134:137], v[190:193], v[90:93]
	v_mfma_f32_16x16x32_bf16 v[90:93], v[138:141], v[194:197], v[90:93]
	v_mfma_f32_16x16x32_bf16 v[122:125], v[142:145], v[166:169], v[122:125]
	v_mfma_f32_16x16x32_bf16 v[122:125], v[146:149], v[170:173], v[122:125]
	v_mfma_f32_16x16x32_bf16 v[114:117], v[142:145], v[174:177], v[114:117]
	v_mfma_f32_16x16x32_bf16 v[114:117], v[146:149], v[178:181], v[114:117]
	v_mfma_f32_16x16x32_bf16 v[98:101], v[142:145], v[182:185], v[98:101]
	v_mfma_f32_16x16x32_bf16 v[98:101], v[146:149], v[186:189], v[98:101]
	v_mfma_f32_16x16x32_bf16 v[82:85], v[142:145], v[190:193], v[82:85]
	v_mfma_f32_16x16x32_bf16 v[82:85], v[146:149], v[194:197], v[82:85]
	v_mfma_f32_16x16x32_bf16 v[110:113], v[150:153], v[166:169], v[110:113]
	v_mfma_f32_16x16x32_bf16 v[110:113], v[154:157], v[170:173], v[110:113]
	v_mfma_f32_16x16x32_bf16 v[94:97], v[150:153], v[174:177], v[94:97]
	v_mfma_f32_16x16x32_bf16 v[94:97], v[154:157], v[178:181], v[94:97]
	v_mfma_f32_16x16x32_bf16 v[78:81], v[150:153], v[182:185], v[78:81]
	v_mfma_f32_16x16x32_bf16 v[78:81], v[154:157], v[186:189], v[78:81]
	v_mfma_f32_16x16x32_bf16 v[70:73], v[150:153], v[190:193], v[70:73]
	v_mfma_f32_16x16x32_bf16 v[70:73], v[154:157], v[194:197], v[70:73]
	v_mfma_f32_16x16x32_bf16 v[102:105], v[158:161], v[166:169], v[102:105]
	v_mfma_f32_16x16x32_bf16 v[102:105], v[162:165], v[170:173], v[102:105]
	v_mfma_f32_16x16x32_bf16 v[86:89], v[158:161], v[174:177], v[86:89]
	v_mfma_f32_16x16x32_bf16 v[86:89], v[162:165], v[178:181], v[86:89]
	v_mfma_f32_16x16x32_bf16 v[74:77], v[158:161], v[182:185], v[74:77]
	v_mfma_f32_16x16x32_bf16 v[74:77], v[162:165], v[186:189], v[74:77]
	v_mfma_f32_16x16x32_bf16 v[66:69], v[158:161], v[190:193], v[66:69]
	v_mfma_f32_16x16x32_bf16 v[66:69], v[162:165], v[194:197], v[66:69]
	s_setprio 0
	s_barrier
	s_mov_b32 m0, s27
	s_mov_b32 s18, s14
	s_mov_b32 s19, s15
	ds_read_b128 v[166:169], v210 offset:16384
	ds_read_b128 v[170:173], v210 offset:17408
	ds_read_b128 v[174:177], v210 offset:18432
	ds_read_b128 v[178:181], v210 offset:19456
	ds_read_b128 v[182:185], v210 offset:20480
	ds_read_b128 v[186:189], v210 offset:21504
	ds_read_b128 v[190:193], v210 offset:22528
	ds_read_b128 v[194:197], v210 offset:23552
	buffer_load_dwordx4 v207, s[16:19], s85 offen lds
	s_add_i32 s86, s85, 0x158000
	s_mov_b32 m0, s30
	s_nop 0
	buffer_load_dwordx4 v207, s[16:19], s86 offen lds
	s_add_i32 s86, s85, 0x2b0000
	s_mov_b32 m0, s31
	s_nop 0
	buffer_load_dwordx4 v207, s[16:19], s86 offen lds
	s_add_i32 s86, s85, 0x408000
	s_mov_b32 m0, s50
	s_nop 0
	buffer_load_dwordx4 v207, s[16:19], s86 offen lds
	s_mov_b32 m0, s25
	s_add_i32 s86, s83, 0x158000
	buffer_load_dwordx4 v206, s[12:15], s83 offen lds
	s_mov_b32 m0, s51
	s_nop 0
	buffer_load_dwordx4 v206, s[12:15], s86 offen lds
	s_waitcnt vmcnt(8)
	s_waitcnt lgkmcnt(0)
	s_setprio 1
	v_mfma_f32_16x16x32_bf16 v[62:65], v[134:137], v[166:169], v[62:65]
	s_barrier
	v_mfma_f32_16x16x32_bf16 v[62:65], v[138:141], v[170:173], v[62:65]
	v_mfma_f32_16x16x32_bf16 v[54:57], v[134:137], v[174:177], v[54:57]
	v_mfma_f32_16x16x32_bf16 v[54:57], v[138:141], v[178:181], v[54:57]
	v_mfma_f32_16x16x32_bf16 v[42:45], v[134:137], v[182:185], v[42:45]
	v_mfma_f32_16x16x32_bf16 v[42:45], v[138:141], v[186:189], v[42:45]
	v_mfma_f32_16x16x32_bf16 v[26:29], v[134:137], v[190:193], v[26:29]
	v_mfma_f32_16x16x32_bf16 v[26:29], v[138:141], v[194:197], v[26:29]
	v_mfma_f32_16x16x32_bf16 v[58:61], v[142:145], v[166:169], v[58:61]
	v_mfma_f32_16x16x32_bf16 v[58:61], v[146:149], v[170:173], v[58:61]
	v_mfma_f32_16x16x32_bf16 v[50:53], v[142:145], v[174:177], v[50:53]
	v_mfma_f32_16x16x32_bf16 v[50:53], v[146:149], v[178:181], v[50:53]
	v_mfma_f32_16x16x32_bf16 v[34:37], v[142:145], v[182:185], v[34:37]
	v_mfma_f32_16x16x32_bf16 v[34:37], v[146:149], v[186:189], v[34:37]
	v_mfma_f32_16x16x32_bf16 v[18:21], v[142:145], v[190:193], v[18:21]
	v_mfma_f32_16x16x32_bf16 v[18:21], v[146:149], v[194:197], v[18:21]
	v_mfma_f32_16x16x32_bf16 v[46:49], v[150:153], v[166:169], v[46:49]
	v_mfma_f32_16x16x32_bf16 v[46:49], v[154:157], v[170:173], v[46:49]
	v_mfma_f32_16x16x32_bf16 v[30:33], v[150:153], v[174:177], v[30:33]
	v_mfma_f32_16x16x32_bf16 v[30:33], v[154:157], v[178:181], v[30:33]
	v_mfma_f32_16x16x32_bf16 v[14:17], v[150:153], v[182:185], v[14:17]
	v_mfma_f32_16x16x32_bf16 v[14:17], v[154:157], v[186:189], v[14:17]
	v_mfma_f32_16x16x32_bf16 v[6:9], v[150:153], v[190:193], v[6:9]
	v_mfma_f32_16x16x32_bf16 v[6:9], v[154:157], v[194:197], v[6:9]
	v_mfma_f32_16x16x32_bf16 v[38:41], v[158:161], v[166:169], v[38:41]
	v_mfma_f32_16x16x32_bf16 v[38:41], v[162:165], v[170:173], v[38:41]
	v_mfma_f32_16x16x32_bf16 v[22:25], v[158:161], v[174:177], v[22:25]
	v_mfma_f32_16x16x32_bf16 v[22:25], v[162:165], v[178:181], v[22:25]
	v_mfma_f32_16x16x32_bf16 v[10:13], v[158:161], v[182:185], v[10:13]
	v_mfma_f32_16x16x32_bf16 v[10:13], v[162:165], v[186:189], v[10:13]
	v_mfma_f32_16x16x32_bf16 v[2:5], v[158:161], v[190:193], v[2:5]
	v_mfma_f32_16x16x32_bf16 v[2:5], v[162:165], v[194:197], v[2:5]
	s_setprio 0
	s_barrier
	ds_read_b128 v[134:137], v211
	ds_read_b128 v[138:141], v211 offset:1024
	ds_read_b128 v[142:145], v211 offset:2048
	ds_read_b128 v[146:149], v211 offset:3072
	ds_read_b128 v[150:153], v212
	ds_read_b128 v[154:157], v212 offset:1024
	ds_read_b128 v[158:161], v212 offset:2048
	ds_read_b128 v[162:165], v212 offset:3072
	s_mov_b32 m0, s52
	s_add_i32 s86, s83, 0x2b0000
	ds_read_b128 v[166:169], v210 offset:32768
	ds_read_b128 v[170:173], v210 offset:33792
	ds_read_b128 v[174:177], v210 offset:34816
	ds_read_b128 v[178:181], v210 offset:35840
	ds_read_b128 v[182:185], v210 offset:36864
	ds_read_b128 v[186:189], v210 offset:37888
	ds_read_b128 v[190:193], v210 offset:38912
	ds_read_b128 v[194:197], v210 offset:39936
	buffer_load_dwordx4 v206, s[12:15], s86 offen lds
	s_add_i32 s86, s83, 0x408000
	s_mov_b32 m0, s53
	s_nop 0
	buffer_load_dwordx4 v206, s[12:15], s86 offen lds
	s_waitcnt vmcnt(8)
	s_waitcnt lgkmcnt(0)
	s_setprio 1
	v_mfma_f32_16x16x32_bf16 v[126:129], v[134:137], v[166:169], v[126:129]
	s_barrier
	v_mfma_f32_16x16x32_bf16 v[126:129], v[138:141], v[170:173], v[126:129]
	v_mfma_f32_16x16x32_bf16 v[118:121], v[134:137], v[174:177], v[118:121]
	v_mfma_f32_16x16x32_bf16 v[118:121], v[138:141], v[178:181], v[118:121]
	v_mfma_f32_16x16x32_bf16 v[106:109], v[134:137], v[182:185], v[106:109]
	v_mfma_f32_16x16x32_bf16 v[106:109], v[138:141], v[186:189], v[106:109]
	v_mfma_f32_16x16x32_bf16 v[90:93], v[134:137], v[190:193], v[90:93]
	v_mfma_f32_16x16x32_bf16 v[90:93], v[138:141], v[194:197], v[90:93]
	v_mfma_f32_16x16x32_bf16 v[122:125], v[142:145], v[166:169], v[122:125]
	v_mfma_f32_16x16x32_bf16 v[122:125], v[146:149], v[170:173], v[122:125]
	v_mfma_f32_16x16x32_bf16 v[114:117], v[142:145], v[174:177], v[114:117]
	v_mfma_f32_16x16x32_bf16 v[114:117], v[146:149], v[178:181], v[114:117]
	v_mfma_f32_16x16x32_bf16 v[98:101], v[142:145], v[182:185], v[98:101]
	v_mfma_f32_16x16x32_bf16 v[98:101], v[146:149], v[186:189], v[98:101]
	v_mfma_f32_16x16x32_bf16 v[82:85], v[142:145], v[190:193], v[82:85]
	v_mfma_f32_16x16x32_bf16 v[82:85], v[146:149], v[194:197], v[82:85]
	v_mfma_f32_16x16x32_bf16 v[110:113], v[150:153], v[166:169], v[110:113]
	v_mfma_f32_16x16x32_bf16 v[110:113], v[154:157], v[170:173], v[110:113]
	v_mfma_f32_16x16x32_bf16 v[94:97], v[150:153], v[174:177], v[94:97]
	v_mfma_f32_16x16x32_bf16 v[94:97], v[154:157], v[178:181], v[94:97]
	v_mfma_f32_16x16x32_bf16 v[78:81], v[150:153], v[182:185], v[78:81]
	v_mfma_f32_16x16x32_bf16 v[78:81], v[154:157], v[186:189], v[78:81]
	v_mfma_f32_16x16x32_bf16 v[70:73], v[150:153], v[190:193], v[70:73]
	v_mfma_f32_16x16x32_bf16 v[70:73], v[154:157], v[194:197], v[70:73]
	v_mfma_f32_16x16x32_bf16 v[102:105], v[158:161], v[166:169], v[102:105]
	v_mfma_f32_16x16x32_bf16 v[102:105], v[162:165], v[170:173], v[102:105]
	v_mfma_f32_16x16x32_bf16 v[86:89], v[158:161], v[174:177], v[86:89]
	v_mfma_f32_16x16x32_bf16 v[86:89], v[162:165], v[178:181], v[86:89]
	v_mfma_f32_16x16x32_bf16 v[74:77], v[158:161], v[182:185], v[74:77]
	v_mfma_f32_16x16x32_bf16 v[74:77], v[162:165], v[186:189], v[74:77]
	v_mfma_f32_16x16x32_bf16 v[66:69], v[158:161], v[190:193], v[66:69]
	v_mfma_f32_16x16x32_bf16 v[66:69], v[162:165], v[194:197], v[66:69]
	s_setprio 0
	s_barrier
	s_mov_b32 m0, s57
	s_or_b32 s86, s85, 0x80
	ds_read_b128 v[166:169], v210 offset:49152
	ds_read_b128 v[170:173], v210 offset:50176
	ds_read_b128 v[174:177], v210 offset:51200
	ds_read_b128 v[178:181], v210 offset:52224
	ds_read_b128 v[182:185], v210 offset:53248
	ds_read_b128 v[186:189], v210 offset:54272
	ds_read_b128 v[190:193], v210 offset:55296
	ds_read_b128 v[194:197], v210 offset:56320
	buffer_load_dwordx4 v207, s[16:19], s86 offen lds
	s_add_i32 s86, s85, 0x158080
	s_mov_b32 m0, s58
	s_add_i32 s83, s83, 0x158080
	buffer_load_dwordx4 v207, s[16:19], s86 offen lds
	s_add_i32 s86, s85, 0x2b0080
	s_mov_b32 m0, s61
	s_add_i32 s85, s85, 0x408080
	buffer_load_dwordx4 v207, s[16:19], s86 offen lds
	s_mov_b32 m0, s62
	s_nop 0
	buffer_load_dwordx4 v207, s[16:19], s85 offen lds
	s_mov_b32 m0, s59
	s_nop 0
	buffer_load_dwordx4 v206, s[12:15], s84 offen lds
	s_mov_b32 m0, s60
	s_nop 0
	buffer_load_dwordx4 v206, s[12:15], s83 offen lds
	s_waitcnt vmcnt(8)
	s_waitcnt lgkmcnt(0)
	s_setprio 1
	v_mfma_f32_16x16x32_bf16 v[62:65], v[134:137], v[166:169], v[62:65]
	s_barrier
	v_mfma_f32_16x16x32_bf16 v[62:65], v[138:141], v[170:173], v[62:65]
	v_mfma_f32_16x16x32_bf16 v[54:57], v[134:137], v[174:177], v[54:57]
	v_mfma_f32_16x16x32_bf16 v[54:57], v[138:141], v[178:181], v[54:57]
	v_mfma_f32_16x16x32_bf16 v[42:45], v[134:137], v[182:185], v[42:45]
	v_mfma_f32_16x16x32_bf16 v[42:45], v[138:141], v[186:189], v[42:45]
	v_mfma_f32_16x16x32_bf16 v[26:29], v[134:137], v[190:193], v[26:29]
	v_mfma_f32_16x16x32_bf16 v[26:29], v[138:141], v[194:197], v[26:29]
	v_mfma_f32_16x16x32_bf16 v[58:61], v[142:145], v[166:169], v[58:61]
	v_mfma_f32_16x16x32_bf16 v[58:61], v[146:149], v[170:173], v[58:61]
	v_mfma_f32_16x16x32_bf16 v[50:53], v[142:145], v[174:177], v[50:53]
	v_mfma_f32_16x16x32_bf16 v[50:53], v[146:149], v[178:181], v[50:53]
	v_mfma_f32_16x16x32_bf16 v[34:37], v[142:145], v[182:185], v[34:37]
	v_mfma_f32_16x16x32_bf16 v[34:37], v[146:149], v[186:189], v[34:37]
	v_mfma_f32_16x16x32_bf16 v[18:21], v[142:145], v[190:193], v[18:21]
	v_mfma_f32_16x16x32_bf16 v[18:21], v[146:149], v[194:197], v[18:21]
	v_mfma_f32_16x16x32_bf16 v[46:49], v[150:153], v[166:169], v[46:49]
	v_mfma_f32_16x16x32_bf16 v[46:49], v[154:157], v[170:173], v[46:49]
	v_mfma_f32_16x16x32_bf16 v[30:33], v[150:153], v[174:177], v[30:33]
	v_mfma_f32_16x16x32_bf16 v[30:33], v[154:157], v[178:181], v[30:33]
	v_mfma_f32_16x16x32_bf16 v[14:17], v[150:153], v[182:185], v[14:17]
	v_mfma_f32_16x16x32_bf16 v[14:17], v[154:157], v[186:189], v[14:17]
	v_mfma_f32_16x16x32_bf16 v[6:9], v[150:153], v[190:193], v[6:9]
	v_mfma_f32_16x16x32_bf16 v[6:9], v[154:157], v[194:197], v[6:9]
	v_mfma_f32_16x16x32_bf16 v[38:41], v[158:161], v[166:169], v[38:41]
	v_mfma_f32_16x16x32_bf16 v[38:41], v[162:165], v[170:173], v[38:41]
	v_mfma_f32_16x16x32_bf16 v[22:25], v[158:161], v[174:177], v[22:25]
	v_mfma_f32_16x16x32_bf16 v[22:25], v[162:165], v[178:181], v[22:25]
	v_mfma_f32_16x16x32_bf16 v[10:13], v[158:161], v[182:185], v[10:13]
	v_mfma_f32_16x16x32_bf16 v[10:13], v[162:165], v[186:189], v[10:13]
	v_mfma_f32_16x16x32_bf16 v[2:5], v[158:161], v[190:193], v[2:5]
	v_mfma_f32_16x16x32_bf16 v[2:5], v[162:165], v[194:197], v[2:5]
	s_setprio 0
	s_barrier
	s_add_i32 s82, s82, 2
	s_addk_i32 s80, 0x100
	s_addk_i32 s81, 0x100
	s_cmp_ge_i32 s82, s3
	s_cbranch_scc0 .LBB0_1519
	v_pk_mul_f32 v[182:183], v[128:129], 0.5 op_sel_hi:[1,0]
	v_pk_mul_f32 v[184:185], v[126:127], 0.5 op_sel_hi:[1,0]
	v_pk_mul_f32 v[186:187], v[124:125], 0.5 op_sel_hi:[1,0]
	v_pk_mul_f32 v[188:189], v[122:123], 0.5 op_sel_hi:[1,0]
	v_pk_mul_f32 v[196:197], v[112:113], 0.5 op_sel_hi:[1,0]
	v_pk_mul_f32 v[194:195], v[110:111], 0.5 op_sel_hi:[1,0]
	v_pk_mul_f32 v[192:193], v[104:105], 0.5 op_sel_hi:[1,0]
	v_pk_mul_f32 v[190:191], v[102:103], 0.5 op_sel_hi:[1,0]
	v_pk_mul_f32 v[180:181], v[120:121], 0.5 op_sel_hi:[1,0]
	v_pk_mul_f32 v[178:179], v[118:119], 0.5 op_sel_hi:[1,0]
	v_pk_mul_f32 v[176:177], v[116:117], 0.5 op_sel_hi:[1,0]
	v_pk_mul_f32 v[174:175], v[114:115], 0.5 op_sel_hi:[1,0]
	v_pk_mul_f32 v[170:171], v[96:97], 0.5 op_sel_hi:[1,0]
	v_pk_mul_f32 v[168:169], v[94:95], 0.5 op_sel_hi:[1,0]
	v_pk_mul_f32 v[166:167], v[88:89], 0.5 op_sel_hi:[1,0]
	v_pk_mul_f32 v[164:165], v[86:87], 0.5 op_sel_hi:[1,0]
	v_pk_mul_f32 v[162:163], v[108:109], 0.5 op_sel_hi:[1,0]
	v_pk_mul_f32 v[160:161], v[106:107], 0.5 op_sel_hi:[1,0]
	v_pk_mul_f32 v[158:159], v[100:101], 0.5 op_sel_hi:[1,0]
	v_pk_mul_f32 v[156:157], v[98:99], 0.5 op_sel_hi:[1,0]
	v_pk_mul_f32 v[154:155], v[80:81], 0.5 op_sel_hi:[1,0]
	v_pk_mul_f32 v[152:153], v[78:79], 0.5 op_sel_hi:[1,0]
	v_pk_mul_f32 v[150:151], v[76:77], 0.5 op_sel_hi:[1,0]
	v_pk_mul_f32 v[148:149], v[74:75], 0.5 op_sel_hi:[1,0]
	v_pk_mul_f32 v[144:145], v[92:93], 0.5 op_sel_hi:[1,0]
	v_pk_mul_f32 v[142:143], v[90:91], 0.5 op_sel_hi:[1,0]
	v_pk_mul_f32 v[140:141], v[84:85], 0.5 op_sel_hi:[1,0]
	v_pk_mul_f32 v[138:139], v[82:83], 0.5 op_sel_hi:[1,0]
	v_pk_mul_f32 v[136:137], v[72:73], 0.5 op_sel_hi:[1,0]
	v_pk_mul_f32 v[134:135], v[70:71], 0.5 op_sel_hi:[1,0]
	v_pk_mul_f32 v[128:129], v[68:69], 0.5 op_sel_hi:[1,0]
	v_pk_mul_f32 v[126:127], v[66:67], 0.5 op_sel_hi:[1,0]
	v_pk_mul_f32 v[122:123], v[64:65], 0.5 op_sel_hi:[1,0]
	v_pk_mul_f32 v[120:121], v[62:63], 0.5 op_sel_hi:[1,0]
	v_pk_mul_f32 v[118:119], v[60:61], 0.5 op_sel_hi:[1,0]
	v_pk_mul_f32 v[116:117], v[58:59], 0.5 op_sel_hi:[1,0]
	v_pk_mul_f32 v[112:113], v[48:49], 0.5 op_sel_hi:[1,0]
	v_pk_mul_f32 v[110:111], v[46:47], 0.5 op_sel_hi:[1,0]
	v_pk_mul_f32 v[108:109], v[40:41], 0.5 op_sel_hi:[1,0]
	v_pk_mul_f32 v[106:107], v[38:39], 0.5 op_sel_hi:[1,0]
	v_pk_mul_f32 v[104:105], v[56:57], 0.5 op_sel_hi:[1,0]
	v_pk_mul_f32 v[102:103], v[54:55], 0.5 op_sel_hi:[1,0]
	v_pk_mul_f32 v[100:101], v[52:53], 0.5 op_sel_hi:[1,0]
	v_pk_mul_f32 v[98:99], v[50:51], 0.5 op_sel_hi:[1,0]
	v_pk_mul_f32 v[96:97], v[32:33], 0.5 op_sel_hi:[1,0]
	v_pk_mul_f32 v[94:95], v[30:31], 0.5 op_sel_hi:[1,0]
	v_pk_mul_f32 v[92:93], v[24:25], 0.5 op_sel_hi:[1,0]
	v_pk_mul_f32 v[90:91], v[22:23], 0.5 op_sel_hi:[1,0]
	v_pk_mul_f32 v[88:89], v[44:45], 0.5 op_sel_hi:[1,0]
	v_pk_mul_f32 v[86:87], v[42:43], 0.5 op_sel_hi:[1,0]
	v_pk_mul_f32 v[84:85], v[36:37], 0.5 op_sel_hi:[1,0]
	v_pk_mul_f32 v[82:83], v[34:35], 0.5 op_sel_hi:[1,0]
	v_pk_mul_f32 v[80:81], v[16:17], 0.5 op_sel_hi:[1,0]
	v_pk_mul_f32 v[78:79], v[14:15], 0.5 op_sel_hi:[1,0]
	v_pk_mul_f32 v[76:77], v[12:13], 0.5 op_sel_hi:[1,0]
	v_pk_mul_f32 v[74:75], v[10:11], 0.5 op_sel_hi:[1,0]
	v_pk_mul_f32 v[72:73], v[28:29], 0.5 op_sel_hi:[1,0]
	v_pk_mul_f32 v[70:71], v[26:27], 0.5 op_sel_hi:[1,0]
	v_pk_mul_f32 v[68:69], v[20:21], 0.5 op_sel_hi:[1,0]
	v_pk_mul_f32 v[66:67], v[18:19], 0.5 op_sel_hi:[1,0]
	v_pk_mul_f32 v[64:65], v[8:9], 0.5 op_sel_hi:[1,0]
	v_pk_mul_f32 v[62:63], v[6:7], 0.5 op_sel_hi:[1,0]
	v_pk_mul_f32 v[60:61], v[4:5], 0.5 op_sel_hi:[1,0]
	v_pk_mul_f32 v[58:59], v[2:3], 0.5 op_sel_hi:[1,0]
	s_and_b64 vcc, exec, s[40:41]
	s_cbranch_vccz .LBB0_1522
